# loop-edge: hoist loop-tail SALU increments and compare above the final barrier in 8 GEMM loops (v100 base)
# baseline (speedup 1.0000x reference)
; #define PG8_STAGE(bufoff, gbase, voff) do { _Pragma("unroll") for (int _i = 0; _i < 2; ++_i) \
;         __builtin_amdgcn_global_load_lds((const unsigned*)((const char*)(gbase) + (voff)[_i]), (LAS unsigned*)(lds + (bufoff) + ldsw + _i * 8192), 16, 0, 0); } while (0)
; #define PG8_LDA(dst, b, h) do { _Pragma("unroll") for (int m = 0; m < 4; ++m) _Pragma("unroll") for (int k = 0; k < 2; ++k) dst[m][k] = *(const LAS bf16x8*)(lds + PG8_SA(b, h) + aoff + m * 2048 + k * 1024); } while (0)
; #define PG8_LDB(dst, b, h) do { _Pragma("unroll") for (int n = 0; n < 2; ++n) _Pragma("unroll") for (int k = 0; k < 2; ++k) dst[n][k] = *(const LAS bf16x8*)(lds + PG8_SB(b, h) + boff + n * 2048 + k * 1024); } while (0)
; #define PG8_MMA(ai, bj, At, Bt) do { __builtin_amdgcn_s_setprio(1); _Pragma("unroll") for (int m = 0; m < 4; ++m) _Pragma("unroll") for (int n = 0; n < 2; ++n) _Pragma("unroll") for (int k = 0; k < 2; ++k) \
;         acc[ai][bj][m][n] = __builtin_amdgcn_mfma_f32_16x16x32_bf16(Bt[n][k], At[m][k], acc[ai][bj][m][n], 0, 0, 0); __builtin_amdgcn_s_setprio(0); } while (0)
; #define PG8_WAIT_V(n) asm volatile("s_waitcnt vmcnt(" #n ")" ::: "memory")
; #define PG8_WAIT_L(n) asm volatile("s_waitcnt lgkmcnt(" #n ")" ::: "memory")
; #define PG8_BAR __builtin_amdgcn_s_barrier()
; #define PG8_SCHED __builtin_amdgcn_sched_barrier(0)
; template <class Epi>
; __device__ __forceinline__ void gemm_phase(LAS unsigned char* lds, const Gemm g, const StaticOrder& S, const Epi& E) {
;     ...
;         for (int t = 0; t < nt; t += 2) {
;             const bool last = (t == nt - 2);
;             const char* a1 = cA + (size_t)(t + 1) * kstep;
;             const char* a2 = last ? nA : cA + (size_t)(t + 2) * kstep; const char* b2 = last ? nB : cB + (size_t)(t + 2) * kstep;
;             const char* a3 = a2 + kstep; const char* b3 = b2 + kstep;
;             PG8_LDB(B0, 0, 0); PG8_LDB(B1, 0, 1); PG8_SCHED; PG8_LDA(At, 0, 0); PG8_STAGE(PG8_SA(1, 1), a1 + hstepA, voffA);
;             PG8_WAIT_V(8); PG8_WAIT_L(0); PG8_BAR; PG8_MMA(0, 0, At, B0); PG8_MMA(0, 1, At, B1); PG8_BAR; PG8_SCHED;
;             PG8_LDA(At, 0, 1); PG8_STAGE(PG8_SB(0, 0), b2, voffB); PG8_STAGE(PG8_SB(0, 1), b2 + hstepB, voffB); PG8_STAGE(PG8_SA(0, 0), a2, voffA);
;             PG8_WAIT_V(8); PG8_WAIT_L(0); PG8_BAR; PG8_MMA(1, 0, At, B0); PG8_MMA(1, 1, At, B1); PG8_BAR; PG8_SCHED;
.LBB0_163:
	s_add_u32 s22, s44, 0xfffc0080
	s_addc_u32 s23, s45, -1
	s_add_i32 s66, 0, 0x10000
	s_cmp_eq_u32 s65, 12
	s_cselect_b32 s47, s35, s23
	s_cselect_b32 s46, s61, s22
	v_add_u32_e32 v142, s66, v144
	s_cselect_b32 s23, s15, s64
	s_cselect_b32 s22, s62, s63
	s_add_i32 s68, 0, 0x14000
	ds_read_b128 v[148:151], v142
	ds_read_b128 v[152:155], v142 offset:1024
	ds_read_b128 v[156:159], v142 offset:2048
	ds_read_b128 v[160:163], v142 offset:3072
	v_add_u32_e32 v142, s68, v144
	ds_read_b128 v[164:167], v142
	ds_read_b128 v[168:171], v142 offset:1024
	ds_read_b128 v[172:175], v142 offset:2048
	ds_read_b128 v[176:179], v142 offset:3072
	v_lshl_add_u64 v[142:143], s[44:45], 0, v[138:139]
	s_add_i32 m0, s53, 0xc000
	ds_read_b128 v[180:183], v146
	ds_read_b128 v[184:187], v146 offset:1024
	ds_read_b128 v[188:191], v146 offset:2048
	ds_read_b128 v[192:195], v146 offset:3072
	ds_read_b128 v[210:213], v146 offset:4096
	ds_read_b128 v[214:217], v146 offset:5120
	ds_read_b128 v[218:221], v146 offset:6144
	ds_read_b128 v[222:225], v146 offset:7168
	global_load_lds_dwordx4 v[142:143], off
	v_lshl_add_u64 v[142:143], s[44:45], 0, v[140:141]
	s_add_i32 m0, s53, 0xe000
	s_nop 0
	global_load_lds_dwordx4 v[142:143], off
	s_waitcnt vmcnt(8)
	s_waitcnt lgkmcnt(0)
	s_barrier
	s_setprio 1
	s_waitcnt lgkmcnt(0)
	v_mfma_f32_16x16x32_bf16 v[128:131], v[148:151], v[180:183], v[128:131]
	v_mfma_f32_16x16x32_bf16 v[120:123], v[156:159], v[180:183], v[120:123]
	v_mfma_f32_16x16x32_bf16 v[112:115], v[148:151], v[188:191], v[112:115]
	v_mfma_f32_16x16x32_bf16 v[100:103], v[156:159], v[188:191], v[100:103]
	v_mfma_f32_16x16x32_bf16 v[92:95], v[148:151], v[210:213], v[92:95]
	v_mfma_f32_16x16x32_bf16 v[84:87], v[156:159], v[210:213], v[84:87]
	v_mfma_f32_16x16x32_bf16 v[76:79], v[148:151], v[218:221], v[76:79]
	v_mfma_f32_16x16x32_bf16 v[68:71], v[156:159], v[218:221], v[68:71]
	v_mfma_f32_16x16x32_bf16 v[128:131], v[152:155], v[184:187], v[128:131]
	v_mfma_f32_16x16x32_bf16 v[120:123], v[160:163], v[184:187], v[120:123]
	v_mfma_f32_16x16x32_bf16 v[112:115], v[152:155], v[192:195], v[112:115]
	v_mfma_f32_16x16x32_bf16 v[100:103], v[160:163], v[192:195], v[100:103]
	v_mfma_f32_16x16x32_bf16 v[92:95], v[152:155], v[214:217], v[92:95]
	v_mfma_f32_16x16x32_bf16 v[84:87], v[160:163], v[214:217], v[84:87]
	v_mfma_f32_16x16x32_bf16 v[76:79], v[152:155], v[222:225], v[76:79]
	v_mfma_f32_16x16x32_bf16 v[68:71], v[160:163], v[222:225], v[68:71]
	s_setprio 0
	s_setprio 1
	v_mfma_f32_16x16x32_bf16 v[124:127], v[164:167], v[180:183], v[124:127]
	v_mfma_f32_16x16x32_bf16 v[116:119], v[172:175], v[180:183], v[116:119]
	v_mfma_f32_16x16x32_bf16 v[108:111], v[164:167], v[188:191], v[108:111]
	v_mfma_f32_16x16x32_bf16 v[104:107], v[172:175], v[188:191], v[104:107]
	v_mfma_f32_16x16x32_bf16 v[96:99], v[164:167], v[210:213], v[96:99]
	v_mfma_f32_16x16x32_bf16 v[88:91], v[172:175], v[210:213], v[88:91]
	v_mfma_f32_16x16x32_bf16 v[80:83], v[164:167], v[218:221], v[80:83]
	v_mfma_f32_16x16x32_bf16 v[72:75], v[172:175], v[218:221], v[72:75]
	v_mfma_f32_16x16x32_bf16 v[124:127], v[168:171], v[184:187], v[124:127]
	v_mfma_f32_16x16x32_bf16 v[116:119], v[176:179], v[184:187], v[116:119]
	v_mfma_f32_16x16x32_bf16 v[108:111], v[168:171], v[192:195], v[108:111]
	v_mfma_f32_16x16x32_bf16 v[104:107], v[176:179], v[192:195], v[104:107]
	v_mfma_f32_16x16x32_bf16 v[96:99], v[168:171], v[214:217], v[96:99]
	v_mfma_f32_16x16x32_bf16 v[88:91], v[176:179], v[214:217], v[88:91]
	v_mfma_f32_16x16x32_bf16 v[80:83], v[168:171], v[222:225], v[80:83]
	v_mfma_f32_16x16x32_bf16 v[72:75], v[176:179], v[222:225], v[72:75]
	s_setprio 0
	s_barrier
	s_add_i32 s66, s66, s52
	v_lshl_add_u64 v[142:143], s[22:23], 0, v[134:135]
	s_mov_b32 m0, s66
	ds_read_b128 v[180:183], v146 offset:16384
	ds_read_b128 v[184:187], v146 offset:17408
	ds_read_b128 v[188:191], v146 offset:18432
	ds_read_b128 v[192:195], v146 offset:19456
	ds_read_b128 v[210:213], v146 offset:20480
	ds_read_b128 v[214:217], v146 offset:21504
	ds_read_b128 v[218:221], v146 offset:22528
	ds_read_b128 v[222:225], v146 offset:23552
	global_load_lds_dwordx4 v[142:143], off
	s_add_i32 m0, s66, 0x2000
	s_add_u32 s66, s22, 0x10000
	v_lshl_add_u64 v[196:197], s[22:23], 0, v[0:1]
	s_addc_u32 s67, s23, 0
	s_add_i32 s68, s68, s52
	global_load_lds_dwordx4 v[196:197], off
	v_lshl_add_u64 v[198:199], s[66:67], 0, v[134:135]
	s_mov_b32 m0, s68
	v_lshl_add_u64 v[226:227], s[46:47], 0, v[132:133]
	global_load_lds_dwordx4 v[198:199], off
	v_lshl_add_u64 v[198:199], s[66:67], 0, v[0:1]
	s_add_i32 m0, s68, 0x2000
	s_nop 0
	global_load_lds_dwordx4 v[198:199], off
	v_lshl_add_u64 v[198:199], s[46:47], 0, v[136:137]
	s_mov_b32 m0, s53
	s_nop 0
	global_load_lds_dwordx4 v[198:199], off
	s_mov_b32 m0, s54
	s_nop 0
	global_load_lds_dwordx4 v[226:227], off
	s_waitcnt vmcnt(8)
	s_waitcnt lgkmcnt(0)
	s_barrier
; #define PG8_STAGE(bufoff, gbase, voff) do { _Pragma("unroll") for (int _i = 0; _i < 2; ++_i) \
;         __builtin_amdgcn_global_load_lds((const unsigned*)((const char*)(gbase) + (voff)[_i]), (LAS unsigned*)(lds + (bufoff) + ldsw + _i * 8192), 16, 0, 0); } while (0)
; #define PG8_LDA(dst, b, h) do { _Pragma("unroll") for (int m = 0; m < 4; ++m) _Pragma("unroll") for (int k = 0; k < 2; ++k) dst[m][k] = *(const LAS bf16x8*)(lds + PG8_SA(b, h) + aoff + m * 2048 + k * 1024); } while (0)
; #define PG8_LDB(dst, b, h) do { _Pragma("unroll") for (int n = 0; n < 2; ++n) _Pragma("unroll") for (int k = 0; k < 2; ++k) dst[n][k] = *(const LAS bf16x8*)(lds + PG8_SB(b, h) + boff + n * 2048 + k * 1024); } while (0)
; #define PG8_MMA(ai, bj, At, Bt) do { __builtin_amdgcn_s_setprio(1); _Pragma("unroll") for (int m = 0; m < 4; ++m) _Pragma("unroll") for (int n = 0; n < 2; ++n) _Pragma("unroll") for (int k = 0; k < 2; ++k) \
;         acc[ai][bj][m][n] = __builtin_amdgcn_mfma_f32_16x16x32_bf16(Bt[n][k], At[m][k], acc[ai][bj][m][n], 0, 0, 0); __builtin_amdgcn_s_setprio(0); } while (0)
; #define PG8_WAIT_V(n) asm volatile("s_waitcnt vmcnt(" #n ")" ::: "memory")
; #define PG8_WAIT_L(n) asm volatile("s_waitcnt lgkmcnt(" #n ")" ::: "memory")
; #define PG8_BAR __builtin_amdgcn_s_barrier()
; #define PG8_SCHED __builtin_amdgcn_sched_barrier(0)
; template <class Epi>
; __device__ __forceinline__ void gemm_phase(LAS unsigned char* lds, const Gemm g, const StaticOrder& S, const Epi& E) {
;     ...
;             PG8_WAIT_V(8); PG8_WAIT_L(0); PG8_BAR; PG8_MMA(1, 0, At, B0); PG8_MMA(1, 1, At, B1); PG8_BAR; PG8_SCHED;
;             PG8_LDB(B0, 1, 0); PG8_LDB(B1, 1, 1); PG8_SCHED; PG8_LDA(At, 1, 0); PG8_STAGE(PG8_SA(0, 1), a2 + hstepA, voffA);
;             PG8_WAIT_V(8); PG8_WAIT_L(0); PG8_BAR; PG8_MMA(0, 0, At, B0); PG8_MMA(0, 1, At, B1); PG8_BAR; PG8_SCHED;
	s_setprio 1
	s_waitcnt lgkmcnt(0)
	v_mfma_f32_16x16x32_bf16 v[60:63], v[148:151], v[180:183], v[60:63]
	v_mfma_f32_16x16x32_bf16 v[52:55], v[156:159], v[180:183], v[52:55]
	v_mfma_f32_16x16x32_bf16 v[44:47], v[148:151], v[188:191], v[44:47]
	v_mfma_f32_16x16x32_bf16 v[36:39], v[156:159], v[188:191], v[36:39]
	v_mfma_f32_16x16x32_bf16 v[28:31], v[148:151], v[210:213], v[28:31]
	v_mfma_f32_16x16x32_bf16 v[20:23], v[156:159], v[210:213], v[20:23]
	v_mfma_f32_16x16x32_bf16 v[4:7], v[148:151], v[218:221], v[4:7]
	v_mfma_f32_16x16x32_bf16 v[12:15], v[156:159], v[218:221], v[12:15]
	v_mfma_f32_16x16x32_bf16 v[60:63], v[152:155], v[184:187], v[60:63]
	v_mfma_f32_16x16x32_bf16 v[52:55], v[160:163], v[184:187], v[52:55]
	v_mfma_f32_16x16x32_bf16 v[44:47], v[152:155], v[192:195], v[44:47]
	v_mfma_f32_16x16x32_bf16 v[36:39], v[160:163], v[192:195], v[36:39]
	v_mfma_f32_16x16x32_bf16 v[28:31], v[152:155], v[214:217], v[28:31]
	v_mfma_f32_16x16x32_bf16 v[20:23], v[160:163], v[214:217], v[20:23]
	v_mfma_f32_16x16x32_bf16 v[4:7], v[152:155], v[222:225], v[4:7]
	v_mfma_f32_16x16x32_bf16 v[12:15], v[160:163], v[222:225], v[12:15]
	s_setprio 0
	s_setprio 1
	v_mfma_f32_16x16x32_bf16 v[64:67], v[164:167], v[180:183], v[64:67]
	v_mfma_f32_16x16x32_bf16 v[56:59], v[172:175], v[180:183], v[56:59]
	v_mfma_f32_16x16x32_bf16 v[48:51], v[164:167], v[188:191], v[48:51]
	v_mfma_f32_16x16x32_bf16 v[40:43], v[172:175], v[188:191], v[40:43]
	v_mfma_f32_16x16x32_bf16 v[32:35], v[164:167], v[210:213], v[32:35]
	v_mfma_f32_16x16x32_bf16 v[24:27], v[172:175], v[210:213], v[24:27]
	v_mfma_f32_16x16x32_bf16 v[8:11], v[164:167], v[218:221], v[8:11]
	v_mfma_f32_16x16x32_bf16 v[16:19], v[172:175], v[218:221], v[16:19]
	v_mfma_f32_16x16x32_bf16 v[64:67], v[168:171], v[184:187], v[64:67]
	v_mfma_f32_16x16x32_bf16 v[56:59], v[176:179], v[184:187], v[56:59]
	v_mfma_f32_16x16x32_bf16 v[48:51], v[168:171], v[192:195], v[48:51]
	v_mfma_f32_16x16x32_bf16 v[40:43], v[176:179], v[192:195], v[40:43]
	v_mfma_f32_16x16x32_bf16 v[32:35], v[168:171], v[214:217], v[32:35]
	v_mfma_f32_16x16x32_bf16 v[24:27], v[176:179], v[214:217], v[24:27]
	v_mfma_f32_16x16x32_bf16 v[8:11], v[168:171], v[222:225], v[8:11]
	v_mfma_f32_16x16x32_bf16 v[16:19], v[176:179], v[222:225], v[16:19]
	s_setprio 0
	s_barrier
	s_add_i32 s66, 0, 0x18000
	v_add_u32_e32 v147, s66, v144
	s_add_i32 s67, 0, 0x1c000
	ds_read_b128 v[148:151], v147
	ds_read_b128 v[152:155], v147 offset:1024
	ds_read_b128 v[156:159], v147 offset:2048
	ds_read_b128 v[160:163], v147 offset:3072
	v_add_u32_e32 v147, s67, v144
	ds_read_b128 v[164:167], v147
	ds_read_b128 v[168:171], v147 offset:1024
	ds_read_b128 v[172:175], v147 offset:2048
	ds_read_b128 v[176:179], v147 offset:3072
	s_add_u32 s46, s46, 0x40000
	s_addc_u32 s47, s47, 0
	s_mov_b32 m0, s55
	v_lshl_add_u64 v[228:229], s[46:47], 0, v[136:137]
	ds_read_b128 v[180:183], v146 offset:32768
	ds_read_b128 v[184:187], v146 offset:33792
	ds_read_b128 v[188:191], v146 offset:34816
	ds_read_b128 v[192:195], v146 offset:35840
	ds_read_b128 v[210:213], v146 offset:36864
	ds_read_b128 v[214:217], v146 offset:37888
	ds_read_b128 v[218:221], v146 offset:38912
	ds_read_b128 v[222:225], v146 offset:39936
	global_load_lds_dwordx4 v[228:229], off
	v_lshl_add_u64 v[228:229], s[46:47], 0, v[132:133]
	s_mov_b32 m0, s56
	s_nop 0
	global_load_lds_dwordx4 v[228:229], off
	s_waitcnt vmcnt(8)
	s_waitcnt lgkmcnt(0)
	s_barrier
	s_setprio 1
	s_waitcnt lgkmcnt(0)
	v_mfma_f32_16x16x32_bf16 v[128:131], v[148:151], v[180:183], v[128:131]
	v_mfma_f32_16x16x32_bf16 v[120:123], v[156:159], v[180:183], v[120:123]
	v_mfma_f32_16x16x32_bf16 v[112:115], v[148:151], v[188:191], v[112:115]
	v_mfma_f32_16x16x32_bf16 v[100:103], v[156:159], v[188:191], v[100:103]
	v_mfma_f32_16x16x32_bf16 v[92:95], v[148:151], v[210:213], v[92:95]
	v_mfma_f32_16x16x32_bf16 v[84:87], v[156:159], v[210:213], v[84:87]
	v_mfma_f32_16x16x32_bf16 v[76:79], v[148:151], v[218:221], v[76:79]
	v_mfma_f32_16x16x32_bf16 v[68:71], v[156:159], v[218:221], v[68:71]
	v_mfma_f32_16x16x32_bf16 v[128:131], v[152:155], v[184:187], v[128:131]
	v_mfma_f32_16x16x32_bf16 v[120:123], v[160:163], v[184:187], v[120:123]
	v_mfma_f32_16x16x32_bf16 v[112:115], v[152:155], v[192:195], v[112:115]
	v_mfma_f32_16x16x32_bf16 v[100:103], v[160:163], v[192:195], v[100:103]
	v_mfma_f32_16x16x32_bf16 v[92:95], v[152:155], v[214:217], v[92:95]
	v_mfma_f32_16x16x32_bf16 v[84:87], v[160:163], v[214:217], v[84:87]
	v_mfma_f32_16x16x32_bf16 v[76:79], v[152:155], v[222:225], v[76:79]
	v_mfma_f32_16x16x32_bf16 v[68:71], v[160:163], v[222:225], v[68:71]
	s_setprio 0
	s_setprio 1
	v_mfma_f32_16x16x32_bf16 v[124:127], v[164:167], v[180:183], v[124:127]
	v_mfma_f32_16x16x32_bf16 v[116:119], v[172:175], v[180:183], v[116:119]
	v_mfma_f32_16x16x32_bf16 v[108:111], v[164:167], v[188:191], v[108:111]
	v_mfma_f32_16x16x32_bf16 v[104:107], v[172:175], v[188:191], v[104:107]
	v_mfma_f32_16x16x32_bf16 v[96:99], v[164:167], v[210:213], v[96:99]
	v_mfma_f32_16x16x32_bf16 v[88:91], v[172:175], v[210:213], v[88:91]
	v_mfma_f32_16x16x32_bf16 v[80:83], v[164:167], v[218:221], v[80:83]
	v_mfma_f32_16x16x32_bf16 v[72:75], v[172:175], v[218:221], v[72:75]
	v_mfma_f32_16x16x32_bf16 v[124:127], v[168:171], v[184:187], v[124:127]
	v_mfma_f32_16x16x32_bf16 v[116:119], v[176:179], v[184:187], v[116:119]
	v_mfma_f32_16x16x32_bf16 v[108:111], v[168:171], v[192:195], v[108:111]
	v_mfma_f32_16x16x32_bf16 v[104:107], v[176:179], v[192:195], v[104:107]
	v_mfma_f32_16x16x32_bf16 v[96:99], v[168:171], v[214:217], v[96:99]
	v_mfma_f32_16x16x32_bf16 v[88:91], v[176:179], v[214:217], v[88:91]
	v_mfma_f32_16x16x32_bf16 v[80:83], v[168:171], v[222:225], v[80:83]
	v_mfma_f32_16x16x32_bf16 v[72:75], v[176:179], v[222:225], v[72:75]
	s_setprio 0
	s_barrier
; #define PG8_STAGE(bufoff, gbase, voff) do { _Pragma("unroll") for (int _i = 0; _i < 2; ++_i) \
;         __builtin_amdgcn_global_load_lds((const unsigned*)((const char*)(gbase) + (voff)[_i]), (LAS unsigned*)(lds + (bufoff) + ldsw + _i * 8192), 16, 0, 0); } while (0)
; #define PG8_LDA(dst, b, h) do { _Pragma("unroll") for (int m = 0; m < 4; ++m) _Pragma("unroll") for (int k = 0; k < 2; ++k) dst[m][k] = *(const LAS bf16x8*)(lds + PG8_SA(b, h) + aoff + m * 2048 + k * 1024); } while (0)
; #define PG8_MMA(ai, bj, At, Bt) do { __builtin_amdgcn_s_setprio(1); _Pragma("unroll") for (int m = 0; m < 4; ++m) _Pragma("unroll") for (int n = 0; n < 2; ++n) _Pragma("unroll") for (int k = 0; k < 2; ++k) \
;         acc[ai][bj][m][n] = __builtin_amdgcn_mfma_f32_16x16x32_bf16(Bt[n][k], At[m][k], acc[ai][bj][m][n], 0, 0, 0); __builtin_amdgcn_s_setprio(0); } while (0)
; #define PG8_WAIT_V(n) asm volatile("s_waitcnt vmcnt(" #n ")" ::: "memory")
; #define PG8_WAIT_L(n) asm volatile("s_waitcnt lgkmcnt(" #n ")" ::: "memory")
; #define PG8_BAR __builtin_amdgcn_s_barrier()
; #define PG8_SCHED __builtin_amdgcn_sched_barrier(0)
; template <class Epi>
; __device__ __forceinline__ void gemm_phase(LAS unsigned char* lds, const Gemm g, const StaticOrder& S, const Epi& E) {
;     ...
;             PG8_LDA(At, 1, 1); PG8_STAGE(PG8_SB(1, 0), b3, voffB); PG8_STAGE(PG8_SB(1, 1), b3 + hstepB, voffB); PG8_STAGE(PG8_SA(1, 0), a3, voffA);
;             PG8_WAIT_V(8); PG8_WAIT_L(0); PG8_BAR; PG8_MMA(1, 0, At, B0); PG8_MMA(1, 1, At, B1); PG8_BAR; PG8_SCHED;
;         }
;         if (wr == 0) PG8_BAR;
	s_add_i32 s46, s66, s52
	v_lshl_add_u64 v[142:143], v[142:143], 0, s[30:31]
	s_mov_b32 m0, s46
	ds_read_b128 v[180:183], v146 offset:49152
	ds_read_b128 v[184:187], v146 offset:50176
	ds_read_b128 v[188:191], v146 offset:51200
	ds_read_b128 v[192:195], v146 offset:52224
	ds_read_b128 v[210:213], v146 offset:53248
	ds_read_b128 v[214:217], v146 offset:54272
	ds_read_b128 v[218:221], v146 offset:55296
	ds_read_b128 v[222:225], v146 offset:56320
	global_load_lds_dwordx4 v[142:143], off
	s_add_i32 m0, s46, 0x2000
	s_add_u32 s22, s22, 0x10080
	v_lshl_add_u64 v[142:143], v[196:197], 0, s[30:31]
	s_addc_u32 s23, s23, 0
	s_add_i32 s46, s67, s52
	global_load_lds_dwordx4 v[142:143], off
	v_lshl_add_u64 v[142:143], s[22:23], 0, v[134:135]
	s_mov_b32 m0, s46
	s_nop 0
	global_load_lds_dwordx4 v[142:143], off
	v_lshl_add_u64 v[142:143], s[22:23], 0, v[0:1]
	s_add_i32 m0, s46, 0x2000
	s_nop 0
	global_load_lds_dwordx4 v[142:143], off
	v_lshl_add_u64 v[142:143], v[198:199], 0, s[30:31]
	s_mov_b32 m0, s28
	s_nop 0
	global_load_lds_dwordx4 v[142:143], off
	v_lshl_add_u64 v[142:143], v[226:227], 0, s[30:31]
	s_mov_b32 m0, s57
	s_nop 0
	global_load_lds_dwordx4 v[142:143], off
	s_waitcnt vmcnt(8)
	s_waitcnt lgkmcnt(0)
	s_barrier
	s_setprio 1
	s_waitcnt lgkmcnt(0)
	v_mfma_f32_16x16x32_bf16 v[60:63], v[148:151], v[180:183], v[60:63]
	v_mfma_f32_16x16x32_bf16 v[52:55], v[156:159], v[180:183], v[52:55]
	v_mfma_f32_16x16x32_bf16 v[44:47], v[148:151], v[188:191], v[44:47]
	v_mfma_f32_16x16x32_bf16 v[36:39], v[156:159], v[188:191], v[36:39]
	v_mfma_f32_16x16x32_bf16 v[28:31], v[148:151], v[210:213], v[28:31]
	v_mfma_f32_16x16x32_bf16 v[20:23], v[156:159], v[210:213], v[20:23]
	v_mfma_f32_16x16x32_bf16 v[4:7], v[148:151], v[218:221], v[4:7]
	v_mfma_f32_16x16x32_bf16 v[12:15], v[156:159], v[218:221], v[12:15]
	v_mfma_f32_16x16x32_bf16 v[60:63], v[152:155], v[184:187], v[60:63]
	v_mfma_f32_16x16x32_bf16 v[52:55], v[160:163], v[184:187], v[52:55]
	v_mfma_f32_16x16x32_bf16 v[44:47], v[152:155], v[192:195], v[44:47]
	v_mfma_f32_16x16x32_bf16 v[36:39], v[160:163], v[192:195], v[36:39]
	v_mfma_f32_16x16x32_bf16 v[28:31], v[152:155], v[214:217], v[28:31]
	v_mfma_f32_16x16x32_bf16 v[20:23], v[160:163], v[214:217], v[20:23]
	v_mfma_f32_16x16x32_bf16 v[4:7], v[152:155], v[222:225], v[4:7]
	v_mfma_f32_16x16x32_bf16 v[12:15], v[160:163], v[222:225], v[12:15]
	s_setprio 0
	s_setprio 1
	v_mfma_f32_16x16x32_bf16 v[64:67], v[164:167], v[180:183], v[64:67]
	v_mfma_f32_16x16x32_bf16 v[56:59], v[172:175], v[180:183], v[56:59]
	v_mfma_f32_16x16x32_bf16 v[48:51], v[164:167], v[188:191], v[48:51]
	v_mfma_f32_16x16x32_bf16 v[40:43], v[172:175], v[188:191], v[40:43]
	v_mfma_f32_16x16x32_bf16 v[32:35], v[164:167], v[210:213], v[32:35]
	v_mfma_f32_16x16x32_bf16 v[24:27], v[172:175], v[210:213], v[24:27]
	v_mfma_f32_16x16x32_bf16 v[8:11], v[164:167], v[218:221], v[8:11]
	v_mfma_f32_16x16x32_bf16 v[16:19], v[172:175], v[218:221], v[16:19]
	v_mfma_f32_16x16x32_bf16 v[64:67], v[168:171], v[184:187], v[64:67]
	v_mfma_f32_16x16x32_bf16 v[56:59], v[176:179], v[184:187], v[56:59]
	v_mfma_f32_16x16x32_bf16 v[48:51], v[168:171], v[192:195], v[48:51]
	v_mfma_f32_16x16x32_bf16 v[40:43], v[176:179], v[192:195], v[40:43]
	v_mfma_f32_16x16x32_bf16 v[32:35], v[168:171], v[214:217], v[32:35]
	v_mfma_f32_16x16x32_bf16 v[24:27], v[176:179], v[214:217], v[24:27]
	v_mfma_f32_16x16x32_bf16 v[8:11], v[168:171], v[222:225], v[8:11]
	v_mfma_f32_16x16x32_bf16 v[16:19], v[176:179], v[222:225], v[16:19]
	s_add_i32 s65, s65, 2
	s_add_u32 s44, s44, 0x100
	s_addc_u32 s45, s45, 0
	s_add_u32 s63, s63, 0x100
	s_addc_u32 s64, s64, 0
	s_cmp_gt_u32 s65, 13
	s_setprio 0
	s_barrier
	s_cbranch_scc0 .LBB0_163
	s_and_b64 vcc, exec, s[12:13]
	s_cbranch_vccz .LBB0_166
	s_barrier

; #define PG8_STAGE(bufoff, gbase, voff) do { _Pragma("unroll") for (int _i = 0; _i < 2; ++_i) \
;         __builtin_amdgcn_global_load_lds((const unsigned*)((const char*)(gbase) + (voff)[_i]), (LAS unsigned*)(lds + (bufoff) + ldsw + _i * 8192), 16, 0, 0); } while (0)
; #define PG8_LDA(dst, b, h) do { _Pragma("unroll") for (int m = 0; m < 4; ++m) _Pragma("unroll") for (int k = 0; k < 2; ++k) dst[m][k] = *(const LAS bf16x8*)(lds + PG8_SA(b, h) + aoff + m * 2048 + k * 1024); } while (0)
; #define PG8_LDB(dst, b, h) do { _Pragma("unroll") for (int n = 0; n < 2; ++n) _Pragma("unroll") for (int k = 0; k < 2; ++k) dst[n][k] = *(const LAS bf16x8*)(lds + PG8_SB(b, h) + boff + n * 2048 + k * 1024); } while (0)
; #define PG8_MMA(ai, bj, At, Bt) do { __builtin_amdgcn_s_setprio(1); _Pragma("unroll") for (int m = 0; m < 4; ++m) _Pragma("unroll") for (int n = 0; n < 2; ++n) _Pragma("unroll") for (int k = 0; k < 2; ++k) \
;         acc[ai][bj][m][n] = __builtin_amdgcn_mfma_f32_16x16x32_bf16(Bt[n][k], At[m][k], acc[ai][bj][m][n], 0, 0, 0); __builtin_amdgcn_s_setprio(0); } while (0)
; #define PG8_WAIT_V(n) asm volatile("s_waitcnt vmcnt(" #n ")" ::: "memory")
; #define PG8_WAIT_L(n) asm volatile("s_waitcnt lgkmcnt(" #n ")" ::: "memory")
; #define PG8_BAR __builtin_amdgcn_s_barrier()
; #define PG8_SCHED __builtin_amdgcn_sched_barrier(0)
; template <class Epi>
; __device__ __forceinline__ void gemm_phase(LAS unsigned char* lds, const Gemm g, const StaticOrder& S, const Epi& E) {
;     ...
;         for (int t = 0; t < nt; t += 2) {
;             const bool last = (t == nt - 2);
;             const char* a1 = cA + (size_t)(t + 1) * kstep;
;             const char* a2 = last ? nA : cA + (size_t)(t + 2) * kstep; const char* b2 = last ? nB : cB + (size_t)(t + 2) * kstep;
;             const char* a3 = a2 + kstep; const char* b3 = b2 + kstep;
;             PG8_LDB(B0, 0, 0); PG8_LDB(B1, 0, 1); PG8_SCHED; PG8_LDA(At, 0, 0); PG8_STAGE(PG8_SA(1, 1), a1 + hstepA, voffA);
;             PG8_WAIT_V(8); PG8_WAIT_L(0); PG8_BAR; PG8_MMA(0, 0, At, B0); PG8_MMA(0, 1, At, B1); PG8_BAR; PG8_SCHED;
;             PG8_LDA(At, 0, 1); PG8_STAGE(PG8_SB(0, 0), b2, voffB); PG8_STAGE(PG8_SB(0, 1), b2 + hstepB, voffB); PG8_STAGE(PG8_SA(0, 0), a2, voffA);
;             PG8_WAIT_V(8); PG8_WAIT_L(0); PG8_BAR; PG8_MMA(1, 0, At, B0); PG8_MMA(1, 1, At, B1); PG8_BAR; PG8_SCHED;
.LBB0_323:
	s_add_u32 s22, s34, 0xfffc0080
	s_addc_u32 s23, s35, -1
	s_add_i32 s52, 0, 0x10000
	s_cmp_eq_u32 s51, 12
	s_cselect_b32 s39, s41, s23
	s_cselect_b32 s38, s46, s22
	s_cselect_b32 s23, s47, s50
	s_cselect_b32 s22, s48, s49
	s_add_i32 s54, 0, 0x14000
	v_add_u32_e32 v160, s52, v147
	v_add_u32_e32 v172, s54, v147
	ds_read_b128 v[132:135], v160
	ds_read_b128 v[136:139], v160 offset:1024
	ds_read_b128 v[156:159], v160 offset:2048
	ds_read_b128 v[160:163], v160 offset:3072
	ds_read_b128 v[164:167], v172
	ds_read_b128 v[168:171], v172 offset:1024
	ds_read_b128 v[176:179], v172 offset:2048
	ds_read_b128 v[180:183], v172 offset:3072
	v_lshl_add_u64 v[172:173], s[34:35], 0, v[152:153]
	s_add_i32 m0, s75, 0xc000
	ds_read_b128 v[184:187], v174
	ds_read_b128 v[188:191], v174 offset:1024
	ds_read_b128 v[192:195], v174 offset:2048
	ds_read_b128 v[210:213], v174 offset:3072
	ds_read_b128 v[214:217], v174 offset:4096
	ds_read_b128 v[218:221], v174 offset:5120
	ds_read_b128 v[222:225], v174 offset:6144
	ds_read_b128 v[226:229], v174 offset:7168
	global_load_lds_dwordx4 v[172:173], off
	v_lshl_add_u64 v[172:173], s[34:35], 0, v[154:155]
	s_add_i32 m0, s75, 0xe000
	s_nop 0
	global_load_lds_dwordx4 v[172:173], off
	s_waitcnt vmcnt(8)
	s_waitcnt lgkmcnt(0)
	s_barrier
	s_setprio 1
	s_waitcnt lgkmcnt(0)
	v_mfma_f32_16x16x32_bf16 v[128:131], v[132:135], v[184:187], v[128:131]
	v_mfma_f32_16x16x32_bf16 v[124:127], v[156:159], v[184:187], v[124:127]
	v_mfma_f32_16x16x32_bf16 v[112:115], v[132:135], v[192:195], v[112:115]
	v_mfma_f32_16x16x32_bf16 v[108:111], v[156:159], v[192:195], v[108:111]
	v_mfma_f32_16x16x32_bf16 v[96:99], v[132:135], v[214:217], v[96:99]
	v_mfma_f32_16x16x32_bf16 v[92:95], v[156:159], v[214:217], v[92:95]
	v_mfma_f32_16x16x32_bf16 v[80:83], v[132:135], v[222:225], v[80:83]
	v_mfma_f32_16x16x32_bf16 v[76:79], v[156:159], v[222:225], v[76:79]
	v_mfma_f32_16x16x32_bf16 v[128:131], v[136:139], v[188:191], v[128:131]
	v_mfma_f32_16x16x32_bf16 v[124:127], v[160:163], v[188:191], v[124:127]
	v_mfma_f32_16x16x32_bf16 v[112:115], v[136:139], v[210:213], v[112:115]
	v_mfma_f32_16x16x32_bf16 v[108:111], v[160:163], v[210:213], v[108:111]
	v_mfma_f32_16x16x32_bf16 v[96:99], v[136:139], v[218:221], v[96:99]
	v_mfma_f32_16x16x32_bf16 v[92:95], v[160:163], v[218:221], v[92:95]
	v_mfma_f32_16x16x32_bf16 v[80:83], v[136:139], v[226:229], v[80:83]
	v_mfma_f32_16x16x32_bf16 v[76:79], v[160:163], v[226:229], v[76:79]
	s_setprio 0
	s_setprio 1
	v_mfma_f32_16x16x32_bf16 v[120:123], v[164:167], v[184:187], v[120:123]
	v_mfma_f32_16x16x32_bf16 v[116:119], v[176:179], v[184:187], v[116:119]
	v_mfma_f32_16x16x32_bf16 v[104:107], v[164:167], v[192:195], v[104:107]
	v_mfma_f32_16x16x32_bf16 v[100:103], v[176:179], v[192:195], v[100:103]
	v_mfma_f32_16x16x32_bf16 v[88:91], v[164:167], v[214:217], v[88:91]
	v_mfma_f32_16x16x32_bf16 v[84:87], v[176:179], v[214:217], v[84:87]
	v_mfma_f32_16x16x32_bf16 v[72:75], v[164:167], v[222:225], v[72:75]
	v_mfma_f32_16x16x32_bf16 v[68:71], v[176:179], v[222:225], v[68:71]
	v_mfma_f32_16x16x32_bf16 v[120:123], v[168:171], v[188:191], v[120:123]
	v_mfma_f32_16x16x32_bf16 v[116:119], v[180:183], v[188:191], v[116:119]
	v_mfma_f32_16x16x32_bf16 v[104:107], v[168:171], v[210:213], v[104:107]
	v_mfma_f32_16x16x32_bf16 v[100:103], v[180:183], v[210:213], v[100:103]
	v_mfma_f32_16x16x32_bf16 v[88:91], v[168:171], v[218:221], v[88:91]
	v_mfma_f32_16x16x32_bf16 v[84:87], v[180:183], v[218:221], v[84:87]
	v_mfma_f32_16x16x32_bf16 v[72:75], v[168:171], v[226:229], v[72:75]
	v_mfma_f32_16x16x32_bf16 v[68:71], v[180:183], v[226:229], v[68:71]
	s_setprio 0
	s_barrier
	s_add_i32 s52, s52, s74
	v_lshl_add_u64 v[172:173], s[22:23], 0, v[142:143]
	s_mov_b32 m0, s52
	ds_read_b128 v[184:187], v174 offset:16384
	ds_read_b128 v[188:191], v174 offset:17408
	ds_read_b128 v[192:195], v174 offset:18432
	ds_read_b128 v[210:213], v174 offset:19456
	ds_read_b128 v[214:217], v174 offset:20480
	ds_read_b128 v[218:221], v174 offset:21504
	ds_read_b128 v[222:225], v174 offset:22528
	ds_read_b128 v[226:229], v174 offset:23552
	global_load_lds_dwordx4 v[172:173], off
	s_add_i32 m0, s52, 0x2000
	s_add_u32 s52, s22, 0x10000
	v_lshl_add_u64 v[196:197], s[22:23], 0, v[0:1]
	s_addc_u32 s53, s23, 0
	s_add_i32 s54, s54, s74
	global_load_lds_dwordx4 v[196:197], off
	v_lshl_add_u64 v[198:199], s[52:53], 0, v[142:143]
	s_mov_b32 m0, s54
	v_lshl_add_u64 v[230:231], s[38:39], 0, v[140:141]
	global_load_lds_dwordx4 v[198:199], off
	v_lshl_add_u64 v[198:199], s[52:53], 0, v[0:1]
	s_add_i32 m0, s54, 0x2000
	s_nop 0
	global_load_lds_dwordx4 v[198:199], off
	v_lshl_add_u64 v[198:199], s[38:39], 0, v[144:145]
	s_mov_b32 m0, s75
	s_nop 0
	global_load_lds_dwordx4 v[198:199], off
	s_mov_b32 m0, s76
	s_nop 0
	global_load_lds_dwordx4 v[230:231], off
	s_waitcnt vmcnt(8)
	s_waitcnt lgkmcnt(0)
	s_barrier
; #define PG8_STAGE(bufoff, gbase, voff) do { _Pragma("unroll") for (int _i = 0; _i < 2; ++_i) \
;         __builtin_amdgcn_global_load_lds((const unsigned*)((const char*)(gbase) + (voff)[_i]), (LAS unsigned*)(lds + (bufoff) + ldsw + _i * 8192), 16, 0, 0); } while (0)
; #define PG8_LDA(dst, b, h) do { _Pragma("unroll") for (int m = 0; m < 4; ++m) _Pragma("unroll") for (int k = 0; k < 2; ++k) dst[m][k] = *(const LAS bf16x8*)(lds + PG8_SA(b, h) + aoff + m * 2048 + k * 1024); } while (0)
; #define PG8_LDB(dst, b, h) do { _Pragma("unroll") for (int n = 0; n < 2; ++n) _Pragma("unroll") for (int k = 0; k < 2; ++k) dst[n][k] = *(const LAS bf16x8*)(lds + PG8_SB(b, h) + boff + n * 2048 + k * 1024); } while (0)
; #define PG8_MMA(ai, bj, At, Bt) do { __builtin_amdgcn_s_setprio(1); _Pragma("unroll") for (int m = 0; m < 4; ++m) _Pragma("unroll") for (int n = 0; n < 2; ++n) _Pragma("unroll") for (int k = 0; k < 2; ++k) \
;         acc[ai][bj][m][n] = __builtin_amdgcn_mfma_f32_16x16x32_bf16(Bt[n][k], At[m][k], acc[ai][bj][m][n], 0, 0, 0); __builtin_amdgcn_s_setprio(0); } while (0)
; #define PG8_WAIT_V(n) asm volatile("s_waitcnt vmcnt(" #n ")" ::: "memory")
; #define PG8_WAIT_L(n) asm volatile("s_waitcnt lgkmcnt(" #n ")" ::: "memory")
; #define PG8_BAR __builtin_amdgcn_s_barrier()
; #define PG8_SCHED __builtin_amdgcn_sched_barrier(0)
; template <class Epi>
; __device__ __forceinline__ void gemm_phase(LAS unsigned char* lds, const Gemm g, const StaticOrder& S, const Epi& E) {
;     ...
;             PG8_WAIT_V(8); PG8_WAIT_L(0); PG8_BAR; PG8_MMA(1, 0, At, B0); PG8_MMA(1, 1, At, B1); PG8_BAR; PG8_SCHED;
;             PG8_LDB(B0, 1, 0); PG8_LDB(B1, 1, 1); PG8_SCHED; PG8_LDA(At, 1, 0); PG8_STAGE(PG8_SA(0, 1), a2 + hstepA, voffA);
;             PG8_WAIT_V(8); PG8_WAIT_L(0); PG8_BAR; PG8_MMA(0, 0, At, B0); PG8_MMA(0, 1, At, B1); PG8_BAR; PG8_SCHED;
	s_setprio 1
	s_waitcnt lgkmcnt(0)
	v_mfma_f32_16x16x32_bf16 v[64:67], v[132:135], v[184:187], v[64:67]
	v_mfma_f32_16x16x32_bf16 v[60:63], v[156:159], v[184:187], v[60:63]
	v_mfma_f32_16x16x32_bf16 v[48:51], v[132:135], v[192:195], v[48:51]
	v_mfma_f32_16x16x32_bf16 v[44:47], v[156:159], v[192:195], v[44:47]
	v_mfma_f32_16x16x32_bf16 v[32:35], v[132:135], v[214:217], v[32:35]
	v_mfma_f32_16x16x32_bf16 v[28:31], v[156:159], v[214:217], v[28:31]
	v_mfma_f32_16x16x32_bf16 v[16:19], v[132:135], v[222:225], v[16:19]
	v_mfma_f32_16x16x32_bf16 v[12:15], v[156:159], v[222:225], v[12:15]
	v_mfma_f32_16x16x32_bf16 v[64:67], v[136:139], v[188:191], v[64:67]
	v_mfma_f32_16x16x32_bf16 v[60:63], v[160:163], v[188:191], v[60:63]
	v_mfma_f32_16x16x32_bf16 v[48:51], v[136:139], v[210:213], v[48:51]
	v_mfma_f32_16x16x32_bf16 v[44:47], v[160:163], v[210:213], v[44:47]
	v_mfma_f32_16x16x32_bf16 v[32:35], v[136:139], v[218:221], v[32:35]
	v_mfma_f32_16x16x32_bf16 v[28:31], v[160:163], v[218:221], v[28:31]
	v_mfma_f32_16x16x32_bf16 v[16:19], v[136:139], v[226:229], v[16:19]
	v_mfma_f32_16x16x32_bf16 v[12:15], v[160:163], v[226:229], v[12:15]
	s_setprio 0
	s_setprio 1
	v_mfma_f32_16x16x32_bf16 v[56:59], v[164:167], v[184:187], v[56:59]
	v_mfma_f32_16x16x32_bf16 v[52:55], v[176:179], v[184:187], v[52:55]
	v_mfma_f32_16x16x32_bf16 v[40:43], v[164:167], v[192:195], v[40:43]
	v_mfma_f32_16x16x32_bf16 v[36:39], v[176:179], v[192:195], v[36:39]
	v_mfma_f32_16x16x32_bf16 v[24:27], v[164:167], v[214:217], v[24:27]
	v_mfma_f32_16x16x32_bf16 v[20:23], v[176:179], v[214:217], v[20:23]
	v_mfma_f32_16x16x32_bf16 v[8:11], v[164:167], v[222:225], v[8:11]
	v_mfma_f32_16x16x32_bf16 v[4:7], v[176:179], v[222:225], v[4:7]
	v_mfma_f32_16x16x32_bf16 v[56:59], v[168:171], v[188:191], v[56:59]
	v_mfma_f32_16x16x32_bf16 v[52:55], v[180:183], v[188:191], v[52:55]
	v_mfma_f32_16x16x32_bf16 v[40:43], v[168:171], v[210:213], v[40:43]
	v_mfma_f32_16x16x32_bf16 v[36:39], v[180:183], v[210:213], v[36:39]
	v_mfma_f32_16x16x32_bf16 v[24:27], v[168:171], v[218:221], v[24:27]
	v_mfma_f32_16x16x32_bf16 v[20:23], v[180:183], v[218:221], v[20:23]
	v_mfma_f32_16x16x32_bf16 v[8:11], v[168:171], v[226:229], v[8:11]
	v_mfma_f32_16x16x32_bf16 v[4:7], v[180:183], v[226:229], v[4:7]
	s_setprio 0
	s_barrier
	s_add_i32 s52, 0, 0x18000
	s_add_i32 s53, 0, 0x1c000
	v_add_u32_e32 v160, s52, v147
	v_add_u32_e32 v175, s53, v147
	ds_read_b128 v[132:135], v160
	ds_read_b128 v[136:139], v160 offset:1024
	ds_read_b128 v[156:159], v160 offset:2048
	ds_read_b128 v[160:163], v160 offset:3072
	ds_read_b128 v[164:167], v175
	ds_read_b128 v[168:171], v175 offset:1024
	ds_read_b128 v[176:179], v175 offset:2048
	ds_read_b128 v[180:183], v175 offset:3072
	s_add_u32 s38, s38, 0x40000
	s_addc_u32 s39, s39, 0
	s_mov_b32 m0, s77
	v_lshl_add_u64 v[232:233], s[38:39], 0, v[144:145]
	ds_read_b128 v[184:187], v174 offset:32768
	ds_read_b128 v[188:191], v174 offset:33792
	ds_read_b128 v[192:195], v174 offset:34816
	ds_read_b128 v[210:213], v174 offset:35840
	ds_read_b128 v[214:217], v174 offset:36864
	ds_read_b128 v[218:221], v174 offset:37888
	ds_read_b128 v[222:225], v174 offset:38912
	ds_read_b128 v[226:229], v174 offset:39936
	global_load_lds_dwordx4 v[232:233], off
	v_lshl_add_u64 v[232:233], s[38:39], 0, v[140:141]
	s_mov_b32 m0, s78
	s_nop 0
	global_load_lds_dwordx4 v[232:233], off
	s_waitcnt vmcnt(8)
	s_waitcnt lgkmcnt(0)
	s_barrier
	s_setprio 1
	s_waitcnt lgkmcnt(0)
	v_mfma_f32_16x16x32_bf16 v[128:131], v[132:135], v[184:187], v[128:131]
	v_mfma_f32_16x16x32_bf16 v[124:127], v[156:159], v[184:187], v[124:127]
	v_mfma_f32_16x16x32_bf16 v[112:115], v[132:135], v[192:195], v[112:115]
	v_mfma_f32_16x16x32_bf16 v[108:111], v[156:159], v[192:195], v[108:111]
	v_mfma_f32_16x16x32_bf16 v[96:99], v[132:135], v[214:217], v[96:99]
	v_mfma_f32_16x16x32_bf16 v[92:95], v[156:159], v[214:217], v[92:95]
	v_mfma_f32_16x16x32_bf16 v[80:83], v[132:135], v[222:225], v[80:83]
	v_mfma_f32_16x16x32_bf16 v[76:79], v[156:159], v[222:225], v[76:79]
	v_mfma_f32_16x16x32_bf16 v[128:131], v[136:139], v[188:191], v[128:131]
	v_mfma_f32_16x16x32_bf16 v[124:127], v[160:163], v[188:191], v[124:127]
	v_mfma_f32_16x16x32_bf16 v[112:115], v[136:139], v[210:213], v[112:115]
	v_mfma_f32_16x16x32_bf16 v[108:111], v[160:163], v[210:213], v[108:111]
	v_mfma_f32_16x16x32_bf16 v[96:99], v[136:139], v[218:221], v[96:99]
	v_mfma_f32_16x16x32_bf16 v[92:95], v[160:163], v[218:221], v[92:95]
	v_mfma_f32_16x16x32_bf16 v[80:83], v[136:139], v[226:229], v[80:83]
	v_mfma_f32_16x16x32_bf16 v[76:79], v[160:163], v[226:229], v[76:79]
	s_setprio 0
	s_setprio 1
	v_mfma_f32_16x16x32_bf16 v[120:123], v[164:167], v[184:187], v[120:123]
	v_mfma_f32_16x16x32_bf16 v[116:119], v[176:179], v[184:187], v[116:119]
	v_mfma_f32_16x16x32_bf16 v[104:107], v[164:167], v[192:195], v[104:107]
	v_mfma_f32_16x16x32_bf16 v[100:103], v[176:179], v[192:195], v[100:103]
	v_mfma_f32_16x16x32_bf16 v[88:91], v[164:167], v[214:217], v[88:91]
	v_mfma_f32_16x16x32_bf16 v[84:87], v[176:179], v[214:217], v[84:87]
	v_mfma_f32_16x16x32_bf16 v[72:75], v[164:167], v[222:225], v[72:75]
	v_mfma_f32_16x16x32_bf16 v[68:71], v[176:179], v[222:225], v[68:71]
	v_mfma_f32_16x16x32_bf16 v[120:123], v[168:171], v[188:191], v[120:123]
	v_mfma_f32_16x16x32_bf16 v[116:119], v[180:183], v[188:191], v[116:119]
	v_mfma_f32_16x16x32_bf16 v[104:107], v[168:171], v[210:213], v[104:107]
	v_mfma_f32_16x16x32_bf16 v[100:103], v[180:183], v[210:213], v[100:103]
	v_mfma_f32_16x16x32_bf16 v[88:91], v[168:171], v[218:221], v[88:91]
	v_mfma_f32_16x16x32_bf16 v[84:87], v[180:183], v[218:221], v[84:87]
	v_mfma_f32_16x16x32_bf16 v[72:75], v[168:171], v[226:229], v[72:75]
	v_mfma_f32_16x16x32_bf16 v[68:71], v[180:183], v[226:229], v[68:71]
	s_setprio 0
	s_barrier
; #define PG8_STAGE(bufoff, gbase, voff) do { _Pragma("unroll") for (int _i = 0; _i < 2; ++_i) \
;         __builtin_amdgcn_global_load_lds((const unsigned*)((const char*)(gbase) + (voff)[_i]), (LAS unsigned*)(lds + (bufoff) + ldsw + _i * 8192), 16, 0, 0); } while (0)
; #define PG8_LDA(dst, b, h) do { _Pragma("unroll") for (int m = 0; m < 4; ++m) _Pragma("unroll") for (int k = 0; k < 2; ++k) dst[m][k] = *(const LAS bf16x8*)(lds + PG8_SA(b, h) + aoff + m * 2048 + k * 1024); } while (0)
; #define PG8_MMA(ai, bj, At, Bt) do { __builtin_amdgcn_s_setprio(1); _Pragma("unroll") for (int m = 0; m < 4; ++m) _Pragma("unroll") for (int n = 0; n < 2; ++n) _Pragma("unroll") for (int k = 0; k < 2; ++k) \
;         acc[ai][bj][m][n] = __builtin_amdgcn_mfma_f32_16x16x32_bf16(Bt[n][k], At[m][k], acc[ai][bj][m][n], 0, 0, 0); __builtin_amdgcn_s_setprio(0); } while (0)
; #define PG8_WAIT_V(n) asm volatile("s_waitcnt vmcnt(" #n ")" ::: "memory")
; #define PG8_WAIT_L(n) asm volatile("s_waitcnt lgkmcnt(" #n ")" ::: "memory")
; #define PG8_BAR __builtin_amdgcn_s_barrier()
; #define PG8_SCHED __builtin_amdgcn_sched_barrier(0)
; template <class Epi>
; __device__ __forceinline__ void gemm_phase(LAS unsigned char* lds, const Gemm g, const StaticOrder& S, const Epi& E) {
;     ...
;             PG8_LDA(At, 1, 1); PG8_STAGE(PG8_SB(1, 0), b3, voffB); PG8_STAGE(PG8_SB(1, 1), b3 + hstepB, voffB); PG8_STAGE(PG8_SA(1, 0), a3, voffA);
;             PG8_WAIT_V(8); PG8_WAIT_L(0); PG8_BAR; PG8_MMA(1, 0, At, B0); PG8_MMA(1, 1, At, B1); PG8_BAR; PG8_SCHED;
;         }
;         if (wr == 0) PG8_BAR;
	s_add_i32 s38, s52, s74
	v_lshl_add_u64 v[172:173], v[172:173], 0, s[30:31]
	s_mov_b32 m0, s38
	ds_read_b128 v[184:187], v174 offset:49152
	ds_read_b128 v[188:191], v174 offset:50176
	ds_read_b128 v[192:195], v174 offset:51200
	ds_read_b128 v[210:213], v174 offset:52224
	ds_read_b128 v[214:217], v174 offset:53248
	ds_read_b128 v[218:221], v174 offset:54272
	ds_read_b128 v[222:225], v174 offset:55296
	ds_read_b128 v[226:229], v174 offset:56320
	global_load_lds_dwordx4 v[172:173], off
	s_add_i32 m0, s38, 0x2000
	s_add_u32 s22, s22, 0x10080
	v_lshl_add_u64 v[172:173], v[196:197], 0, s[30:31]
	s_addc_u32 s23, s23, 0
	s_add_i32 s38, s53, s74
	global_load_lds_dwordx4 v[172:173], off
	v_lshl_add_u64 v[172:173], s[22:23], 0, v[142:143]
	s_mov_b32 m0, s38
	s_nop 0
	global_load_lds_dwordx4 v[172:173], off
	v_lshl_add_u64 v[172:173], s[22:23], 0, v[0:1]
	s_add_i32 m0, s38, 0x2000
	s_nop 0
	global_load_lds_dwordx4 v[172:173], off
	v_lshl_add_u64 v[172:173], v[198:199], 0, s[30:31]
	s_mov_b32 m0, s85
	s_nop 0
	global_load_lds_dwordx4 v[172:173], off
	v_lshl_add_u64 v[172:173], v[230:231], 0, s[30:31]
	s_mov_b32 m0, s86
	s_nop 0
	global_load_lds_dwordx4 v[172:173], off
	s_waitcnt vmcnt(8)
	s_waitcnt lgkmcnt(0)
	s_barrier
	s_setprio 1
	s_waitcnt lgkmcnt(0)
	v_mfma_f32_16x16x32_bf16 v[64:67], v[132:135], v[184:187], v[64:67]
	v_mfma_f32_16x16x32_bf16 v[60:63], v[156:159], v[184:187], v[60:63]
	v_mfma_f32_16x16x32_bf16 v[48:51], v[132:135], v[192:195], v[48:51]
	v_mfma_f32_16x16x32_bf16 v[44:47], v[156:159], v[192:195], v[44:47]
	v_mfma_f32_16x16x32_bf16 v[32:35], v[132:135], v[214:217], v[32:35]
	v_mfma_f32_16x16x32_bf16 v[28:31], v[156:159], v[214:217], v[28:31]
	v_mfma_f32_16x16x32_bf16 v[16:19], v[132:135], v[222:225], v[16:19]
	v_mfma_f32_16x16x32_bf16 v[12:15], v[156:159], v[222:225], v[12:15]
	v_mfma_f32_16x16x32_bf16 v[64:67], v[136:139], v[188:191], v[64:67]
	v_mfma_f32_16x16x32_bf16 v[60:63], v[160:163], v[188:191], v[60:63]
	v_mfma_f32_16x16x32_bf16 v[48:51], v[136:139], v[210:213], v[48:51]
	v_mfma_f32_16x16x32_bf16 v[44:47], v[160:163], v[210:213], v[44:47]
	v_mfma_f32_16x16x32_bf16 v[32:35], v[136:139], v[218:221], v[32:35]
	v_mfma_f32_16x16x32_bf16 v[28:31], v[160:163], v[218:221], v[28:31]
	v_mfma_f32_16x16x32_bf16 v[16:19], v[136:139], v[226:229], v[16:19]
	v_mfma_f32_16x16x32_bf16 v[12:15], v[160:163], v[226:229], v[12:15]
	s_setprio 0
	s_setprio 1
	v_mfma_f32_16x16x32_bf16 v[56:59], v[164:167], v[184:187], v[56:59]
	v_mfma_f32_16x16x32_bf16 v[52:55], v[176:179], v[184:187], v[52:55]
	v_mfma_f32_16x16x32_bf16 v[40:43], v[164:167], v[192:195], v[40:43]
	v_mfma_f32_16x16x32_bf16 v[36:39], v[176:179], v[192:195], v[36:39]
	v_mfma_f32_16x16x32_bf16 v[24:27], v[164:167], v[214:217], v[24:27]
	v_mfma_f32_16x16x32_bf16 v[20:23], v[176:179], v[214:217], v[20:23]
	v_mfma_f32_16x16x32_bf16 v[8:11], v[164:167], v[222:225], v[8:11]
	v_mfma_f32_16x16x32_bf16 v[4:7], v[176:179], v[222:225], v[4:7]
	v_mfma_f32_16x16x32_bf16 v[56:59], v[168:171], v[188:191], v[56:59]
	v_mfma_f32_16x16x32_bf16 v[52:55], v[180:183], v[188:191], v[52:55]
	v_mfma_f32_16x16x32_bf16 v[40:43], v[168:171], v[210:213], v[40:43]
	v_mfma_f32_16x16x32_bf16 v[36:39], v[180:183], v[210:213], v[36:39]
	v_mfma_f32_16x16x32_bf16 v[24:27], v[168:171], v[218:221], v[24:27]
	v_mfma_f32_16x16x32_bf16 v[20:23], v[180:183], v[218:221], v[20:23]
	v_mfma_f32_16x16x32_bf16 v[8:11], v[168:171], v[226:229], v[8:11]
	v_mfma_f32_16x16x32_bf16 v[4:7], v[180:183], v[226:229], v[4:7]
	s_add_i32 s51, s51, 2
	s_add_u32 s34, s34, 0x100
	s_addc_u32 s35, s35, 0
	s_add_u32 s49, s49, 0x100
	s_addc_u32 s50, s50, 0
	s_cmp_gt_u32 s51, 13
	s_setprio 0
	s_barrier
	s_cbranch_scc0 .LBB0_323
	s_and_b64 vcc, exec, s[14:15]
	s_cbranch_vccz .LBB0_326
	s_barrier

; #define PG8_STAGE(bufoff, gbase, voff) do { _Pragma("unroll") for (int _i = 0; _i < 2; ++_i) \
;         __builtin_amdgcn_global_load_lds((const unsigned*)((const char*)(gbase) + (voff)[_i]), (LAS unsigned*)(lds + (bufoff) + ldsw + _i * 8192), 16, 0, 0); } while (0)
; #define PG8_LDA(dst, b, h) do { _Pragma("unroll") for (int m = 0; m < 4; ++m) _Pragma("unroll") for (int k = 0; k < 2; ++k) dst[m][k] = *(const LAS bf16x8*)(lds + PG8_SA(b, h) + aoff + m * 2048 + k * 1024); } while (0)
; #define PG8_LDB(dst, b, h) do { _Pragma("unroll") for (int n = 0; n < 2; ++n) _Pragma("unroll") for (int k = 0; k < 2; ++k) dst[n][k] = *(const LAS bf16x8*)(lds + PG8_SB(b, h) + boff + n * 2048 + k * 1024); } while (0)
; #define PG8_MMA(ai, bj, At, Bt) do { __builtin_amdgcn_s_setprio(1); _Pragma("unroll") for (int m = 0; m < 4; ++m) _Pragma("unroll") for (int n = 0; n < 2; ++n) _Pragma("unroll") for (int k = 0; k < 2; ++k) \
;         acc[ai][bj][m][n] = __builtin_amdgcn_mfma_f32_16x16x32_bf16(Bt[n][k], At[m][k], acc[ai][bj][m][n], 0, 0, 0); __builtin_amdgcn_s_setprio(0); } while (0)
; #define PG8_WAIT_V(n) asm volatile("s_waitcnt vmcnt(" #n ")" ::: "memory")
; #define PG8_WAIT_L(n) asm volatile("s_waitcnt lgkmcnt(" #n ")" ::: "memory")
; #define PG8_BAR __builtin_amdgcn_s_barrier()
; #define PG8_SCHED __builtin_amdgcn_sched_barrier(0)
; template <class Epi>
; __device__ __forceinline__ void gemm_phase(LAS unsigned char* lds, const Gemm g, const StaticOrder& S, const Epi& E) {
;     ...
;         for (int t = 0; t < nt; t += 2) {
;             const bool last = (t == nt - 2);
;             const char* a1 = cA + (size_t)(t + 1) * kstep;
;             const char* a2 = last ? nA : cA + (size_t)(t + 2) * kstep; const char* b2 = last ? nB : cB + (size_t)(t + 2) * kstep;
;             const char* a3 = a2 + kstep; const char* b3 = b2 + kstep;
;             PG8_LDB(B0, 0, 0); PG8_LDB(B1, 0, 1); PG8_SCHED; PG8_LDA(At, 0, 0); PG8_STAGE(PG8_SA(1, 1), a1 + hstepA, voffA);
;             PG8_WAIT_V(8); PG8_WAIT_L(0); PG8_BAR; PG8_MMA(0, 0, At, B0); PG8_MMA(0, 1, At, B1); PG8_BAR; PG8_SCHED;
;             PG8_LDA(At, 0, 1); PG8_STAGE(PG8_SB(0, 0), b2, voffB); PG8_STAGE(PG8_SB(0, 1), b2 + hstepB, voffB); PG8_STAGE(PG8_SA(0, 0), a2, voffA);
;             PG8_WAIT_V(8); PG8_WAIT_L(0); PG8_BAR; PG8_MMA(1, 0, At, B0); PG8_MMA(1, 1, At, B1); PG8_BAR; PG8_SCHED;
.LBB0_551:
	s_add_u32 s22, s44, 0xfffc0080
	s_addc_u32 s23, s45, -1
	s_add_i32 s66, 0, 0x10000
	s_cmp_eq_u32 s65, 12
	s_cselect_b32 s47, s35, s23
	s_cselect_b32 s46, s61, s22
	v_add_u32_e32 v150, s66, v152
	s_cselect_b32 s23, s15, s64
	s_cselect_b32 s22, s62, s63
	s_add_i32 s68, 0, 0x14000
	ds_read_b128 v[142:145], v150
	ds_read_b128 v[146:149], v150 offset:1024
	ds_read_b128 v[156:159], v150 offset:2048
	ds_read_b128 v[160:163], v150 offset:3072
	v_add_u32_e32 v150, s68, v152
	ds_read_b128 v[164:167], v150
	ds_read_b128 v[168:171], v150 offset:1024
	ds_read_b128 v[172:175], v150 offset:2048
	ds_read_b128 v[176:179], v150 offset:3072
	v_lshl_add_u64 v[150:151], s[44:45], 0, v[138:139]
	s_add_i32 m0, s52, 0xc000
	ds_read_b128 v[180:183], v154
	ds_read_b128 v[184:187], v154 offset:1024
	ds_read_b128 v[188:191], v154 offset:2048
	ds_read_b128 v[192:195], v154 offset:3072
	ds_read_b128 v[210:213], v154 offset:4096
	ds_read_b128 v[214:217], v154 offset:5120
	ds_read_b128 v[218:221], v154 offset:6144
	ds_read_b128 v[222:225], v154 offset:7168
	global_load_lds_dwordx4 v[150:151], off
	v_lshl_add_u64 v[150:151], s[44:45], 0, v[140:141]
	s_add_i32 m0, s52, 0xe000
	s_nop 0
	global_load_lds_dwordx4 v[150:151], off
	s_waitcnt vmcnt(8)
	s_waitcnt lgkmcnt(0)
	s_barrier
	s_setprio 1
	s_waitcnt lgkmcnt(0)
	v_mfma_f32_16x16x32_bf16 v[128:131], v[142:145], v[180:183], v[128:131]
	v_mfma_f32_16x16x32_bf16 v[124:127], v[156:159], v[180:183], v[124:127]
	v_mfma_f32_16x16x32_bf16 v[120:123], v[142:145], v[188:191], v[120:123]
	v_mfma_f32_16x16x32_bf16 v[116:119], v[156:159], v[188:191], v[116:119]
	v_mfma_f32_16x16x32_bf16 v[112:115], v[142:145], v[210:213], v[112:115]
	v_mfma_f32_16x16x32_bf16 v[108:111], v[156:159], v[210:213], v[108:111]
	v_mfma_f32_16x16x32_bf16 v[104:107], v[142:145], v[218:221], v[104:107]
	v_mfma_f32_16x16x32_bf16 v[100:103], v[156:159], v[218:221], v[100:103]
	v_mfma_f32_16x16x32_bf16 v[128:131], v[146:149], v[184:187], v[128:131]
	v_mfma_f32_16x16x32_bf16 v[124:127], v[160:163], v[184:187], v[124:127]
	v_mfma_f32_16x16x32_bf16 v[120:123], v[146:149], v[192:195], v[120:123]
	v_mfma_f32_16x16x32_bf16 v[116:119], v[160:163], v[192:195], v[116:119]
	v_mfma_f32_16x16x32_bf16 v[112:115], v[146:149], v[214:217], v[112:115]
	v_mfma_f32_16x16x32_bf16 v[108:111], v[160:163], v[214:217], v[108:111]
	v_mfma_f32_16x16x32_bf16 v[104:107], v[146:149], v[222:225], v[104:107]
	v_mfma_f32_16x16x32_bf16 v[100:103], v[160:163], v[222:225], v[100:103]
	s_setprio 0
	s_setprio 1
	v_mfma_f32_16x16x32_bf16 v[64:67], v[164:167], v[180:183], v[64:67]
	v_mfma_f32_16x16x32_bf16 v[60:63], v[172:175], v[180:183], v[60:63]
	v_mfma_f32_16x16x32_bf16 v[56:59], v[164:167], v[188:191], v[56:59]
	v_mfma_f32_16x16x32_bf16 v[52:55], v[172:175], v[188:191], v[52:55]
	v_mfma_f32_16x16x32_bf16 v[48:51], v[164:167], v[210:213], v[48:51]
	v_mfma_f32_16x16x32_bf16 v[44:47], v[172:175], v[210:213], v[44:47]
	v_mfma_f32_16x16x32_bf16 v[40:43], v[164:167], v[218:221], v[40:43]
	v_mfma_f32_16x16x32_bf16 v[36:39], v[172:175], v[218:221], v[36:39]
	v_mfma_f32_16x16x32_bf16 v[64:67], v[168:171], v[184:187], v[64:67]
	v_mfma_f32_16x16x32_bf16 v[60:63], v[176:179], v[184:187], v[60:63]
	v_mfma_f32_16x16x32_bf16 v[56:59], v[168:171], v[192:195], v[56:59]
	v_mfma_f32_16x16x32_bf16 v[52:55], v[176:179], v[192:195], v[52:55]
	v_mfma_f32_16x16x32_bf16 v[48:51], v[168:171], v[214:217], v[48:51]
	v_mfma_f32_16x16x32_bf16 v[44:47], v[176:179], v[214:217], v[44:47]
	v_mfma_f32_16x16x32_bf16 v[40:43], v[168:171], v[222:225], v[40:43]
	v_mfma_f32_16x16x32_bf16 v[36:39], v[176:179], v[222:225], v[36:39]
	s_setprio 0
	s_barrier
	s_add_i32 s66, s66, s51
	v_lshl_add_u64 v[150:151], s[22:23], 0, v[134:135]
	s_mov_b32 m0, s66
	ds_read_b128 v[180:183], v154 offset:16384
	ds_read_b128 v[184:187], v154 offset:17408
	ds_read_b128 v[188:191], v154 offset:18432
	ds_read_b128 v[192:195], v154 offset:19456
	ds_read_b128 v[210:213], v154 offset:20480
	ds_read_b128 v[214:217], v154 offset:21504
	ds_read_b128 v[218:221], v154 offset:22528
	ds_read_b128 v[222:225], v154 offset:23552
	global_load_lds_dwordx4 v[150:151], off
	s_add_i32 m0, s66, 0x2000
	s_add_u32 s66, s22, 0x10000
	v_lshl_add_u64 v[196:197], s[22:23], 0, v[0:1]
	s_addc_u32 s67, s23, 0
	s_add_i32 s68, s68, s51
	global_load_lds_dwordx4 v[196:197], off
	v_lshl_add_u64 v[198:199], s[66:67], 0, v[134:135]
	s_mov_b32 m0, s68
	v_lshl_add_u64 v[226:227], s[46:47], 0, v[132:133]
	global_load_lds_dwordx4 v[198:199], off
	v_lshl_add_u64 v[198:199], s[66:67], 0, v[0:1]
	s_add_i32 m0, s68, 0x2000
	s_nop 0
	global_load_lds_dwordx4 v[198:199], off
	v_lshl_add_u64 v[198:199], s[46:47], 0, v[136:137]
	s_mov_b32 m0, s52
	s_nop 0
	global_load_lds_dwordx4 v[198:199], off
	s_mov_b32 m0, s53
	s_nop 0
	global_load_lds_dwordx4 v[226:227], off
	s_waitcnt vmcnt(8)
	s_waitcnt lgkmcnt(0)
	s_barrier
; #define PG8_STAGE(bufoff, gbase, voff) do { _Pragma("unroll") for (int _i = 0; _i < 2; ++_i) \
;         __builtin_amdgcn_global_load_lds((const unsigned*)((const char*)(gbase) + (voff)[_i]), (LAS unsigned*)(lds + (bufoff) + ldsw + _i * 8192), 16, 0, 0); } while (0)
; #define PG8_LDA(dst, b, h) do { _Pragma("unroll") for (int m = 0; m < 4; ++m) _Pragma("unroll") for (int k = 0; k < 2; ++k) dst[m][k] = *(const LAS bf16x8*)(lds + PG8_SA(b, h) + aoff + m * 2048 + k * 1024); } while (0)
; #define PG8_LDB(dst, b, h) do { _Pragma("unroll") for (int n = 0; n < 2; ++n) _Pragma("unroll") for (int k = 0; k < 2; ++k) dst[n][k] = *(const LAS bf16x8*)(lds + PG8_SB(b, h) + boff + n * 2048 + k * 1024); } while (0)
; #define PG8_MMA(ai, bj, At, Bt) do { __builtin_amdgcn_s_setprio(1); _Pragma("unroll") for (int m = 0; m < 4; ++m) _Pragma("unroll") for (int n = 0; n < 2; ++n) _Pragma("unroll") for (int k = 0; k < 2; ++k) \
;         acc[ai][bj][m][n] = __builtin_amdgcn_mfma_f32_16x16x32_bf16(Bt[n][k], At[m][k], acc[ai][bj][m][n], 0, 0, 0); __builtin_amdgcn_s_setprio(0); } while (0)
; #define PG8_WAIT_V(n) asm volatile("s_waitcnt vmcnt(" #n ")" ::: "memory")
; #define PG8_WAIT_L(n) asm volatile("s_waitcnt lgkmcnt(" #n ")" ::: "memory")
; #define PG8_BAR __builtin_amdgcn_s_barrier()
; #define PG8_SCHED __builtin_amdgcn_sched_barrier(0)
; template <class Epi>
; __device__ __forceinline__ void gemm_phase(LAS unsigned char* lds, const Gemm g, const StaticOrder& S, const Epi& E) {
;     ...
;             PG8_WAIT_V(8); PG8_WAIT_L(0); PG8_BAR; PG8_MMA(1, 0, At, B0); PG8_MMA(1, 1, At, B1); PG8_BAR; PG8_SCHED;
;             PG8_LDB(B0, 1, 0); PG8_LDB(B1, 1, 1); PG8_SCHED; PG8_LDA(At, 1, 0); PG8_STAGE(PG8_SA(0, 1), a2 + hstepA, voffA);
;             PG8_WAIT_V(8); PG8_WAIT_L(0); PG8_BAR; PG8_MMA(0, 0, At, B0); PG8_MMA(0, 1, At, B1); PG8_BAR; PG8_SCHED;
	s_setprio 1
	s_waitcnt lgkmcnt(0)
	v_mfma_f32_16x16x32_bf16 v[96:99], v[142:145], v[180:183], v[96:99]
	v_mfma_f32_16x16x32_bf16 v[92:95], v[156:159], v[180:183], v[92:95]
	v_mfma_f32_16x16x32_bf16 v[88:91], v[142:145], v[188:191], v[88:91]
	v_mfma_f32_16x16x32_bf16 v[84:87], v[156:159], v[188:191], v[84:87]
	v_mfma_f32_16x16x32_bf16 v[80:83], v[142:145], v[210:213], v[80:83]
	v_mfma_f32_16x16x32_bf16 v[76:79], v[156:159], v[210:213], v[76:79]
	v_mfma_f32_16x16x32_bf16 v[72:75], v[142:145], v[218:221], v[72:75]
	v_mfma_f32_16x16x32_bf16 v[68:71], v[156:159], v[218:221], v[68:71]
	v_mfma_f32_16x16x32_bf16 v[96:99], v[146:149], v[184:187], v[96:99]
	v_mfma_f32_16x16x32_bf16 v[92:95], v[160:163], v[184:187], v[92:95]
	v_mfma_f32_16x16x32_bf16 v[88:91], v[146:149], v[192:195], v[88:91]
	v_mfma_f32_16x16x32_bf16 v[84:87], v[160:163], v[192:195], v[84:87]
	v_mfma_f32_16x16x32_bf16 v[80:83], v[146:149], v[214:217], v[80:83]
	v_mfma_f32_16x16x32_bf16 v[76:79], v[160:163], v[214:217], v[76:79]
	v_mfma_f32_16x16x32_bf16 v[72:75], v[146:149], v[222:225], v[72:75]
	v_mfma_f32_16x16x32_bf16 v[68:71], v[160:163], v[222:225], v[68:71]
	s_setprio 0
	s_setprio 1
	v_mfma_f32_16x16x32_bf16 v[32:35], v[164:167], v[180:183], v[32:35]
	v_mfma_f32_16x16x32_bf16 v[28:31], v[172:175], v[180:183], v[28:31]
	v_mfma_f32_16x16x32_bf16 v[24:27], v[164:167], v[188:191], v[24:27]
	v_mfma_f32_16x16x32_bf16 v[20:23], v[172:175], v[188:191], v[20:23]
	v_mfma_f32_16x16x32_bf16 v[16:19], v[164:167], v[210:213], v[16:19]
	v_mfma_f32_16x16x32_bf16 v[12:15], v[172:175], v[210:213], v[12:15]
	v_mfma_f32_16x16x32_bf16 v[8:11], v[164:167], v[218:221], v[8:11]
	v_mfma_f32_16x16x32_bf16 v[4:7], v[172:175], v[218:221], v[4:7]
	v_mfma_f32_16x16x32_bf16 v[32:35], v[168:171], v[184:187], v[32:35]
	v_mfma_f32_16x16x32_bf16 v[28:31], v[176:179], v[184:187], v[28:31]
	v_mfma_f32_16x16x32_bf16 v[24:27], v[168:171], v[192:195], v[24:27]
	v_mfma_f32_16x16x32_bf16 v[20:23], v[176:179], v[192:195], v[20:23]
	v_mfma_f32_16x16x32_bf16 v[16:19], v[168:171], v[214:217], v[16:19]
	v_mfma_f32_16x16x32_bf16 v[12:15], v[176:179], v[214:217], v[12:15]
	v_mfma_f32_16x16x32_bf16 v[8:11], v[168:171], v[222:225], v[8:11]
	v_mfma_f32_16x16x32_bf16 v[4:7], v[176:179], v[222:225], v[4:7]
	s_setprio 0
	s_barrier
	s_add_i32 s66, 0, 0x18000
	v_add_u32_e32 v155, s66, v152
	s_add_i32 s67, 0, 0x1c000
	ds_read_b128 v[142:145], v155
	ds_read_b128 v[146:149], v155 offset:1024
	ds_read_b128 v[156:159], v155 offset:2048
	ds_read_b128 v[160:163], v155 offset:3072
	v_add_u32_e32 v155, s67, v152
	ds_read_b128 v[164:167], v155
	ds_read_b128 v[168:171], v155 offset:1024
	ds_read_b128 v[172:175], v155 offset:2048
	ds_read_b128 v[176:179], v155 offset:3072
	s_add_u32 s46, s46, 0x40000
	s_addc_u32 s47, s47, 0
	s_mov_b32 m0, s54
	v_lshl_add_u64 v[228:229], s[46:47], 0, v[136:137]
	ds_read_b128 v[180:183], v154 offset:32768
	ds_read_b128 v[184:187], v154 offset:33792
	ds_read_b128 v[188:191], v154 offset:34816
	ds_read_b128 v[192:195], v154 offset:35840
	ds_read_b128 v[210:213], v154 offset:36864
	ds_read_b128 v[214:217], v154 offset:37888
	ds_read_b128 v[218:221], v154 offset:38912
	ds_read_b128 v[222:225], v154 offset:39936
	global_load_lds_dwordx4 v[228:229], off
	v_lshl_add_u64 v[228:229], s[46:47], 0, v[132:133]
	s_mov_b32 m0, s55
	s_nop 0
	global_load_lds_dwordx4 v[228:229], off
	s_waitcnt vmcnt(8)
	s_waitcnt lgkmcnt(0)
	s_barrier
	s_setprio 1
	s_waitcnt lgkmcnt(0)
	v_mfma_f32_16x16x32_bf16 v[128:131], v[142:145], v[180:183], v[128:131]
	v_mfma_f32_16x16x32_bf16 v[124:127], v[156:159], v[180:183], v[124:127]
	v_mfma_f32_16x16x32_bf16 v[120:123], v[142:145], v[188:191], v[120:123]
	v_mfma_f32_16x16x32_bf16 v[116:119], v[156:159], v[188:191], v[116:119]
	v_mfma_f32_16x16x32_bf16 v[112:115], v[142:145], v[210:213], v[112:115]
	v_mfma_f32_16x16x32_bf16 v[108:111], v[156:159], v[210:213], v[108:111]
	v_mfma_f32_16x16x32_bf16 v[104:107], v[142:145], v[218:221], v[104:107]
	v_mfma_f32_16x16x32_bf16 v[100:103], v[156:159], v[218:221], v[100:103]
	v_mfma_f32_16x16x32_bf16 v[128:131], v[146:149], v[184:187], v[128:131]
	v_mfma_f32_16x16x32_bf16 v[124:127], v[160:163], v[184:187], v[124:127]
	v_mfma_f32_16x16x32_bf16 v[120:123], v[146:149], v[192:195], v[120:123]
	v_mfma_f32_16x16x32_bf16 v[116:119], v[160:163], v[192:195], v[116:119]
	v_mfma_f32_16x16x32_bf16 v[112:115], v[146:149], v[214:217], v[112:115]
	v_mfma_f32_16x16x32_bf16 v[108:111], v[160:163], v[214:217], v[108:111]
	v_mfma_f32_16x16x32_bf16 v[104:107], v[146:149], v[222:225], v[104:107]
	v_mfma_f32_16x16x32_bf16 v[100:103], v[160:163], v[222:225], v[100:103]
	s_setprio 0
	s_setprio 1
	v_mfma_f32_16x16x32_bf16 v[64:67], v[164:167], v[180:183], v[64:67]
	v_mfma_f32_16x16x32_bf16 v[60:63], v[172:175], v[180:183], v[60:63]
	v_mfma_f32_16x16x32_bf16 v[56:59], v[164:167], v[188:191], v[56:59]
	v_mfma_f32_16x16x32_bf16 v[52:55], v[172:175], v[188:191], v[52:55]
	v_mfma_f32_16x16x32_bf16 v[48:51], v[164:167], v[210:213], v[48:51]
	v_mfma_f32_16x16x32_bf16 v[44:47], v[172:175], v[210:213], v[44:47]
	v_mfma_f32_16x16x32_bf16 v[40:43], v[164:167], v[218:221], v[40:43]
	v_mfma_f32_16x16x32_bf16 v[36:39], v[172:175], v[218:221], v[36:39]
	v_mfma_f32_16x16x32_bf16 v[64:67], v[168:171], v[184:187], v[64:67]
	v_mfma_f32_16x16x32_bf16 v[60:63], v[176:179], v[184:187], v[60:63]
	v_mfma_f32_16x16x32_bf16 v[56:59], v[168:171], v[192:195], v[56:59]
	v_mfma_f32_16x16x32_bf16 v[52:55], v[176:179], v[192:195], v[52:55]
	v_mfma_f32_16x16x32_bf16 v[48:51], v[168:171], v[214:217], v[48:51]
	v_mfma_f32_16x16x32_bf16 v[44:47], v[176:179], v[214:217], v[44:47]
	v_mfma_f32_16x16x32_bf16 v[40:43], v[168:171], v[222:225], v[40:43]
	v_mfma_f32_16x16x32_bf16 v[36:39], v[176:179], v[222:225], v[36:39]
	s_setprio 0
	s_barrier
; #define PG8_STAGE(bufoff, gbase, voff) do { _Pragma("unroll") for (int _i = 0; _i < 2; ++_i) \
;         __builtin_amdgcn_global_load_lds((const unsigned*)((const char*)(gbase) + (voff)[_i]), (LAS unsigned*)(lds + (bufoff) + ldsw + _i * 8192), 16, 0, 0); } while (0)
; #define PG8_LDA(dst, b, h) do { _Pragma("unroll") for (int m = 0; m < 4; ++m) _Pragma("unroll") for (int k = 0; k < 2; ++k) dst[m][k] = *(const LAS bf16x8*)(lds + PG8_SA(b, h) + aoff + m * 2048 + k * 1024); } while (0)
; #define PG8_MMA(ai, bj, At, Bt) do { __builtin_amdgcn_s_setprio(1); _Pragma("unroll") for (int m = 0; m < 4; ++m) _Pragma("unroll") for (int n = 0; n < 2; ++n) _Pragma("unroll") for (int k = 0; k < 2; ++k) \
;         acc[ai][bj][m][n] = __builtin_amdgcn_mfma_f32_16x16x32_bf16(Bt[n][k], At[m][k], acc[ai][bj][m][n], 0, 0, 0); __builtin_amdgcn_s_setprio(0); } while (0)
; #define PG8_WAIT_V(n) asm volatile("s_waitcnt vmcnt(" #n ")" ::: "memory")
; #define PG8_WAIT_L(n) asm volatile("s_waitcnt lgkmcnt(" #n ")" ::: "memory")
; #define PG8_BAR __builtin_amdgcn_s_barrier()
; #define PG8_SCHED __builtin_amdgcn_sched_barrier(0)
; template <class Epi>
; __device__ __forceinline__ void gemm_phase(LAS unsigned char* lds, const Gemm g, const StaticOrder& S, const Epi& E) {
;     ...
;             PG8_LDA(At, 1, 1); PG8_STAGE(PG8_SB(1, 0), b3, voffB); PG8_STAGE(PG8_SB(1, 1), b3 + hstepB, voffB); PG8_STAGE(PG8_SA(1, 0), a3, voffA);
;             PG8_WAIT_V(8); PG8_WAIT_L(0); PG8_BAR; PG8_MMA(1, 0, At, B0); PG8_MMA(1, 1, At, B1); PG8_BAR; PG8_SCHED;
;         }
;         if (wr == 0) PG8_BAR;
	s_add_i32 s46, s66, s51
	v_lshl_add_u64 v[150:151], v[150:151], 0, s[30:31]
	s_mov_b32 m0, s46
	ds_read_b128 v[180:183], v154 offset:49152
	ds_read_b128 v[184:187], v154 offset:50176
	ds_read_b128 v[188:191], v154 offset:51200
	ds_read_b128 v[192:195], v154 offset:52224
	ds_read_b128 v[210:213], v154 offset:53248
	ds_read_b128 v[214:217], v154 offset:54272
	ds_read_b128 v[218:221], v154 offset:55296
	ds_read_b128 v[222:225], v154 offset:56320
	global_load_lds_dwordx4 v[150:151], off
	s_add_i32 m0, s46, 0x2000
	s_add_u32 s22, s22, 0x10080
	v_lshl_add_u64 v[150:151], v[196:197], 0, s[30:31]
	s_addc_u32 s23, s23, 0
	s_add_i32 s46, s67, s51
	global_load_lds_dwordx4 v[150:151], off
	v_lshl_add_u64 v[150:151], s[22:23], 0, v[134:135]
	s_mov_b32 m0, s46
	s_nop 0
	global_load_lds_dwordx4 v[150:151], off
	v_lshl_add_u64 v[150:151], s[22:23], 0, v[0:1]
	s_add_i32 m0, s46, 0x2000
	s_nop 0
	global_load_lds_dwordx4 v[150:151], off
	v_lshl_add_u64 v[150:151], v[198:199], 0, s[30:31]
	s_mov_b32 m0, s56
	s_nop 0
	global_load_lds_dwordx4 v[150:151], off
	v_lshl_add_u64 v[150:151], v[226:227], 0, s[30:31]
	s_mov_b32 m0, s57
	s_nop 0
	global_load_lds_dwordx4 v[150:151], off
	s_waitcnt vmcnt(8)
	s_waitcnt lgkmcnt(0)
	s_barrier
	s_setprio 1
	s_waitcnt lgkmcnt(0)
	v_mfma_f32_16x16x32_bf16 v[96:99], v[142:145], v[180:183], v[96:99]
	v_mfma_f32_16x16x32_bf16 v[92:95], v[156:159], v[180:183], v[92:95]
	v_mfma_f32_16x16x32_bf16 v[88:91], v[142:145], v[188:191], v[88:91]
	v_mfma_f32_16x16x32_bf16 v[84:87], v[156:159], v[188:191], v[84:87]
	v_mfma_f32_16x16x32_bf16 v[80:83], v[142:145], v[210:213], v[80:83]
	v_mfma_f32_16x16x32_bf16 v[76:79], v[156:159], v[210:213], v[76:79]
	v_mfma_f32_16x16x32_bf16 v[72:75], v[142:145], v[218:221], v[72:75]
	v_mfma_f32_16x16x32_bf16 v[68:71], v[156:159], v[218:221], v[68:71]
	v_mfma_f32_16x16x32_bf16 v[96:99], v[146:149], v[184:187], v[96:99]
	v_mfma_f32_16x16x32_bf16 v[92:95], v[160:163], v[184:187], v[92:95]
	v_mfma_f32_16x16x32_bf16 v[88:91], v[146:149], v[192:195], v[88:91]
	v_mfma_f32_16x16x32_bf16 v[84:87], v[160:163], v[192:195], v[84:87]
	v_mfma_f32_16x16x32_bf16 v[80:83], v[146:149], v[214:217], v[80:83]
	v_mfma_f32_16x16x32_bf16 v[76:79], v[160:163], v[214:217], v[76:79]
	v_mfma_f32_16x16x32_bf16 v[72:75], v[146:149], v[222:225], v[72:75]
	v_mfma_f32_16x16x32_bf16 v[68:71], v[160:163], v[222:225], v[68:71]
	s_setprio 0
	s_setprio 1
	v_mfma_f32_16x16x32_bf16 v[32:35], v[164:167], v[180:183], v[32:35]
	v_mfma_f32_16x16x32_bf16 v[28:31], v[172:175], v[180:183], v[28:31]
	v_mfma_f32_16x16x32_bf16 v[24:27], v[164:167], v[188:191], v[24:27]
	v_mfma_f32_16x16x32_bf16 v[20:23], v[172:175], v[188:191], v[20:23]
	v_mfma_f32_16x16x32_bf16 v[16:19], v[164:167], v[210:213], v[16:19]
	v_mfma_f32_16x16x32_bf16 v[12:15], v[172:175], v[210:213], v[12:15]
	v_mfma_f32_16x16x32_bf16 v[8:11], v[164:167], v[218:221], v[8:11]
	v_mfma_f32_16x16x32_bf16 v[4:7], v[172:175], v[218:221], v[4:7]
	v_mfma_f32_16x16x32_bf16 v[32:35], v[168:171], v[184:187], v[32:35]
	v_mfma_f32_16x16x32_bf16 v[28:31], v[176:179], v[184:187], v[28:31]
	v_mfma_f32_16x16x32_bf16 v[24:27], v[168:171], v[192:195], v[24:27]
	v_mfma_f32_16x16x32_bf16 v[20:23], v[176:179], v[192:195], v[20:23]
	v_mfma_f32_16x16x32_bf16 v[16:19], v[168:171], v[214:217], v[16:19]
	v_mfma_f32_16x16x32_bf16 v[12:15], v[176:179], v[214:217], v[12:15]
	v_mfma_f32_16x16x32_bf16 v[8:11], v[168:171], v[222:225], v[8:11]
	v_mfma_f32_16x16x32_bf16 v[4:7], v[176:179], v[222:225], v[4:7]
	s_add_i32 s65, s65, 2
	s_add_u32 s44, s44, 0x100
	s_addc_u32 s45, s45, 0
	s_add_u32 s63, s63, 0x100
	s_addc_u32 s64, s64, 0
	s_cmp_gt_u32 s65, 13
	s_setprio 0
	s_barrier
	s_cbranch_scc0 .LBB0_551
	v_readlane_b32 s64, v252, 28
	s_and_b64 vcc, exec, s[12:13]
	v_readlane_b32 s65, v252, 29
	s_cbranch_vccz .LBB0_554
	s_barrier

; #define PG8_STAGE(bufoff, gbase, voff) do { _Pragma("unroll") for (int _i = 0; _i < 2; ++_i) \
;         __builtin_amdgcn_global_load_lds((const unsigned*)((const char*)(gbase) + (voff)[_i]), (LAS unsigned*)(lds + (bufoff) + ldsw + _i * 8192), 16, 0, 0); } while (0)
; #define PG8_LDA(dst, b, h) do { _Pragma("unroll") for (int m = 0; m < 4; ++m) _Pragma("unroll") for (int k = 0; k < 2; ++k) dst[m][k] = *(const LAS bf16x8*)(lds + PG8_SA(b, h) + aoff + m * 2048 + k * 1024); } while (0)
; #define PG8_LDB(dst, b, h) do { _Pragma("unroll") for (int n = 0; n < 2; ++n) _Pragma("unroll") for (int k = 0; k < 2; ++k) dst[n][k] = *(const LAS bf16x8*)(lds + PG8_SB(b, h) + boff + n * 2048 + k * 1024); } while (0)
; #define PG8_MMA(ai, bj, At, Bt) do { __builtin_amdgcn_s_setprio(1); _Pragma("unroll") for (int m = 0; m < 4; ++m) _Pragma("unroll") for (int n = 0; n < 2; ++n) _Pragma("unroll") for (int k = 0; k < 2; ++k) \
;         acc[ai][bj][m][n] = __builtin_amdgcn_mfma_f32_16x16x32_bf16(Bt[n][k], At[m][k], acc[ai][bj][m][n], 0, 0, 0); __builtin_amdgcn_s_setprio(0); } while (0)
; #define PG8_WAIT_V(n) asm volatile("s_waitcnt vmcnt(" #n ")" ::: "memory")
; #define PG8_WAIT_L(n) asm volatile("s_waitcnt lgkmcnt(" #n ")" ::: "memory")
; #define PG8_BAR __builtin_amdgcn_s_barrier()
; #define PG8_SCHED __builtin_amdgcn_sched_barrier(0)
; template <class Epi>
; __device__ __forceinline__ void gemm_phase(LAS unsigned char* lds, const Gemm g, const StaticOrder& S, const Epi& E) {
;     ...
;         for (int t = 0; t < nt; t += 2) {
;             const bool last = (t == nt - 2);
;             const char* a1 = cA + (size_t)(t + 1) * kstep;
;             const char* a2 = last ? nA : cA + (size_t)(t + 2) * kstep; const char* b2 = last ? nB : cB + (size_t)(t + 2) * kstep;
;             const char* a3 = a2 + kstep; const char* b3 = b2 + kstep;
;             PG8_LDB(B0, 0, 0); PG8_LDB(B1, 0, 1); PG8_SCHED; PG8_LDA(At, 0, 0); PG8_STAGE(PG8_SA(1, 1), a1 + hstepA, voffA);
;             PG8_WAIT_V(8); PG8_WAIT_L(0); PG8_BAR; PG8_MMA(0, 0, At, B0); PG8_MMA(0, 1, At, B1); PG8_BAR; PG8_SCHED;
;             PG8_LDA(At, 0, 1); PG8_STAGE(PG8_SB(0, 0), b2, voffB); PG8_STAGE(PG8_SB(0, 1), b2 + hstepB, voffB); PG8_STAGE(PG8_SA(0, 0), a2, voffA);
;             PG8_WAIT_V(8); PG8_WAIT_L(0); PG8_BAR; PG8_MMA(1, 0, At, B0); PG8_MMA(1, 1, At, B1); PG8_BAR; PG8_SCHED;
.LBB0_880:
	s_add_u32 s22, s48, 0xfffc0080
	s_addc_u32 s23, s49, -1
	s_add_i32 s72, 0, 0x10000
	s_cmp_eq_u32 s71, 12
	s_cselect_b32 s51, s39, s23
	s_cselect_b32 s50, s67, s22
	v_add_u32_e32 v150, s72, v152
	s_cselect_b32 s23, s35, s70
	s_cselect_b32 s22, s68, s69
	s_add_i32 s74, 0, 0x14000
	ds_read_b128 v[142:145], v150
	ds_read_b128 v[146:149], v150 offset:1024
	ds_read_b128 v[156:159], v150 offset:2048
	ds_read_b128 v[160:163], v150 offset:3072
	v_add_u32_e32 v150, s74, v152
	ds_read_b128 v[164:167], v150
	ds_read_b128 v[168:171], v150 offset:1024
	ds_read_b128 v[172:175], v150 offset:2048
	ds_read_b128 v[176:179], v150 offset:3072
	v_lshl_add_u64 v[150:151], s[48:49], 0, v[138:139]
	s_add_i32 m0, s58, 0xc000
	ds_read_b128 v[180:183], v154
	ds_read_b128 v[184:187], v154 offset:1024
	ds_read_b128 v[188:191], v154 offset:2048
	ds_read_b128 v[192:195], v154 offset:3072
	ds_read_b128 v[210:213], v154 offset:4096
	ds_read_b128 v[214:217], v154 offset:5120
	ds_read_b128 v[218:221], v154 offset:6144
	ds_read_b128 v[222:225], v154 offset:7168
	global_load_lds_dwordx4 v[150:151], off
	v_lshl_add_u64 v[150:151], s[48:49], 0, v[140:141]
	s_add_i32 m0, s58, 0xe000
	s_nop 0
	global_load_lds_dwordx4 v[150:151], off
	s_waitcnt vmcnt(8)
	s_waitcnt lgkmcnt(0)
	s_barrier
	s_setprio 1
	s_waitcnt lgkmcnt(0)
	v_mfma_f32_16x16x32_bf16 v[128:131], v[142:145], v[180:183], v[128:131]
	v_mfma_f32_16x16x32_bf16 v[124:127], v[156:159], v[180:183], v[124:127]
	v_mfma_f32_16x16x32_bf16 v[112:115], v[142:145], v[188:191], v[112:115]
	v_mfma_f32_16x16x32_bf16 v[108:111], v[156:159], v[188:191], v[108:111]
	v_mfma_f32_16x16x32_bf16 v[96:99], v[142:145], v[210:213], v[96:99]
	v_mfma_f32_16x16x32_bf16 v[92:95], v[156:159], v[210:213], v[92:95]
	v_mfma_f32_16x16x32_bf16 v[80:83], v[142:145], v[218:221], v[80:83]
	v_mfma_f32_16x16x32_bf16 v[76:79], v[156:159], v[218:221], v[76:79]
	v_mfma_f32_16x16x32_bf16 v[128:131], v[146:149], v[184:187], v[128:131]
	v_mfma_f32_16x16x32_bf16 v[124:127], v[160:163], v[184:187], v[124:127]
	v_mfma_f32_16x16x32_bf16 v[112:115], v[146:149], v[192:195], v[112:115]
	v_mfma_f32_16x16x32_bf16 v[108:111], v[160:163], v[192:195], v[108:111]
	v_mfma_f32_16x16x32_bf16 v[96:99], v[146:149], v[214:217], v[96:99]
	v_mfma_f32_16x16x32_bf16 v[92:95], v[160:163], v[214:217], v[92:95]
	v_mfma_f32_16x16x32_bf16 v[80:83], v[146:149], v[222:225], v[80:83]
	v_mfma_f32_16x16x32_bf16 v[76:79], v[160:163], v[222:225], v[76:79]
	s_setprio 0
	s_setprio 1
	v_mfma_f32_16x16x32_bf16 v[120:123], v[164:167], v[180:183], v[120:123]
	v_mfma_f32_16x16x32_bf16 v[116:119], v[172:175], v[180:183], v[116:119]
	v_mfma_f32_16x16x32_bf16 v[104:107], v[164:167], v[188:191], v[104:107]
	v_mfma_f32_16x16x32_bf16 v[100:103], v[172:175], v[188:191], v[100:103]
	v_mfma_f32_16x16x32_bf16 v[88:91], v[164:167], v[210:213], v[88:91]
	v_mfma_f32_16x16x32_bf16 v[84:87], v[172:175], v[210:213], v[84:87]
	v_mfma_f32_16x16x32_bf16 v[72:75], v[164:167], v[218:221], v[72:75]
	v_mfma_f32_16x16x32_bf16 v[68:71], v[172:175], v[218:221], v[68:71]
	v_mfma_f32_16x16x32_bf16 v[120:123], v[168:171], v[184:187], v[120:123]
	v_mfma_f32_16x16x32_bf16 v[116:119], v[176:179], v[184:187], v[116:119]
	v_mfma_f32_16x16x32_bf16 v[104:107], v[168:171], v[192:195], v[104:107]
	v_mfma_f32_16x16x32_bf16 v[100:103], v[176:179], v[192:195], v[100:103]
	v_mfma_f32_16x16x32_bf16 v[88:91], v[168:171], v[214:217], v[88:91]
	v_mfma_f32_16x16x32_bf16 v[84:87], v[176:179], v[214:217], v[84:87]
	v_mfma_f32_16x16x32_bf16 v[72:75], v[168:171], v[222:225], v[72:75]
	v_mfma_f32_16x16x32_bf16 v[68:71], v[176:179], v[222:225], v[68:71]
	s_setprio 0
	s_barrier
	s_add_i32 s72, s72, s57
	v_lshl_add_u64 v[150:151], s[22:23], 0, v[134:135]
	s_mov_b32 m0, s72
	ds_read_b128 v[180:183], v154 offset:16384
	ds_read_b128 v[184:187], v154 offset:17408
	ds_read_b128 v[188:191], v154 offset:18432
	ds_read_b128 v[192:195], v154 offset:19456
	ds_read_b128 v[210:213], v154 offset:20480
	ds_read_b128 v[214:217], v154 offset:21504
	ds_read_b128 v[218:221], v154 offset:22528
	ds_read_b128 v[222:225], v154 offset:23552
	global_load_lds_dwordx4 v[150:151], off
	s_add_i32 m0, s72, 0x2000
	s_add_u32 s72, s22, 0x10000
	v_lshl_add_u64 v[196:197], s[22:23], 0, v[0:1]
	s_addc_u32 s73, s23, 0
	s_add_i32 s74, s74, s57
	global_load_lds_dwordx4 v[196:197], off
	v_lshl_add_u64 v[198:199], s[72:73], 0, v[134:135]
	s_mov_b32 m0, s74
	v_lshl_add_u64 v[226:227], s[50:51], 0, v[132:133]
	global_load_lds_dwordx4 v[198:199], off
	v_lshl_add_u64 v[198:199], s[72:73], 0, v[0:1]
	s_add_i32 m0, s74, 0x2000
	s_nop 0
	global_load_lds_dwordx4 v[198:199], off
	v_lshl_add_u64 v[198:199], s[50:51], 0, v[136:137]
	s_mov_b32 m0, s58
	s_nop 0
	global_load_lds_dwordx4 v[198:199], off
	s_mov_b32 m0, s59
	s_nop 0
	global_load_lds_dwordx4 v[226:227], off
	s_waitcnt vmcnt(8)
	s_waitcnt lgkmcnt(0)
	s_barrier
; #define PG8_STAGE(bufoff, gbase, voff) do { _Pragma("unroll") for (int _i = 0; _i < 2; ++_i) \
;         __builtin_amdgcn_global_load_lds((const unsigned*)((const char*)(gbase) + (voff)[_i]), (LAS unsigned*)(lds + (bufoff) + ldsw + _i * 8192), 16, 0, 0); } while (0)
; #define PG8_LDA(dst, b, h) do { _Pragma("unroll") for (int m = 0; m < 4; ++m) _Pragma("unroll") for (int k = 0; k < 2; ++k) dst[m][k] = *(const LAS bf16x8*)(lds + PG8_SA(b, h) + aoff + m * 2048 + k * 1024); } while (0)
; #define PG8_LDB(dst, b, h) do { _Pragma("unroll") for (int n = 0; n < 2; ++n) _Pragma("unroll") for (int k = 0; k < 2; ++k) dst[n][k] = *(const LAS bf16x8*)(lds + PG8_SB(b, h) + boff + n * 2048 + k * 1024); } while (0)
; #define PG8_MMA(ai, bj, At, Bt) do { __builtin_amdgcn_s_setprio(1); _Pragma("unroll") for (int m = 0; m < 4; ++m) _Pragma("unroll") for (int n = 0; n < 2; ++n) _Pragma("unroll") for (int k = 0; k < 2; ++k) \
;         acc[ai][bj][m][n] = __builtin_amdgcn_mfma_f32_16x16x32_bf16(Bt[n][k], At[m][k], acc[ai][bj][m][n], 0, 0, 0); __builtin_amdgcn_s_setprio(0); } while (0)
; #define PG8_WAIT_V(n) asm volatile("s_waitcnt vmcnt(" #n ")" ::: "memory")
; #define PG8_WAIT_L(n) asm volatile("s_waitcnt lgkmcnt(" #n ")" ::: "memory")
; #define PG8_BAR __builtin_amdgcn_s_barrier()
; #define PG8_SCHED __builtin_amdgcn_sched_barrier(0)
; template <class Epi>
; __device__ __forceinline__ void gemm_phase(LAS unsigned char* lds, const Gemm g, const StaticOrder& S, const Epi& E) {
;     ...
;             PG8_WAIT_V(8); PG8_WAIT_L(0); PG8_BAR; PG8_MMA(1, 0, At, B0); PG8_MMA(1, 1, At, B1); PG8_BAR; PG8_SCHED;
;             PG8_LDB(B0, 1, 0); PG8_LDB(B1, 1, 1); PG8_SCHED; PG8_LDA(At, 1, 0); PG8_STAGE(PG8_SA(0, 1), a2 + hstepA, voffA);
;             PG8_WAIT_V(8); PG8_WAIT_L(0); PG8_BAR; PG8_MMA(0, 0, At, B0); PG8_MMA(0, 1, At, B1); PG8_BAR; PG8_SCHED;
	s_setprio 1
	s_waitcnt lgkmcnt(0)
	v_mfma_f32_16x16x32_bf16 v[64:67], v[142:145], v[180:183], v[64:67]
	v_mfma_f32_16x16x32_bf16 v[60:63], v[156:159], v[180:183], v[60:63]
	v_mfma_f32_16x16x32_bf16 v[48:51], v[142:145], v[188:191], v[48:51]
	v_mfma_f32_16x16x32_bf16 v[44:47], v[156:159], v[188:191], v[44:47]
	v_mfma_f32_16x16x32_bf16 v[32:35], v[142:145], v[210:213], v[32:35]
	v_mfma_f32_16x16x32_bf16 v[28:31], v[156:159], v[210:213], v[28:31]
	v_mfma_f32_16x16x32_bf16 v[16:19], v[142:145], v[218:221], v[16:19]
	v_mfma_f32_16x16x32_bf16 v[12:15], v[156:159], v[218:221], v[12:15]
	v_mfma_f32_16x16x32_bf16 v[64:67], v[146:149], v[184:187], v[64:67]
	v_mfma_f32_16x16x32_bf16 v[60:63], v[160:163], v[184:187], v[60:63]
	v_mfma_f32_16x16x32_bf16 v[48:51], v[146:149], v[192:195], v[48:51]
	v_mfma_f32_16x16x32_bf16 v[44:47], v[160:163], v[192:195], v[44:47]
	v_mfma_f32_16x16x32_bf16 v[32:35], v[146:149], v[214:217], v[32:35]
	v_mfma_f32_16x16x32_bf16 v[28:31], v[160:163], v[214:217], v[28:31]
	v_mfma_f32_16x16x32_bf16 v[16:19], v[146:149], v[222:225], v[16:19]
	v_mfma_f32_16x16x32_bf16 v[12:15], v[160:163], v[222:225], v[12:15]
	s_setprio 0
	s_setprio 1
	v_mfma_f32_16x16x32_bf16 v[56:59], v[164:167], v[180:183], v[56:59]
	v_mfma_f32_16x16x32_bf16 v[52:55], v[172:175], v[180:183], v[52:55]
	v_mfma_f32_16x16x32_bf16 v[40:43], v[164:167], v[188:191], v[40:43]
	v_mfma_f32_16x16x32_bf16 v[36:39], v[172:175], v[188:191], v[36:39]
	v_mfma_f32_16x16x32_bf16 v[24:27], v[164:167], v[210:213], v[24:27]
	v_mfma_f32_16x16x32_bf16 v[20:23], v[172:175], v[210:213], v[20:23]
	v_mfma_f32_16x16x32_bf16 v[8:11], v[164:167], v[218:221], v[8:11]
	v_mfma_f32_16x16x32_bf16 v[4:7], v[172:175], v[218:221], v[4:7]
	v_mfma_f32_16x16x32_bf16 v[56:59], v[168:171], v[184:187], v[56:59]
	v_mfma_f32_16x16x32_bf16 v[52:55], v[176:179], v[184:187], v[52:55]
	v_mfma_f32_16x16x32_bf16 v[40:43], v[168:171], v[192:195], v[40:43]
	v_mfma_f32_16x16x32_bf16 v[36:39], v[176:179], v[192:195], v[36:39]
	v_mfma_f32_16x16x32_bf16 v[24:27], v[168:171], v[214:217], v[24:27]
	v_mfma_f32_16x16x32_bf16 v[20:23], v[176:179], v[214:217], v[20:23]
	v_mfma_f32_16x16x32_bf16 v[8:11], v[168:171], v[222:225], v[8:11]
	v_mfma_f32_16x16x32_bf16 v[4:7], v[176:179], v[222:225], v[4:7]
	s_setprio 0
	s_barrier
	s_add_i32 s72, 0, 0x18000
	v_add_u32_e32 v155, s72, v152
	s_add_i32 s73, 0, 0x1c000
	ds_read_b128 v[142:145], v155
	ds_read_b128 v[146:149], v155 offset:1024
	ds_read_b128 v[156:159], v155 offset:2048
	ds_read_b128 v[160:163], v155 offset:3072
	v_add_u32_e32 v155, s73, v152
	ds_read_b128 v[164:167], v155
	ds_read_b128 v[168:171], v155 offset:1024
	ds_read_b128 v[172:175], v155 offset:2048
	ds_read_b128 v[176:179], v155 offset:3072
	s_add_u32 s50, s50, 0x40000
	s_addc_u32 s51, s51, 0
	s_mov_b32 m0, s60
	v_lshl_add_u64 v[228:229], s[50:51], 0, v[136:137]
	ds_read_b128 v[180:183], v154 offset:32768
	ds_read_b128 v[184:187], v154 offset:33792
	ds_read_b128 v[188:191], v154 offset:34816
	ds_read_b128 v[192:195], v154 offset:35840
	ds_read_b128 v[210:213], v154 offset:36864
	ds_read_b128 v[214:217], v154 offset:37888
	ds_read_b128 v[218:221], v154 offset:38912
	ds_read_b128 v[222:225], v154 offset:39936
	global_load_lds_dwordx4 v[228:229], off
	v_lshl_add_u64 v[228:229], s[50:51], 0, v[132:133]
	s_mov_b32 m0, s61
	s_nop 0
	global_load_lds_dwordx4 v[228:229], off
	s_waitcnt vmcnt(8)
	s_waitcnt lgkmcnt(0)
	s_barrier
	s_setprio 1
	s_waitcnt lgkmcnt(0)
	v_mfma_f32_16x16x32_bf16 v[128:131], v[142:145], v[180:183], v[128:131]
	v_mfma_f32_16x16x32_bf16 v[124:127], v[156:159], v[180:183], v[124:127]
	v_mfma_f32_16x16x32_bf16 v[112:115], v[142:145], v[188:191], v[112:115]
	v_mfma_f32_16x16x32_bf16 v[108:111], v[156:159], v[188:191], v[108:111]
	v_mfma_f32_16x16x32_bf16 v[96:99], v[142:145], v[210:213], v[96:99]
	v_mfma_f32_16x16x32_bf16 v[92:95], v[156:159], v[210:213], v[92:95]
	v_mfma_f32_16x16x32_bf16 v[80:83], v[142:145], v[218:221], v[80:83]
	v_mfma_f32_16x16x32_bf16 v[76:79], v[156:159], v[218:221], v[76:79]
	v_mfma_f32_16x16x32_bf16 v[128:131], v[146:149], v[184:187], v[128:131]
	v_mfma_f32_16x16x32_bf16 v[124:127], v[160:163], v[184:187], v[124:127]
	v_mfma_f32_16x16x32_bf16 v[112:115], v[146:149], v[192:195], v[112:115]
	v_mfma_f32_16x16x32_bf16 v[108:111], v[160:163], v[192:195], v[108:111]
	v_mfma_f32_16x16x32_bf16 v[96:99], v[146:149], v[214:217], v[96:99]
	v_mfma_f32_16x16x32_bf16 v[92:95], v[160:163], v[214:217], v[92:95]
	v_mfma_f32_16x16x32_bf16 v[80:83], v[146:149], v[222:225], v[80:83]
	v_mfma_f32_16x16x32_bf16 v[76:79], v[160:163], v[222:225], v[76:79]
	s_setprio 0
	s_setprio 1
	v_mfma_f32_16x16x32_bf16 v[120:123], v[164:167], v[180:183], v[120:123]
	v_mfma_f32_16x16x32_bf16 v[116:119], v[172:175], v[180:183], v[116:119]
	v_mfma_f32_16x16x32_bf16 v[104:107], v[164:167], v[188:191], v[104:107]
	v_mfma_f32_16x16x32_bf16 v[100:103], v[172:175], v[188:191], v[100:103]
	v_mfma_f32_16x16x32_bf16 v[88:91], v[164:167], v[210:213], v[88:91]
	v_mfma_f32_16x16x32_bf16 v[84:87], v[172:175], v[210:213], v[84:87]
	v_mfma_f32_16x16x32_bf16 v[72:75], v[164:167], v[218:221], v[72:75]
	v_mfma_f32_16x16x32_bf16 v[68:71], v[172:175], v[218:221], v[68:71]
	v_mfma_f32_16x16x32_bf16 v[120:123], v[168:171], v[184:187], v[120:123]
	v_mfma_f32_16x16x32_bf16 v[116:119], v[176:179], v[184:187], v[116:119]
	v_mfma_f32_16x16x32_bf16 v[104:107], v[168:171], v[192:195], v[104:107]
	v_mfma_f32_16x16x32_bf16 v[100:103], v[176:179], v[192:195], v[100:103]
	v_mfma_f32_16x16x32_bf16 v[88:91], v[168:171], v[214:217], v[88:91]
	v_mfma_f32_16x16x32_bf16 v[84:87], v[176:179], v[214:217], v[84:87]
	v_mfma_f32_16x16x32_bf16 v[72:75], v[168:171], v[222:225], v[72:75]
	v_mfma_f32_16x16x32_bf16 v[68:71], v[176:179], v[222:225], v[68:71]
	s_setprio 0
	s_barrier
; #define PG8_STAGE(bufoff, gbase, voff) do { _Pragma("unroll") for (int _i = 0; _i < 2; ++_i) \
;         __builtin_amdgcn_global_load_lds((const unsigned*)((const char*)(gbase) + (voff)[_i]), (LAS unsigned*)(lds + (bufoff) + ldsw + _i * 8192), 16, 0, 0); } while (0)
; #define PG8_LDA(dst, b, h) do { _Pragma("unroll") for (int m = 0; m < 4; ++m) _Pragma("unroll") for (int k = 0; k < 2; ++k) dst[m][k] = *(const LAS bf16x8*)(lds + PG8_SA(b, h) + aoff + m * 2048 + k * 1024); } while (0)
; #define PG8_MMA(ai, bj, At, Bt) do { __builtin_amdgcn_s_setprio(1); _Pragma("unroll") for (int m = 0; m < 4; ++m) _Pragma("unroll") for (int n = 0; n < 2; ++n) _Pragma("unroll") for (int k = 0; k < 2; ++k) \
;         acc[ai][bj][m][n] = __builtin_amdgcn_mfma_f32_16x16x32_bf16(Bt[n][k], At[m][k], acc[ai][bj][m][n], 0, 0, 0); __builtin_amdgcn_s_setprio(0); } while (0)
; #define PG8_WAIT_V(n) asm volatile("s_waitcnt vmcnt(" #n ")" ::: "memory")
; #define PG8_WAIT_L(n) asm volatile("s_waitcnt lgkmcnt(" #n ")" ::: "memory")
; #define PG8_BAR __builtin_amdgcn_s_barrier()
; #define PG8_SCHED __builtin_amdgcn_sched_barrier(0)
; template <class Epi>
; __device__ __forceinline__ void gemm_phase(LAS unsigned char* lds, const Gemm g, const StaticOrder& S, const Epi& E) {
;     ...
;             PG8_LDA(At, 1, 1); PG8_STAGE(PG8_SB(1, 0), b3, voffB); PG8_STAGE(PG8_SB(1, 1), b3 + hstepB, voffB); PG8_STAGE(PG8_SA(1, 0), a3, voffA);
;             PG8_WAIT_V(8); PG8_WAIT_L(0); PG8_BAR; PG8_MMA(1, 0, At, B0); PG8_MMA(1, 1, At, B1); PG8_BAR; PG8_SCHED;
;         }
;         if (wr == 0) PG8_BAR;
	s_add_i32 s50, s72, s57
	v_lshl_add_u64 v[150:151], v[150:151], 0, s[30:31]
	s_mov_b32 m0, s50
	ds_read_b128 v[180:183], v154 offset:49152
	ds_read_b128 v[184:187], v154 offset:50176
	ds_read_b128 v[188:191], v154 offset:51200
	ds_read_b128 v[192:195], v154 offset:52224
	ds_read_b128 v[210:213], v154 offset:53248
	ds_read_b128 v[214:217], v154 offset:54272
	ds_read_b128 v[218:221], v154 offset:55296
	ds_read_b128 v[222:225], v154 offset:56320
	global_load_lds_dwordx4 v[150:151], off
	s_add_i32 m0, s50, 0x2000
	s_add_u32 s22, s22, 0x10080
	v_lshl_add_u64 v[150:151], v[196:197], 0, s[30:31]
	s_addc_u32 s23, s23, 0
	s_add_i32 s50, s73, s57
	global_load_lds_dwordx4 v[150:151], off
	v_lshl_add_u64 v[150:151], s[22:23], 0, v[134:135]
	s_mov_b32 m0, s50
	s_nop 0
	global_load_lds_dwordx4 v[150:151], off
	v_lshl_add_u64 v[150:151], s[22:23], 0, v[0:1]
	s_add_i32 m0, s50, 0x2000
	s_nop 0
	global_load_lds_dwordx4 v[150:151], off
	v_lshl_add_u64 v[150:151], v[198:199], 0, s[30:31]
	s_mov_b32 m0, s62
	s_nop 0
	global_load_lds_dwordx4 v[150:151], off
	v_lshl_add_u64 v[150:151], v[226:227], 0, s[30:31]
	s_mov_b32 m0, s63
	s_nop 0
	global_load_lds_dwordx4 v[150:151], off
	s_waitcnt vmcnt(8)
	s_waitcnt lgkmcnt(0)
	s_barrier
	s_setprio 1
	s_waitcnt lgkmcnt(0)
	v_mfma_f32_16x16x32_bf16 v[64:67], v[142:145], v[180:183], v[64:67]
	v_mfma_f32_16x16x32_bf16 v[60:63], v[156:159], v[180:183], v[60:63]
	v_mfma_f32_16x16x32_bf16 v[48:51], v[142:145], v[188:191], v[48:51]
	v_mfma_f32_16x16x32_bf16 v[44:47], v[156:159], v[188:191], v[44:47]
	v_mfma_f32_16x16x32_bf16 v[32:35], v[142:145], v[210:213], v[32:35]
	v_mfma_f32_16x16x32_bf16 v[28:31], v[156:159], v[210:213], v[28:31]
	v_mfma_f32_16x16x32_bf16 v[16:19], v[142:145], v[218:221], v[16:19]
	v_mfma_f32_16x16x32_bf16 v[12:15], v[156:159], v[218:221], v[12:15]
	v_mfma_f32_16x16x32_bf16 v[64:67], v[146:149], v[184:187], v[64:67]
	v_mfma_f32_16x16x32_bf16 v[60:63], v[160:163], v[184:187], v[60:63]
	v_mfma_f32_16x16x32_bf16 v[48:51], v[146:149], v[192:195], v[48:51]
	v_mfma_f32_16x16x32_bf16 v[44:47], v[160:163], v[192:195], v[44:47]
	v_mfma_f32_16x16x32_bf16 v[32:35], v[146:149], v[214:217], v[32:35]
	v_mfma_f32_16x16x32_bf16 v[28:31], v[160:163], v[214:217], v[28:31]
	v_mfma_f32_16x16x32_bf16 v[16:19], v[146:149], v[222:225], v[16:19]
	v_mfma_f32_16x16x32_bf16 v[12:15], v[160:163], v[222:225], v[12:15]
	s_setprio 0
	s_setprio 1
	v_mfma_f32_16x16x32_bf16 v[56:59], v[164:167], v[180:183], v[56:59]
	v_mfma_f32_16x16x32_bf16 v[52:55], v[172:175], v[180:183], v[52:55]
	v_mfma_f32_16x16x32_bf16 v[40:43], v[164:167], v[188:191], v[40:43]
	v_mfma_f32_16x16x32_bf16 v[36:39], v[172:175], v[188:191], v[36:39]
	v_mfma_f32_16x16x32_bf16 v[24:27], v[164:167], v[210:213], v[24:27]
	v_mfma_f32_16x16x32_bf16 v[20:23], v[172:175], v[210:213], v[20:23]
	v_mfma_f32_16x16x32_bf16 v[8:11], v[164:167], v[218:221], v[8:11]
	v_mfma_f32_16x16x32_bf16 v[4:7], v[172:175], v[218:221], v[4:7]
	v_mfma_f32_16x16x32_bf16 v[56:59], v[168:171], v[184:187], v[56:59]
	v_mfma_f32_16x16x32_bf16 v[52:55], v[176:179], v[184:187], v[52:55]
	v_mfma_f32_16x16x32_bf16 v[40:43], v[168:171], v[192:195], v[40:43]
	v_mfma_f32_16x16x32_bf16 v[36:39], v[176:179], v[192:195], v[36:39]
	v_mfma_f32_16x16x32_bf16 v[24:27], v[168:171], v[214:217], v[24:27]
	v_mfma_f32_16x16x32_bf16 v[20:23], v[176:179], v[214:217], v[20:23]
	v_mfma_f32_16x16x32_bf16 v[8:11], v[168:171], v[222:225], v[8:11]
	v_mfma_f32_16x16x32_bf16 v[4:7], v[176:179], v[222:225], v[4:7]
	s_add_i32 s71, s71, 2
	s_add_u32 s48, s48, 0x100
	s_addc_u32 s49, s49, 0
	s_add_u32 s69, s69, 0x100
	s_addc_u32 s70, s70, 0
	s_cmp_gt_u32 s71, 13
	s_setprio 0
	s_barrier
	s_cbranch_scc0 .LBB0_880
	s_and_b64 vcc, exec, s[14:15]
	s_cbranch_vccz .LBB0_883
	s_barrier

; #define PG8_STAGE(bufoff, gbase, voff) do { _Pragma("unroll") for (int _i = 0; _i < 2; ++_i) \
;         __builtin_amdgcn_global_load_lds((const unsigned*)((const char*)(gbase) + (voff)[_i]), (LAS unsigned*)(lds + (bufoff) + ldsw + _i * 8192), 16, 0, 0); } while (0)
; #define PG8_LDA(dst, b, h) do { _Pragma("unroll") for (int m = 0; m < 4; ++m) _Pragma("unroll") for (int k = 0; k < 2; ++k) dst[m][k] = *(const LAS bf16x8*)(lds + PG8_SA(b, h) + aoff + m * 2048 + k * 1024); } while (0)
; #define PG8_LDB(dst, b, h) do { _Pragma("unroll") for (int n = 0; n < 2; ++n) _Pragma("unroll") for (int k = 0; k < 2; ++k) dst[n][k] = *(const LAS bf16x8*)(lds + PG8_SB(b, h) + boff + n * 2048 + k * 1024); } while (0)
; #define PG8_MMA(ai, bj, At, Bt) do { __builtin_amdgcn_s_setprio(1); _Pragma("unroll") for (int m = 0; m < 4; ++m) _Pragma("unroll") for (int n = 0; n < 2; ++n) _Pragma("unroll") for (int k = 0; k < 2; ++k) \
;         acc[ai][bj][m][n] = __builtin_amdgcn_mfma_f32_16x16x32_bf16(Bt[n][k], At[m][k], acc[ai][bj][m][n], 0, 0, 0); __builtin_amdgcn_s_setprio(0); } while (0)
; #define PG8_WAIT_V(n) asm volatile("s_waitcnt vmcnt(" #n ")" ::: "memory")
; #define PG8_WAIT_L(n) asm volatile("s_waitcnt lgkmcnt(" #n ")" ::: "memory")
; #define PG8_BAR __builtin_amdgcn_s_barrier()
; #define PG8_SCHED __builtin_amdgcn_sched_barrier(0)
; template <class Epi>
; __device__ __forceinline__ void gemm_phase(LAS unsigned char* lds, const Gemm g, const StaticOrder& S, const Epi& E) {
;     ...
;         for (int t = 0; t < nt; t += 2) {
;             const bool last = (t == nt - 2);
;             const char* a1 = cA + (size_t)(t + 1) * kstep;
;             const char* a2 = last ? nA : cA + (size_t)(t + 2) * kstep; const char* b2 = last ? nB : cB + (size_t)(t + 2) * kstep;
;             const char* a3 = a2 + kstep; const char* b3 = b2 + kstep;
;             PG8_LDB(B0, 0, 0); PG8_LDB(B1, 0, 1); PG8_SCHED; PG8_LDA(At, 0, 0); PG8_STAGE(PG8_SA(1, 1), a1 + hstepA, voffA);
;             PG8_WAIT_V(8); PG8_WAIT_L(0); PG8_BAR; PG8_MMA(0, 0, At, B0); PG8_MMA(0, 1, At, B1); PG8_BAR; PG8_SCHED;
;             PG8_LDA(At, 0, 1); PG8_STAGE(PG8_SB(0, 0), b2, voffB); PG8_STAGE(PG8_SB(0, 1), b2 + hstepB, voffB); PG8_STAGE(PG8_SA(0, 0), a2, voffA);
;             PG8_WAIT_V(8); PG8_WAIT_L(0); PG8_BAR; PG8_MMA(1, 0, At, B0); PG8_MMA(1, 1, At, B1); PG8_BAR; PG8_SCHED;
.LBB0_902:
	s_add_u32 s22, s50, s4
	s_addc_u32 s23, s51, s5
	s_add_u32 s22, s22, 0x100
	s_addc_u32 s23, s23, 0
	s_add_u32 s73, s70, s4
	s_addc_u32 s74, s71, s5
	s_add_i32 s75, 0, 0x10000
	s_cmpk_eq_i32 s4, 0x300
	s_cselect_b32 s53, s47, s23
	s_cselect_b32 s52, s46, s22
	s_cselect_b32 s23, s41, s74
	s_cselect_b32 s22, s45, s73
	s_add_i32 s73, 0, 0x14000
	v_add_u32_e32 v148, s75, v242
	v_add_u32_e32 v164, s73, v242
	ds_read_b128 v[136:139], v148
	ds_read_b128 v[140:143], v148 offset:1024
	ds_read_b128 v[144:147], v148 offset:2048
	ds_read_b128 v[148:151], v148 offset:3072
	ds_read_b128 v[152:155], v164
	ds_read_b128 v[156:159], v164 offset:1024
	ds_read_b128 v[160:163], v164 offset:2048
	ds_read_b128 v[164:167], v164 offset:3072
	v_lshl_add_u64 v[196:197], v[134:135], 0, s[4:5]
	s_add_i32 m0, s61, 0xc000
	ds_read_b128 v[168:171], v244
	ds_read_b128 v[172:175], v244 offset:1024
	ds_read_b128 v[176:179], v244 offset:2048
	ds_read_b128 v[180:183], v244 offset:3072
	ds_read_b128 v[184:187], v244 offset:4096
	ds_read_b128 v[188:191], v244 offset:5120
	ds_read_b128 v[192:195], v244 offset:6144
	ds_read_b128 v[220:223], v244 offset:7168
	global_load_lds_dwordx4 v[196:197], off
	v_lshl_add_u64 v[196:197], v[132:133], 0, s[4:5]
	s_add_i32 m0, s61, 0xe000
	s_nop 0
	global_load_lds_dwordx4 v[196:197], off
	s_waitcnt vmcnt(8)
	s_waitcnt lgkmcnt(0)
	s_barrier
	s_setprio 1
	s_waitcnt lgkmcnt(0)
	v_mfma_f32_16x16x32_bf16 v[128:131], v[136:139], v[168:171], v[128:131]
	v_mfma_f32_16x16x32_bf16 v[124:127], v[144:147], v[168:171], v[124:127]
	v_mfma_f32_16x16x32_bf16 v[112:115], v[136:139], v[176:179], v[112:115]
	v_mfma_f32_16x16x32_bf16 v[108:111], v[144:147], v[176:179], v[108:111]
	v_mfma_f32_16x16x32_bf16 v[96:99], v[136:139], v[184:187], v[96:99]
	v_mfma_f32_16x16x32_bf16 v[92:95], v[144:147], v[184:187], v[92:95]
	v_mfma_f32_16x16x32_bf16 v[80:83], v[136:139], v[192:195], v[80:83]
	v_mfma_f32_16x16x32_bf16 v[76:79], v[144:147], v[192:195], v[76:79]
	v_mfma_f32_16x16x32_bf16 v[128:131], v[140:143], v[172:175], v[128:131]
	v_mfma_f32_16x16x32_bf16 v[124:127], v[148:151], v[172:175], v[124:127]
	v_mfma_f32_16x16x32_bf16 v[112:115], v[140:143], v[180:183], v[112:115]
	v_mfma_f32_16x16x32_bf16 v[108:111], v[148:151], v[180:183], v[108:111]
	v_mfma_f32_16x16x32_bf16 v[96:99], v[140:143], v[188:191], v[96:99]
	v_mfma_f32_16x16x32_bf16 v[92:95], v[148:151], v[188:191], v[92:95]
	v_mfma_f32_16x16x32_bf16 v[80:83], v[140:143], v[220:223], v[80:83]
	v_mfma_f32_16x16x32_bf16 v[76:79], v[148:151], v[220:223], v[76:79]
	s_setprio 0
	s_setprio 1
	v_mfma_f32_16x16x32_bf16 v[120:123], v[152:155], v[168:171], v[120:123]
	v_mfma_f32_16x16x32_bf16 v[116:119], v[160:163], v[168:171], v[116:119]
	v_mfma_f32_16x16x32_bf16 v[104:107], v[152:155], v[176:179], v[104:107]
	v_mfma_f32_16x16x32_bf16 v[100:103], v[160:163], v[176:179], v[100:103]
	v_mfma_f32_16x16x32_bf16 v[88:91], v[152:155], v[184:187], v[88:91]
	v_mfma_f32_16x16x32_bf16 v[84:87], v[160:163], v[184:187], v[84:87]
	v_mfma_f32_16x16x32_bf16 v[72:75], v[152:155], v[192:195], v[72:75]
	v_mfma_f32_16x16x32_bf16 v[68:71], v[160:163], v[192:195], v[68:71]
	v_mfma_f32_16x16x32_bf16 v[120:123], v[156:159], v[172:175], v[120:123]
	v_mfma_f32_16x16x32_bf16 v[116:119], v[164:167], v[172:175], v[116:119]
	v_mfma_f32_16x16x32_bf16 v[104:107], v[156:159], v[180:183], v[104:107]
	v_mfma_f32_16x16x32_bf16 v[100:103], v[164:167], v[180:183], v[100:103]
	v_mfma_f32_16x16x32_bf16 v[88:91], v[156:159], v[188:191], v[88:91]
	v_mfma_f32_16x16x32_bf16 v[84:87], v[164:167], v[188:191], v[84:87]
	v_mfma_f32_16x16x32_bf16 v[72:75], v[156:159], v[220:223], v[72:75]
	v_mfma_f32_16x16x32_bf16 v[68:71], v[164:167], v[220:223], v[68:71]
	s_setprio 0
	s_barrier
	s_add_i32 s74, s75, s60
	v_lshl_add_u64 v[196:197], s[22:23], 0, v[212:213]
	s_mov_b32 m0, s74
	ds_read_b128 v[168:171], v244 offset:16384
	ds_read_b128 v[172:175], v244 offset:17408
	ds_read_b128 v[176:179], v244 offset:18432
	ds_read_b128 v[180:183], v244 offset:19456
	ds_read_b128 v[184:187], v244 offset:20480
	ds_read_b128 v[188:191], v244 offset:21504
	ds_read_b128 v[192:195], v244 offset:22528
	ds_read_b128 v[220:223], v244 offset:23552
	global_load_lds_dwordx4 v[196:197], off
	s_add_i32 m0, s74, 0x2000
	s_add_u32 s74, s22, 0x8000
	v_lshl_add_u64 v[198:199], s[22:23], 0, v[0:1]
	s_addc_u32 s75, s23, 0
	s_add_i32 s73, s73, s60
	global_load_lds_dwordx4 v[198:199], off
	v_lshl_add_u64 v[224:225], s[74:75], 0, v[212:213]
	s_mov_b32 m0, s73
	v_lshl_add_u64 v[226:227], s[52:53], 0, v[210:211]
	global_load_lds_dwordx4 v[224:225], off
	v_lshl_add_u64 v[224:225], s[74:75], 0, v[0:1]
	s_add_i32 m0, s73, 0x2000
	s_nop 0
	global_load_lds_dwordx4 v[224:225], off
	v_lshl_add_u64 v[224:225], s[52:53], 0, v[214:215]
	s_mov_b32 m0, s61
	s_nop 0
	global_load_lds_dwordx4 v[224:225], off
	s_mov_b32 m0, s62
	s_nop 0
	global_load_lds_dwordx4 v[226:227], off
	s_waitcnt vmcnt(8)
	s_waitcnt lgkmcnt(0)
	s_barrier
; #define PG8_STAGE(bufoff, gbase, voff) do { _Pragma("unroll") for (int _i = 0; _i < 2; ++_i) \
;         __builtin_amdgcn_global_load_lds((const unsigned*)((const char*)(gbase) + (voff)[_i]), (LAS unsigned*)(lds + (bufoff) + ldsw + _i * 8192), 16, 0, 0); } while (0)
; #define PG8_LDA(dst, b, h) do { _Pragma("unroll") for (int m = 0; m < 4; ++m) _Pragma("unroll") for (int k = 0; k < 2; ++k) dst[m][k] = *(const LAS bf16x8*)(lds + PG8_SA(b, h) + aoff + m * 2048 + k * 1024); } while (0)
; #define PG8_LDB(dst, b, h) do { _Pragma("unroll") for (int n = 0; n < 2; ++n) _Pragma("unroll") for (int k = 0; k < 2; ++k) dst[n][k] = *(const LAS bf16x8*)(lds + PG8_SB(b, h) + boff + n * 2048 + k * 1024); } while (0)
; #define PG8_MMA(ai, bj, At, Bt) do { __builtin_amdgcn_s_setprio(1); _Pragma("unroll") for (int m = 0; m < 4; ++m) _Pragma("unroll") for (int n = 0; n < 2; ++n) _Pragma("unroll") for (int k = 0; k < 2; ++k) \
;         acc[ai][bj][m][n] = __builtin_amdgcn_mfma_f32_16x16x32_bf16(Bt[n][k], At[m][k], acc[ai][bj][m][n], 0, 0, 0); __builtin_amdgcn_s_setprio(0); } while (0)
; #define PG8_WAIT_V(n) asm volatile("s_waitcnt vmcnt(" #n ")" ::: "memory")
; #define PG8_WAIT_L(n) asm volatile("s_waitcnt lgkmcnt(" #n ")" ::: "memory")
; #define PG8_BAR __builtin_amdgcn_s_barrier()
; #define PG8_SCHED __builtin_amdgcn_sched_barrier(0)
; template <class Epi>
; __device__ __forceinline__ void gemm_phase(LAS unsigned char* lds, const Gemm g, const StaticOrder& S, const Epi& E) {
;     ...
;             PG8_WAIT_V(8); PG8_WAIT_L(0); PG8_BAR; PG8_MMA(1, 0, At, B0); PG8_MMA(1, 1, At, B1); PG8_BAR; PG8_SCHED;
;             PG8_LDB(B0, 1, 0); PG8_LDB(B1, 1, 1); PG8_SCHED; PG8_LDA(At, 1, 0); PG8_STAGE(PG8_SA(0, 1), a2 + hstepA, voffA);
;             PG8_WAIT_V(8); PG8_WAIT_L(0); PG8_BAR; PG8_MMA(0, 0, At, B0); PG8_MMA(0, 1, At, B1); PG8_BAR; PG8_SCHED;
	s_setprio 1
	s_waitcnt lgkmcnt(0)
	v_mfma_f32_16x16x32_bf16 v[64:67], v[136:139], v[168:171], v[64:67]
	v_mfma_f32_16x16x32_bf16 v[60:63], v[144:147], v[168:171], v[60:63]
	v_mfma_f32_16x16x32_bf16 v[48:51], v[136:139], v[176:179], v[48:51]
	v_mfma_f32_16x16x32_bf16 v[44:47], v[144:147], v[176:179], v[44:47]
	v_mfma_f32_16x16x32_bf16 v[32:35], v[136:139], v[184:187], v[32:35]
	v_mfma_f32_16x16x32_bf16 v[28:31], v[144:147], v[184:187], v[28:31]
	v_mfma_f32_16x16x32_bf16 v[16:19], v[136:139], v[192:195], v[16:19]
	v_mfma_f32_16x16x32_bf16 v[12:15], v[144:147], v[192:195], v[12:15]
	v_mfma_f32_16x16x32_bf16 v[64:67], v[140:143], v[172:175], v[64:67]
	v_mfma_f32_16x16x32_bf16 v[60:63], v[148:151], v[172:175], v[60:63]
	v_mfma_f32_16x16x32_bf16 v[48:51], v[140:143], v[180:183], v[48:51]
	v_mfma_f32_16x16x32_bf16 v[44:47], v[148:151], v[180:183], v[44:47]
	v_mfma_f32_16x16x32_bf16 v[32:35], v[140:143], v[188:191], v[32:35]
	v_mfma_f32_16x16x32_bf16 v[28:31], v[148:151], v[188:191], v[28:31]
	v_mfma_f32_16x16x32_bf16 v[16:19], v[140:143], v[220:223], v[16:19]
	v_mfma_f32_16x16x32_bf16 v[12:15], v[148:151], v[220:223], v[12:15]
	s_setprio 0
	s_setprio 1
	v_mfma_f32_16x16x32_bf16 v[56:59], v[152:155], v[168:171], v[56:59]
	v_mfma_f32_16x16x32_bf16 v[52:55], v[160:163], v[168:171], v[52:55]
	v_mfma_f32_16x16x32_bf16 v[40:43], v[152:155], v[176:179], v[40:43]
	v_mfma_f32_16x16x32_bf16 v[36:39], v[160:163], v[176:179], v[36:39]
	v_mfma_f32_16x16x32_bf16 v[24:27], v[152:155], v[184:187], v[24:27]
	v_mfma_f32_16x16x32_bf16 v[20:23], v[160:163], v[184:187], v[20:23]
	v_mfma_f32_16x16x32_bf16 v[8:11], v[152:155], v[192:195], v[8:11]
	v_mfma_f32_16x16x32_bf16 v[4:7], v[160:163], v[192:195], v[4:7]
	v_mfma_f32_16x16x32_bf16 v[56:59], v[156:159], v[172:175], v[56:59]
	v_mfma_f32_16x16x32_bf16 v[52:55], v[164:167], v[172:175], v[52:55]
	v_mfma_f32_16x16x32_bf16 v[40:43], v[156:159], v[180:183], v[40:43]
	v_mfma_f32_16x16x32_bf16 v[36:39], v[164:167], v[180:183], v[36:39]
	v_mfma_f32_16x16x32_bf16 v[24:27], v[156:159], v[188:191], v[24:27]
	v_mfma_f32_16x16x32_bf16 v[20:23], v[164:167], v[188:191], v[20:23]
	v_mfma_f32_16x16x32_bf16 v[8:11], v[156:159], v[220:223], v[8:11]
	v_mfma_f32_16x16x32_bf16 v[4:7], v[164:167], v[220:223], v[4:7]
	s_setprio 0
	s_barrier
	s_add_i32 s73, 0, 0x18000
	s_add_i32 s74, 0, 0x1c000
	v_add_u32_e32 v148, s73, v242
	v_add_u32_e32 v164, s74, v242
	ds_read_b128 v[136:139], v148
	ds_read_b128 v[140:143], v148 offset:1024
	ds_read_b128 v[144:147], v148 offset:2048
	ds_read_b128 v[148:151], v148 offset:3072
	ds_read_b128 v[152:155], v164
	ds_read_b128 v[156:159], v164 offset:1024
	ds_read_b128 v[160:163], v164 offset:2048
	ds_read_b128 v[164:167], v164 offset:3072
	s_add_u32 s52, s52, s28
	s_addc_u32 s53, s53, 0
	s_mov_b32 m0, s63
	v_lshl_add_u64 v[228:229], s[52:53], 0, v[214:215]
	ds_read_b128 v[168:171], v244 offset:32768
	ds_read_b128 v[172:175], v244 offset:33792
	ds_read_b128 v[176:179], v244 offset:34816
	ds_read_b128 v[180:183], v244 offset:35840
	ds_read_b128 v[184:187], v244 offset:36864
	ds_read_b128 v[188:191], v244 offset:37888
	ds_read_b128 v[192:195], v244 offset:38912
	ds_read_b128 v[220:223], v244 offset:39936
	global_load_lds_dwordx4 v[228:229], off
	v_lshl_add_u64 v[228:229], s[52:53], 0, v[210:211]
	s_mov_b32 m0, s64
	s_nop 0
	global_load_lds_dwordx4 v[228:229], off
	s_waitcnt vmcnt(8)
	s_waitcnt lgkmcnt(0)
	s_barrier
	s_setprio 1
	s_waitcnt lgkmcnt(0)
	v_mfma_f32_16x16x32_bf16 v[128:131], v[136:139], v[168:171], v[128:131]
	v_mfma_f32_16x16x32_bf16 v[124:127], v[144:147], v[168:171], v[124:127]
	v_mfma_f32_16x16x32_bf16 v[112:115], v[136:139], v[176:179], v[112:115]
	v_mfma_f32_16x16x32_bf16 v[108:111], v[144:147], v[176:179], v[108:111]
	v_mfma_f32_16x16x32_bf16 v[96:99], v[136:139], v[184:187], v[96:99]
	v_mfma_f32_16x16x32_bf16 v[92:95], v[144:147], v[184:187], v[92:95]
	v_mfma_f32_16x16x32_bf16 v[80:83], v[136:139], v[192:195], v[80:83]
	v_mfma_f32_16x16x32_bf16 v[76:79], v[144:147], v[192:195], v[76:79]
	v_mfma_f32_16x16x32_bf16 v[128:131], v[140:143], v[172:175], v[128:131]
	v_mfma_f32_16x16x32_bf16 v[124:127], v[148:151], v[172:175], v[124:127]
	v_mfma_f32_16x16x32_bf16 v[112:115], v[140:143], v[180:183], v[112:115]
	v_mfma_f32_16x16x32_bf16 v[108:111], v[148:151], v[180:183], v[108:111]
	v_mfma_f32_16x16x32_bf16 v[96:99], v[140:143], v[188:191], v[96:99]
	v_mfma_f32_16x16x32_bf16 v[92:95], v[148:151], v[188:191], v[92:95]
	v_mfma_f32_16x16x32_bf16 v[80:83], v[140:143], v[220:223], v[80:83]
	v_mfma_f32_16x16x32_bf16 v[76:79], v[148:151], v[220:223], v[76:79]
	s_setprio 0
	s_setprio 1
	v_mfma_f32_16x16x32_bf16 v[120:123], v[152:155], v[168:171], v[120:123]
	v_mfma_f32_16x16x32_bf16 v[116:119], v[160:163], v[168:171], v[116:119]
	v_mfma_f32_16x16x32_bf16 v[104:107], v[152:155], v[176:179], v[104:107]
	v_mfma_f32_16x16x32_bf16 v[100:103], v[160:163], v[176:179], v[100:103]
	v_mfma_f32_16x16x32_bf16 v[88:91], v[152:155], v[184:187], v[88:91]
	v_mfma_f32_16x16x32_bf16 v[84:87], v[160:163], v[184:187], v[84:87]
	v_mfma_f32_16x16x32_bf16 v[72:75], v[152:155], v[192:195], v[72:75]
	v_mfma_f32_16x16x32_bf16 v[68:71], v[160:163], v[192:195], v[68:71]
	v_mfma_f32_16x16x32_bf16 v[120:123], v[156:159], v[172:175], v[120:123]
	v_mfma_f32_16x16x32_bf16 v[116:119], v[164:167], v[172:175], v[116:119]
	v_mfma_f32_16x16x32_bf16 v[104:107], v[156:159], v[180:183], v[104:107]
	v_mfma_f32_16x16x32_bf16 v[100:103], v[164:167], v[180:183], v[100:103]
	v_mfma_f32_16x16x32_bf16 v[88:91], v[156:159], v[188:191], v[88:91]
	v_mfma_f32_16x16x32_bf16 v[84:87], v[164:167], v[188:191], v[84:87]
	v_mfma_f32_16x16x32_bf16 v[72:75], v[156:159], v[220:223], v[72:75]
	v_mfma_f32_16x16x32_bf16 v[68:71], v[164:167], v[220:223], v[68:71]
	s_setprio 0
	s_barrier
; #define PG8_STAGE(bufoff, gbase, voff) do { _Pragma("unroll") for (int _i = 0; _i < 2; ++_i) \
;         __builtin_amdgcn_global_load_lds((const unsigned*)((const char*)(gbase) + (voff)[_i]), (LAS unsigned*)(lds + (bufoff) + ldsw + _i * 8192), 16, 0, 0); } while (0)
; #define PG8_LDA(dst, b, h) do { _Pragma("unroll") for (int m = 0; m < 4; ++m) _Pragma("unroll") for (int k = 0; k < 2; ++k) dst[m][k] = *(const LAS bf16x8*)(lds + PG8_SA(b, h) + aoff + m * 2048 + k * 1024); } while (0)
; #define PG8_MMA(ai, bj, At, Bt) do { __builtin_amdgcn_s_setprio(1); _Pragma("unroll") for (int m = 0; m < 4; ++m) _Pragma("unroll") for (int n = 0; n < 2; ++n) _Pragma("unroll") for (int k = 0; k < 2; ++k) \
;         acc[ai][bj][m][n] = __builtin_amdgcn_mfma_f32_16x16x32_bf16(Bt[n][k], At[m][k], acc[ai][bj][m][n], 0, 0, 0); __builtin_amdgcn_s_setprio(0); } while (0)
; #define PG8_WAIT_V(n) asm volatile("s_waitcnt vmcnt(" #n ")" ::: "memory")
; #define PG8_WAIT_L(n) asm volatile("s_waitcnt lgkmcnt(" #n ")" ::: "memory")
; #define PG8_BAR __builtin_amdgcn_s_barrier()
; #define PG8_SCHED __builtin_amdgcn_sched_barrier(0)
; template <class Epi>
; __device__ __forceinline__ void gemm_phase(LAS unsigned char* lds, const Gemm g, const StaticOrder& S, const Epi& E) {
;     ...
;             PG8_LDA(At, 1, 1); PG8_STAGE(PG8_SB(1, 0), b3, voffB); PG8_STAGE(PG8_SB(1, 1), b3 + hstepB, voffB); PG8_STAGE(PG8_SA(1, 0), a3, voffA);
;             PG8_WAIT_V(8); PG8_WAIT_L(0); PG8_BAR; PG8_MMA(1, 0, At, B0); PG8_MMA(1, 1, At, B1); PG8_BAR; PG8_SCHED;
;         }
;         if (wr == 0) PG8_BAR;
	s_add_i32 s52, s73, s60
	v_lshl_add_u64 v[196:197], v[196:197], 0, s[30:31]
	s_mov_b32 m0, s52
	ds_read_b128 v[168:171], v244 offset:49152
	ds_read_b128 v[172:175], v244 offset:50176
	ds_read_b128 v[176:179], v244 offset:51200
	ds_read_b128 v[180:183], v244 offset:52224
	ds_read_b128 v[184:187], v244 offset:53248
	ds_read_b128 v[188:191], v244 offset:54272
	ds_read_b128 v[192:195], v244 offset:55296
	ds_read_b128 v[220:223], v244 offset:56320
	global_load_lds_dwordx4 v[196:197], off
	s_add_i32 m0, s52, 0x2000
	s_add_u32 s22, s22, 0x8080
	v_lshl_add_u64 v[196:197], v[198:199], 0, s[30:31]
	s_addc_u32 s23, s23, 0
	s_add_i32 s52, s74, s60
	global_load_lds_dwordx4 v[196:197], off
	v_lshl_add_u64 v[196:197], s[22:23], 0, v[212:213]
	s_mov_b32 m0, s52
	s_nop 0
	global_load_lds_dwordx4 v[196:197], off
	v_lshl_add_u64 v[196:197], s[22:23], 0, v[0:1]
	s_add_i32 m0, s52, 0x2000
	s_nop 0
	global_load_lds_dwordx4 v[196:197], off
	v_lshl_add_u64 v[196:197], v[224:225], 0, s[30:31]
	s_mov_b32 m0, s65
	s_nop 0
	global_load_lds_dwordx4 v[196:197], off
	v_lshl_add_u64 v[196:197], v[226:227], 0, s[30:31]
	s_mov_b32 m0, s66
	s_nop 0
	global_load_lds_dwordx4 v[196:197], off
	s_waitcnt vmcnt(8)
	s_waitcnt lgkmcnt(0)
	s_barrier
	s_setprio 1
	s_waitcnt lgkmcnt(0)
	v_mfma_f32_16x16x32_bf16 v[64:67], v[136:139], v[168:171], v[64:67]
	v_mfma_f32_16x16x32_bf16 v[60:63], v[144:147], v[168:171], v[60:63]
	v_mfma_f32_16x16x32_bf16 v[48:51], v[136:139], v[176:179], v[48:51]
	v_mfma_f32_16x16x32_bf16 v[44:47], v[144:147], v[176:179], v[44:47]
	v_mfma_f32_16x16x32_bf16 v[32:35], v[136:139], v[184:187], v[32:35]
	v_mfma_f32_16x16x32_bf16 v[28:31], v[144:147], v[184:187], v[28:31]
	v_mfma_f32_16x16x32_bf16 v[16:19], v[136:139], v[192:195], v[16:19]
	v_mfma_f32_16x16x32_bf16 v[12:15], v[144:147], v[192:195], v[12:15]
	v_mfma_f32_16x16x32_bf16 v[64:67], v[140:143], v[172:175], v[64:67]
	v_mfma_f32_16x16x32_bf16 v[60:63], v[148:151], v[172:175], v[60:63]
	v_mfma_f32_16x16x32_bf16 v[48:51], v[140:143], v[180:183], v[48:51]
	v_mfma_f32_16x16x32_bf16 v[44:47], v[148:151], v[180:183], v[44:47]
	v_mfma_f32_16x16x32_bf16 v[32:35], v[140:143], v[188:191], v[32:35]
	v_mfma_f32_16x16x32_bf16 v[28:31], v[148:151], v[188:191], v[28:31]
	v_mfma_f32_16x16x32_bf16 v[16:19], v[140:143], v[220:223], v[16:19]
	v_mfma_f32_16x16x32_bf16 v[12:15], v[148:151], v[220:223], v[12:15]
	s_setprio 0
	s_setprio 1
	v_mfma_f32_16x16x32_bf16 v[56:59], v[152:155], v[168:171], v[56:59]
	v_mfma_f32_16x16x32_bf16 v[52:55], v[160:163], v[168:171], v[52:55]
	v_mfma_f32_16x16x32_bf16 v[40:43], v[152:155], v[176:179], v[40:43]
	v_mfma_f32_16x16x32_bf16 v[36:39], v[160:163], v[176:179], v[36:39]
	v_mfma_f32_16x16x32_bf16 v[24:27], v[152:155], v[184:187], v[24:27]
	v_mfma_f32_16x16x32_bf16 v[20:23], v[160:163], v[184:187], v[20:23]
	v_mfma_f32_16x16x32_bf16 v[8:11], v[152:155], v[192:195], v[8:11]
	v_mfma_f32_16x16x32_bf16 v[4:7], v[160:163], v[192:195], v[4:7]
	v_mfma_f32_16x16x32_bf16 v[56:59], v[156:159], v[172:175], v[56:59]
	v_mfma_f32_16x16x32_bf16 v[52:55], v[164:167], v[172:175], v[52:55]
	v_mfma_f32_16x16x32_bf16 v[40:43], v[156:159], v[180:183], v[40:43]
	v_mfma_f32_16x16x32_bf16 v[36:39], v[164:167], v[180:183], v[36:39]
	v_mfma_f32_16x16x32_bf16 v[24:27], v[156:159], v[188:191], v[24:27]
	v_mfma_f32_16x16x32_bf16 v[20:23], v[164:167], v[188:191], v[20:23]
	v_mfma_f32_16x16x32_bf16 v[8:11], v[156:159], v[220:223], v[8:11]
	v_mfma_f32_16x16x32_bf16 v[4:7], v[164:167], v[220:223], v[4:7]
	s_add_i32 s72, s72, 2
	s_add_u32 s4, s4, 0x100
	s_addc_u32 s5, s5, 0
	s_cmp_gt_u32 s72, 5
	s_setprio 0
	s_barrier
	s_cbranch_scc0 .LBB0_902
	s_and_b64 vcc, exec, s[38:39]
	s_cbranch_vccz .LBB0_905
	s_barrier

; #define PG8_STAGE(bufoff, gbase, voff) do { _Pragma("unroll") for (int _i = 0; _i < 2; ++_i) \
;         __builtin_amdgcn_global_load_lds((const unsigned*)((const char*)(gbase) + (voff)[_i]), (LAS unsigned*)(lds + (bufoff) + ldsw + _i * 8192), 16, 0, 0); } while (0)
; #define PG8_LDA(dst, b, h) do { _Pragma("unroll") for (int m = 0; m < 4; ++m) _Pragma("unroll") for (int k = 0; k < 2; ++k) dst[m][k] = *(const LAS bf16x8*)(lds + PG8_SA(b, h) + aoff + m * 2048 + k * 1024); } while (0)
; #define PG8_LDB(dst, b, h) do { _Pragma("unroll") for (int n = 0; n < 2; ++n) _Pragma("unroll") for (int k = 0; k < 2; ++k) dst[n][k] = *(const LAS bf16x8*)(lds + PG8_SB(b, h) + boff + n * 2048 + k * 1024); } while (0)
; #define PG8_MMA(ai, bj, At, Bt) do { __builtin_amdgcn_s_setprio(1); _Pragma("unroll") for (int m = 0; m < 4; ++m) _Pragma("unroll") for (int n = 0; n < 2; ++n) _Pragma("unroll") for (int k = 0; k < 2; ++k) \
;         acc[ai][bj][m][n] = __builtin_amdgcn_mfma_f32_16x16x32_bf16(Bt[n][k], At[m][k], acc[ai][bj][m][n], 0, 0, 0); __builtin_amdgcn_s_setprio(0); } while (0)
; #define PG8_WAIT_V(n) asm volatile("s_waitcnt vmcnt(" #n ")" ::: "memory")
; #define PG8_WAIT_L(n) asm volatile("s_waitcnt lgkmcnt(" #n ")" ::: "memory")
; #define PG8_BAR __builtin_amdgcn_s_barrier()
; #define PG8_SCHED __builtin_amdgcn_sched_barrier(0)
; template <class Epi>
; __device__ __forceinline__ void gemm_phase(LAS unsigned char* lds, const Gemm g, const StaticOrder& S, const Epi& E) {
;     ...
;         for (int t = 0; t < nt; t += 2) {
;             const bool last = (t == nt - 2);
;             const char* a1 = cA + (size_t)(t + 1) * kstep;
;             const char* a2 = last ? nA : cA + (size_t)(t + 2) * kstep; const char* b2 = last ? nB : cB + (size_t)(t + 2) * kstep;
;             const char* a3 = a2 + kstep; const char* b3 = b2 + kstep;
;             PG8_LDB(B0, 0, 0); PG8_LDB(B1, 0, 1); PG8_SCHED; PG8_LDA(At, 0, 0); PG8_STAGE(PG8_SA(1, 1), a1 + hstepA, voffA);
;             PG8_WAIT_V(8); PG8_WAIT_L(0); PG8_BAR; PG8_MMA(0, 0, At, B0); PG8_MMA(0, 1, At, B1); PG8_BAR; PG8_SCHED;
;             PG8_LDA(At, 0, 1); PG8_STAGE(PG8_SB(0, 0), b2, voffB); PG8_STAGE(PG8_SB(0, 1), b2 + hstepB, voffB); PG8_STAGE(PG8_SA(0, 0), a2, voffA);
;             PG8_WAIT_V(8); PG8_WAIT_L(0); PG8_BAR; PG8_MMA(1, 0, At, B0); PG8_MMA(1, 1, At, B1); PG8_BAR; PG8_SCHED;
.LBB0_1005:
	s_add_u32 s22, s50, 0xfffc0080
	s_addc_u32 s23, s51, -1
	s_add_i32 s72, 0, 0x10000
	s_cmp_eq_u32 s71, 12
	s_cselect_b32 s53, s39, s23
	s_cselect_b32 s52, s67, s22
	s_cselect_b32 s23, s35, s70
	s_cselect_b32 s22, s68, s69
	s_add_i32 s74, 0, 0x14000
	v_add_u32_e32 v144, s72, v232
	v_add_u32_e32 v160, s74, v232
	ds_read_b128 v[132:135], v144
	ds_read_b128 v[136:139], v144 offset:1024
	ds_read_b128 v[140:143], v144 offset:2048
	ds_read_b128 v[144:147], v144 offset:3072
	ds_read_b128 v[148:151], v160
	ds_read_b128 v[152:155], v160 offset:1024
	ds_read_b128 v[156:159], v160 offset:2048
	ds_read_b128 v[160:163], v160 offset:3072
	v_lshl_add_u64 v[196:197], s[50:51], 0, v[194:195]
	s_add_i32 m0, s59, 0xc000
	ds_read_b128 v[164:167], v242
	ds_read_b128 v[168:171], v242 offset:1024
	ds_read_b128 v[172:175], v242 offset:2048
	ds_read_b128 v[176:179], v242 offset:3072
	ds_read_b128 v[180:183], v242 offset:4096
	ds_read_b128 v[184:187], v242 offset:5120
	ds_read_b128 v[212:215], v242 offset:6144
	ds_read_b128 v[216:219], v242 offset:7168
	global_load_lds_dwordx4 v[196:197], off
	v_lshl_add_u64 v[196:197], s[50:51], 0, v[210:211]
	s_add_i32 m0, s59, 0xe000
	s_nop 0
	global_load_lds_dwordx4 v[196:197], off
	s_waitcnt vmcnt(8)
	s_waitcnt lgkmcnt(0)
	s_barrier
	s_setprio 1
	s_waitcnt lgkmcnt(0)
	v_mfma_f32_16x16x32_bf16 v[128:131], v[132:135], v[164:167], v[128:131]
	v_mfma_f32_16x16x32_bf16 v[124:127], v[140:143], v[164:167], v[124:127]
	v_mfma_f32_16x16x32_bf16 v[112:115], v[132:135], v[172:175], v[112:115]
	v_mfma_f32_16x16x32_bf16 v[108:111], v[140:143], v[172:175], v[108:111]
	v_mfma_f32_16x16x32_bf16 v[96:99], v[132:135], v[180:183], v[96:99]
	v_mfma_f32_16x16x32_bf16 v[92:95], v[140:143], v[180:183], v[92:95]
	v_mfma_f32_16x16x32_bf16 v[80:83], v[132:135], v[212:215], v[80:83]
	v_mfma_f32_16x16x32_bf16 v[76:79], v[140:143], v[212:215], v[76:79]
	v_mfma_f32_16x16x32_bf16 v[128:131], v[136:139], v[168:171], v[128:131]
	v_mfma_f32_16x16x32_bf16 v[124:127], v[144:147], v[168:171], v[124:127]
	v_mfma_f32_16x16x32_bf16 v[112:115], v[136:139], v[176:179], v[112:115]
	v_mfma_f32_16x16x32_bf16 v[108:111], v[144:147], v[176:179], v[108:111]
	v_mfma_f32_16x16x32_bf16 v[96:99], v[136:139], v[184:187], v[96:99]
	v_mfma_f32_16x16x32_bf16 v[92:95], v[144:147], v[184:187], v[92:95]
	v_mfma_f32_16x16x32_bf16 v[80:83], v[136:139], v[216:219], v[80:83]
	v_mfma_f32_16x16x32_bf16 v[76:79], v[144:147], v[216:219], v[76:79]
	s_setprio 0
	s_setprio 1
	v_mfma_f32_16x16x32_bf16 v[120:123], v[148:151], v[164:167], v[120:123]
	v_mfma_f32_16x16x32_bf16 v[116:119], v[156:159], v[164:167], v[116:119]
	v_mfma_f32_16x16x32_bf16 v[104:107], v[148:151], v[172:175], v[104:107]
	v_mfma_f32_16x16x32_bf16 v[100:103], v[156:159], v[172:175], v[100:103]
	v_mfma_f32_16x16x32_bf16 v[88:91], v[148:151], v[180:183], v[88:91]
	v_mfma_f32_16x16x32_bf16 v[84:87], v[156:159], v[180:183], v[84:87]
	v_mfma_f32_16x16x32_bf16 v[72:75], v[148:151], v[212:215], v[72:75]
	v_mfma_f32_16x16x32_bf16 v[68:71], v[156:159], v[212:215], v[68:71]
	v_mfma_f32_16x16x32_bf16 v[120:123], v[152:155], v[168:171], v[120:123]
	v_mfma_f32_16x16x32_bf16 v[116:119], v[160:163], v[168:171], v[116:119]
	v_mfma_f32_16x16x32_bf16 v[104:107], v[152:155], v[176:179], v[104:107]
	v_mfma_f32_16x16x32_bf16 v[100:103], v[160:163], v[176:179], v[100:103]
	v_mfma_f32_16x16x32_bf16 v[88:91], v[152:155], v[184:187], v[88:91]
	v_mfma_f32_16x16x32_bf16 v[84:87], v[160:163], v[184:187], v[84:87]
	v_mfma_f32_16x16x32_bf16 v[72:75], v[152:155], v[216:219], v[72:75]
	v_mfma_f32_16x16x32_bf16 v[68:71], v[160:163], v[216:219], v[68:71]
	s_setprio 0
	s_barrier
	s_add_i32 s72, s72, s58
	v_lshl_add_u64 v[196:197], s[22:23], 0, v[190:191]
	s_mov_b32 m0, s72
	ds_read_b128 v[164:167], v242 offset:16384
	ds_read_b128 v[168:171], v242 offset:17408
	ds_read_b128 v[172:175], v242 offset:18432
	ds_read_b128 v[176:179], v242 offset:19456
	ds_read_b128 v[180:183], v242 offset:20480
	ds_read_b128 v[184:187], v242 offset:21504
	ds_read_b128 v[212:215], v242 offset:22528
	ds_read_b128 v[216:219], v242 offset:23552
	global_load_lds_dwordx4 v[196:197], off
	s_add_i32 m0, s72, 0x2000
	s_add_u32 s72, s22, 0x10000
	v_lshl_add_u64 v[198:199], s[22:23], 0, v[0:1]
	s_addc_u32 s73, s23, 0
	s_add_i32 s74, s74, s58
	global_load_lds_dwordx4 v[198:199], off
	v_lshl_add_u64 v[220:221], s[72:73], 0, v[190:191]
	s_mov_b32 m0, s74
	v_lshl_add_u64 v[222:223], s[52:53], 0, v[188:189]
	global_load_lds_dwordx4 v[220:221], off
	v_lshl_add_u64 v[220:221], s[72:73], 0, v[0:1]
	s_add_i32 m0, s74, 0x2000
	s_nop 0
	global_load_lds_dwordx4 v[220:221], off
	v_lshl_add_u64 v[220:221], s[52:53], 0, v[192:193]
	s_mov_b32 m0, s59
	s_nop 0
	global_load_lds_dwordx4 v[220:221], off
	s_mov_b32 m0, s60
	s_nop 0
	global_load_lds_dwordx4 v[222:223], off
	s_waitcnt vmcnt(8)
	s_waitcnt lgkmcnt(0)
	s_barrier
; #define PG8_STAGE(bufoff, gbase, voff) do { _Pragma("unroll") for (int _i = 0; _i < 2; ++_i) \
;         __builtin_amdgcn_global_load_lds((const unsigned*)((const char*)(gbase) + (voff)[_i]), (LAS unsigned*)(lds + (bufoff) + ldsw + _i * 8192), 16, 0, 0); } while (0)
; #define PG8_LDA(dst, b, h) do { _Pragma("unroll") for (int m = 0; m < 4; ++m) _Pragma("unroll") for (int k = 0; k < 2; ++k) dst[m][k] = *(const LAS bf16x8*)(lds + PG8_SA(b, h) + aoff + m * 2048 + k * 1024); } while (0)
; #define PG8_LDB(dst, b, h) do { _Pragma("unroll") for (int n = 0; n < 2; ++n) _Pragma("unroll") for (int k = 0; k < 2; ++k) dst[n][k] = *(const LAS bf16x8*)(lds + PG8_SB(b, h) + boff + n * 2048 + k * 1024); } while (0)
; #define PG8_MMA(ai, bj, At, Bt) do { __builtin_amdgcn_s_setprio(1); _Pragma("unroll") for (int m = 0; m < 4; ++m) _Pragma("unroll") for (int n = 0; n < 2; ++n) _Pragma("unroll") for (int k = 0; k < 2; ++k) \
;         acc[ai][bj][m][n] = __builtin_amdgcn_mfma_f32_16x16x32_bf16(Bt[n][k], At[m][k], acc[ai][bj][m][n], 0, 0, 0); __builtin_amdgcn_s_setprio(0); } while (0)
; #define PG8_WAIT_V(n) asm volatile("s_waitcnt vmcnt(" #n ")" ::: "memory")
; #define PG8_WAIT_L(n) asm volatile("s_waitcnt lgkmcnt(" #n ")" ::: "memory")
; #define PG8_BAR __builtin_amdgcn_s_barrier()
; #define PG8_SCHED __builtin_amdgcn_sched_barrier(0)
; template <class Epi>
; __device__ __forceinline__ void gemm_phase(LAS unsigned char* lds, const Gemm g, const StaticOrder& S, const Epi& E) {
;     ...
;             PG8_WAIT_V(8); PG8_WAIT_L(0); PG8_BAR; PG8_MMA(1, 0, At, B0); PG8_MMA(1, 1, At, B1); PG8_BAR; PG8_SCHED;
;             PG8_LDB(B0, 1, 0); PG8_LDB(B1, 1, 1); PG8_SCHED; PG8_LDA(At, 1, 0); PG8_STAGE(PG8_SA(0, 1), a2 + hstepA, voffA);
;             PG8_WAIT_V(8); PG8_WAIT_L(0); PG8_BAR; PG8_MMA(0, 0, At, B0); PG8_MMA(0, 1, At, B1); PG8_BAR; PG8_SCHED;
	s_setprio 1
	s_waitcnt lgkmcnt(0)
	v_mfma_f32_16x16x32_bf16 v[64:67], v[132:135], v[164:167], v[64:67]
	v_mfma_f32_16x16x32_bf16 v[60:63], v[140:143], v[164:167], v[60:63]
	v_mfma_f32_16x16x32_bf16 v[48:51], v[132:135], v[172:175], v[48:51]
	v_mfma_f32_16x16x32_bf16 v[44:47], v[140:143], v[172:175], v[44:47]
	v_mfma_f32_16x16x32_bf16 v[32:35], v[132:135], v[180:183], v[32:35]
	v_mfma_f32_16x16x32_bf16 v[28:31], v[140:143], v[180:183], v[28:31]
	v_mfma_f32_16x16x32_bf16 v[16:19], v[132:135], v[212:215], v[16:19]
	v_mfma_f32_16x16x32_bf16 v[12:15], v[140:143], v[212:215], v[12:15]
	v_mfma_f32_16x16x32_bf16 v[64:67], v[136:139], v[168:171], v[64:67]
	v_mfma_f32_16x16x32_bf16 v[60:63], v[144:147], v[168:171], v[60:63]
	v_mfma_f32_16x16x32_bf16 v[48:51], v[136:139], v[176:179], v[48:51]
	v_mfma_f32_16x16x32_bf16 v[44:47], v[144:147], v[176:179], v[44:47]
	v_mfma_f32_16x16x32_bf16 v[32:35], v[136:139], v[184:187], v[32:35]
	v_mfma_f32_16x16x32_bf16 v[28:31], v[144:147], v[184:187], v[28:31]
	v_mfma_f32_16x16x32_bf16 v[16:19], v[136:139], v[216:219], v[16:19]
	v_mfma_f32_16x16x32_bf16 v[12:15], v[144:147], v[216:219], v[12:15]
	s_setprio 0
	s_setprio 1
	v_mfma_f32_16x16x32_bf16 v[56:59], v[148:151], v[164:167], v[56:59]
	v_mfma_f32_16x16x32_bf16 v[52:55], v[156:159], v[164:167], v[52:55]
	v_mfma_f32_16x16x32_bf16 v[40:43], v[148:151], v[172:175], v[40:43]
	v_mfma_f32_16x16x32_bf16 v[36:39], v[156:159], v[172:175], v[36:39]
	v_mfma_f32_16x16x32_bf16 v[24:27], v[148:151], v[180:183], v[24:27]
	v_mfma_f32_16x16x32_bf16 v[20:23], v[156:159], v[180:183], v[20:23]
	v_mfma_f32_16x16x32_bf16 v[8:11], v[148:151], v[212:215], v[8:11]
	v_mfma_f32_16x16x32_bf16 v[4:7], v[156:159], v[212:215], v[4:7]
	v_mfma_f32_16x16x32_bf16 v[56:59], v[152:155], v[168:171], v[56:59]
	v_mfma_f32_16x16x32_bf16 v[52:55], v[160:163], v[168:171], v[52:55]
	v_mfma_f32_16x16x32_bf16 v[40:43], v[152:155], v[176:179], v[40:43]
	v_mfma_f32_16x16x32_bf16 v[36:39], v[160:163], v[176:179], v[36:39]
	v_mfma_f32_16x16x32_bf16 v[24:27], v[152:155], v[184:187], v[24:27]
	v_mfma_f32_16x16x32_bf16 v[20:23], v[160:163], v[184:187], v[20:23]
	v_mfma_f32_16x16x32_bf16 v[8:11], v[152:155], v[216:219], v[8:11]
	v_mfma_f32_16x16x32_bf16 v[4:7], v[160:163], v[216:219], v[4:7]
	s_setprio 0
	s_barrier
	s_add_i32 s72, 0, 0x18000
	s_add_i32 s73, 0, 0x1c000
	v_add_u32_e32 v144, s72, v232
	v_add_u32_e32 v160, s73, v232
	ds_read_b128 v[132:135], v144
	ds_read_b128 v[136:139], v144 offset:1024
	ds_read_b128 v[140:143], v144 offset:2048
	ds_read_b128 v[144:147], v144 offset:3072
	ds_read_b128 v[148:151], v160
	ds_read_b128 v[152:155], v160 offset:1024
	ds_read_b128 v[156:159], v160 offset:2048
	ds_read_b128 v[160:163], v160 offset:3072
	s_add_u32 s52, s52, 0x40000
	s_addc_u32 s53, s53, 0
	s_mov_b32 m0, s61
	v_lshl_add_u64 v[224:225], s[52:53], 0, v[192:193]
	ds_read_b128 v[164:167], v242 offset:32768
	ds_read_b128 v[168:171], v242 offset:33792
	ds_read_b128 v[172:175], v242 offset:34816
	ds_read_b128 v[176:179], v242 offset:35840
	ds_read_b128 v[180:183], v242 offset:36864
	ds_read_b128 v[184:187], v242 offset:37888
	ds_read_b128 v[212:215], v242 offset:38912
	ds_read_b128 v[216:219], v242 offset:39936
	global_load_lds_dwordx4 v[224:225], off
	v_lshl_add_u64 v[224:225], s[52:53], 0, v[188:189]
	s_mov_b32 m0, s62
	s_nop 0
	global_load_lds_dwordx4 v[224:225], off
	s_waitcnt vmcnt(8)
	s_waitcnt lgkmcnt(0)
	s_barrier
	s_setprio 1
	s_waitcnt lgkmcnt(0)
	v_mfma_f32_16x16x32_bf16 v[128:131], v[132:135], v[164:167], v[128:131]
	v_mfma_f32_16x16x32_bf16 v[124:127], v[140:143], v[164:167], v[124:127]
	v_mfma_f32_16x16x32_bf16 v[112:115], v[132:135], v[172:175], v[112:115]
	v_mfma_f32_16x16x32_bf16 v[108:111], v[140:143], v[172:175], v[108:111]
	v_mfma_f32_16x16x32_bf16 v[96:99], v[132:135], v[180:183], v[96:99]
	v_mfma_f32_16x16x32_bf16 v[92:95], v[140:143], v[180:183], v[92:95]
	v_mfma_f32_16x16x32_bf16 v[80:83], v[132:135], v[212:215], v[80:83]
	v_mfma_f32_16x16x32_bf16 v[76:79], v[140:143], v[212:215], v[76:79]
	v_mfma_f32_16x16x32_bf16 v[128:131], v[136:139], v[168:171], v[128:131]
	v_mfma_f32_16x16x32_bf16 v[124:127], v[144:147], v[168:171], v[124:127]
	v_mfma_f32_16x16x32_bf16 v[112:115], v[136:139], v[176:179], v[112:115]
	v_mfma_f32_16x16x32_bf16 v[108:111], v[144:147], v[176:179], v[108:111]
	v_mfma_f32_16x16x32_bf16 v[96:99], v[136:139], v[184:187], v[96:99]
	v_mfma_f32_16x16x32_bf16 v[92:95], v[144:147], v[184:187], v[92:95]
	v_mfma_f32_16x16x32_bf16 v[80:83], v[136:139], v[216:219], v[80:83]
	v_mfma_f32_16x16x32_bf16 v[76:79], v[144:147], v[216:219], v[76:79]
	s_setprio 0
	s_setprio 1
	v_mfma_f32_16x16x32_bf16 v[120:123], v[148:151], v[164:167], v[120:123]
	v_mfma_f32_16x16x32_bf16 v[116:119], v[156:159], v[164:167], v[116:119]
	v_mfma_f32_16x16x32_bf16 v[104:107], v[148:151], v[172:175], v[104:107]
	v_mfma_f32_16x16x32_bf16 v[100:103], v[156:159], v[172:175], v[100:103]
	v_mfma_f32_16x16x32_bf16 v[88:91], v[148:151], v[180:183], v[88:91]
	v_mfma_f32_16x16x32_bf16 v[84:87], v[156:159], v[180:183], v[84:87]
	v_mfma_f32_16x16x32_bf16 v[72:75], v[148:151], v[212:215], v[72:75]
	v_mfma_f32_16x16x32_bf16 v[68:71], v[156:159], v[212:215], v[68:71]
	v_mfma_f32_16x16x32_bf16 v[120:123], v[152:155], v[168:171], v[120:123]
	v_mfma_f32_16x16x32_bf16 v[116:119], v[160:163], v[168:171], v[116:119]
	v_mfma_f32_16x16x32_bf16 v[104:107], v[152:155], v[176:179], v[104:107]
	v_mfma_f32_16x16x32_bf16 v[100:103], v[160:163], v[176:179], v[100:103]
	v_mfma_f32_16x16x32_bf16 v[88:91], v[152:155], v[184:187], v[88:91]
	v_mfma_f32_16x16x32_bf16 v[84:87], v[160:163], v[184:187], v[84:87]
	v_mfma_f32_16x16x32_bf16 v[72:75], v[152:155], v[216:219], v[72:75]
	v_mfma_f32_16x16x32_bf16 v[68:71], v[160:163], v[216:219], v[68:71]
	s_setprio 0
	s_barrier
; #define PG8_STAGE(bufoff, gbase, voff) do { _Pragma("unroll") for (int _i = 0; _i < 2; ++_i) \
;         __builtin_amdgcn_global_load_lds((const unsigned*)((const char*)(gbase) + (voff)[_i]), (LAS unsigned*)(lds + (bufoff) + ldsw + _i * 8192), 16, 0, 0); } while (0)
; #define PG8_LDA(dst, b, h) do { _Pragma("unroll") for (int m = 0; m < 4; ++m) _Pragma("unroll") for (int k = 0; k < 2; ++k) dst[m][k] = *(const LAS bf16x8*)(lds + PG8_SA(b, h) + aoff + m * 2048 + k * 1024); } while (0)
; #define PG8_MMA(ai, bj, At, Bt) do { __builtin_amdgcn_s_setprio(1); _Pragma("unroll") for (int m = 0; m < 4; ++m) _Pragma("unroll") for (int n = 0; n < 2; ++n) _Pragma("unroll") for (int k = 0; k < 2; ++k) \
;         acc[ai][bj][m][n] = __builtin_amdgcn_mfma_f32_16x16x32_bf16(Bt[n][k], At[m][k], acc[ai][bj][m][n], 0, 0, 0); __builtin_amdgcn_s_setprio(0); } while (0)
; #define PG8_WAIT_V(n) asm volatile("s_waitcnt vmcnt(" #n ")" ::: "memory")
; #define PG8_WAIT_L(n) asm volatile("s_waitcnt lgkmcnt(" #n ")" ::: "memory")
; #define PG8_BAR __builtin_amdgcn_s_barrier()
; #define PG8_SCHED __builtin_amdgcn_sched_barrier(0)
; template <class Epi>
; __device__ __forceinline__ void gemm_phase(LAS unsigned char* lds, const Gemm g, const StaticOrder& S, const Epi& E) {
;     ...
;             PG8_LDA(At, 1, 1); PG8_STAGE(PG8_SB(1, 0), b3, voffB); PG8_STAGE(PG8_SB(1, 1), b3 + hstepB, voffB); PG8_STAGE(PG8_SA(1, 0), a3, voffA);
;             PG8_WAIT_V(8); PG8_WAIT_L(0); PG8_BAR; PG8_MMA(1, 0, At, B0); PG8_MMA(1, 1, At, B1); PG8_BAR; PG8_SCHED;
;         }
;         if (wr == 0) PG8_BAR;
	s_add_i32 s52, s72, s58
	v_lshl_add_u64 v[196:197], v[196:197], 0, s[30:31]
	s_mov_b32 m0, s52
	ds_read_b128 v[164:167], v242 offset:49152
	ds_read_b128 v[168:171], v242 offset:50176
	ds_read_b128 v[172:175], v242 offset:51200
	ds_read_b128 v[176:179], v242 offset:52224
	ds_read_b128 v[180:183], v242 offset:53248
	ds_read_b128 v[184:187], v242 offset:54272
	ds_read_b128 v[212:215], v242 offset:55296
	ds_read_b128 v[216:219], v242 offset:56320
	global_load_lds_dwordx4 v[196:197], off
	s_add_i32 m0, s52, 0x2000
	s_add_u32 s22, s22, 0x10080
	v_lshl_add_u64 v[196:197], v[198:199], 0, s[30:31]
	s_addc_u32 s23, s23, 0
	s_add_i32 s52, s73, s58
	global_load_lds_dwordx4 v[196:197], off
	v_lshl_add_u64 v[196:197], s[22:23], 0, v[190:191]
	s_mov_b32 m0, s52
	s_nop 0
	global_load_lds_dwordx4 v[196:197], off
	v_lshl_add_u64 v[196:197], s[22:23], 0, v[0:1]
	s_add_i32 m0, s52, 0x2000
	s_nop 0
	global_load_lds_dwordx4 v[196:197], off
	v_lshl_add_u64 v[196:197], v[220:221], 0, s[30:31]
	s_mov_b32 m0, s28
	s_nop 0
	global_load_lds_dwordx4 v[196:197], off
	v_lshl_add_u64 v[196:197], v[222:223], 0, s[30:31]
	s_mov_b32 m0, s63
	s_nop 0
	global_load_lds_dwordx4 v[196:197], off
	s_waitcnt vmcnt(8)
	s_waitcnt lgkmcnt(0)
	s_barrier
	s_setprio 1
	s_waitcnt lgkmcnt(0)
	v_mfma_f32_16x16x32_bf16 v[64:67], v[132:135], v[164:167], v[64:67]
	v_mfma_f32_16x16x32_bf16 v[60:63], v[140:143], v[164:167], v[60:63]
	v_mfma_f32_16x16x32_bf16 v[48:51], v[132:135], v[172:175], v[48:51]
	v_mfma_f32_16x16x32_bf16 v[44:47], v[140:143], v[172:175], v[44:47]
	v_mfma_f32_16x16x32_bf16 v[32:35], v[132:135], v[180:183], v[32:35]
	v_mfma_f32_16x16x32_bf16 v[28:31], v[140:143], v[180:183], v[28:31]
	v_mfma_f32_16x16x32_bf16 v[16:19], v[132:135], v[212:215], v[16:19]
	v_mfma_f32_16x16x32_bf16 v[12:15], v[140:143], v[212:215], v[12:15]
	v_mfma_f32_16x16x32_bf16 v[64:67], v[136:139], v[168:171], v[64:67]
	v_mfma_f32_16x16x32_bf16 v[60:63], v[144:147], v[168:171], v[60:63]
	v_mfma_f32_16x16x32_bf16 v[48:51], v[136:139], v[176:179], v[48:51]
	v_mfma_f32_16x16x32_bf16 v[44:47], v[144:147], v[176:179], v[44:47]
	v_mfma_f32_16x16x32_bf16 v[32:35], v[136:139], v[184:187], v[32:35]
	v_mfma_f32_16x16x32_bf16 v[28:31], v[144:147], v[184:187], v[28:31]
	v_mfma_f32_16x16x32_bf16 v[16:19], v[136:139], v[216:219], v[16:19]
	v_mfma_f32_16x16x32_bf16 v[12:15], v[144:147], v[216:219], v[12:15]
	s_setprio 0
	s_setprio 1
	v_mfma_f32_16x16x32_bf16 v[56:59], v[148:151], v[164:167], v[56:59]
	v_mfma_f32_16x16x32_bf16 v[52:55], v[156:159], v[164:167], v[52:55]
	v_mfma_f32_16x16x32_bf16 v[40:43], v[148:151], v[172:175], v[40:43]
	v_mfma_f32_16x16x32_bf16 v[36:39], v[156:159], v[172:175], v[36:39]
	v_mfma_f32_16x16x32_bf16 v[24:27], v[148:151], v[180:183], v[24:27]
	v_mfma_f32_16x16x32_bf16 v[20:23], v[156:159], v[180:183], v[20:23]
	v_mfma_f32_16x16x32_bf16 v[8:11], v[148:151], v[212:215], v[8:11]
	v_mfma_f32_16x16x32_bf16 v[4:7], v[156:159], v[212:215], v[4:7]
	v_mfma_f32_16x16x32_bf16 v[56:59], v[152:155], v[168:171], v[56:59]
	v_mfma_f32_16x16x32_bf16 v[52:55], v[160:163], v[168:171], v[52:55]
	v_mfma_f32_16x16x32_bf16 v[40:43], v[152:155], v[176:179], v[40:43]
	v_mfma_f32_16x16x32_bf16 v[36:39], v[160:163], v[176:179], v[36:39]
	v_mfma_f32_16x16x32_bf16 v[24:27], v[152:155], v[184:187], v[24:27]
	v_mfma_f32_16x16x32_bf16 v[20:23], v[160:163], v[184:187], v[20:23]
	v_mfma_f32_16x16x32_bf16 v[8:11], v[152:155], v[216:219], v[8:11]
	v_mfma_f32_16x16x32_bf16 v[4:7], v[160:163], v[216:219], v[4:7]
	s_add_i32 s71, s71, 2
	s_add_u32 s50, s50, 0x100
	s_addc_u32 s51, s51, 0
	s_add_u32 s69, s69, 0x100
	s_addc_u32 s70, s70, 0
	s_cmp_gt_u32 s71, 13
	s_setprio 0
	s_barrier
	s_cbranch_scc0 .LBB0_1005
	s_and_b64 vcc, exec, s[14:15]
	s_cbranch_vccz .LBB0_1008
	s_barrier

; #define PG8_STAGE(bufoff, gbase, voff) do { _Pragma("unroll") for (int _i = 0; _i < 2; ++_i) \
;         __builtin_amdgcn_global_load_lds((const unsigned*)((const char*)(gbase) + (voff)[_i]), (LAS unsigned*)(lds + (bufoff) + ldsw + _i * 8192), 16, 0, 0); } while (0)
; #define PG8_LDA(dst, b, h) do { _Pragma("unroll") for (int m = 0; m < 4; ++m) _Pragma("unroll") for (int k = 0; k < 2; ++k) dst[m][k] = *(const LAS bf16x8*)(lds + PG8_SA(b, h) + aoff + m * 2048 + k * 1024); } while (0)
; #define PG8_LDB(dst, b, h) do { _Pragma("unroll") for (int n = 0; n < 2; ++n) _Pragma("unroll") for (int k = 0; k < 2; ++k) dst[n][k] = *(const LAS bf16x8*)(lds + PG8_SB(b, h) + boff + n * 2048 + k * 1024); } while (0)
; #define PG8_MMA(ai, bj, At, Bt) do { __builtin_amdgcn_s_setprio(1); _Pragma("unroll") for (int m = 0; m < 4; ++m) _Pragma("unroll") for (int n = 0; n < 2; ++n) _Pragma("unroll") for (int k = 0; k < 2; ++k) \
;         acc[ai][bj][m][n] = __builtin_amdgcn_mfma_f32_16x16x32_bf16(Bt[n][k], At[m][k], acc[ai][bj][m][n], 0, 0, 0); __builtin_amdgcn_s_setprio(0); } while (0)
; #define PG8_WAIT_V(n) asm volatile("s_waitcnt vmcnt(" #n ")" ::: "memory")
; #define PG8_WAIT_L(n) asm volatile("s_waitcnt lgkmcnt(" #n ")" ::: "memory")
; #define PG8_BAR __builtin_amdgcn_s_barrier()
; #define PG8_SCHED __builtin_amdgcn_sched_barrier(0)
; template <class Epi>
; __device__ __forceinline__ void gemm_phase(LAS unsigned char* lds, const Gemm g, const StaticOrder& S, const Epi& E) {
;     ...
;         for (int t = 0; t < nt; t += 2) {
;             const bool last = (t == nt - 2);
;             const char* a1 = cA + (size_t)(t + 1) * kstep;
;             const char* a2 = last ? nA : cA + (size_t)(t + 2) * kstep; const char* b2 = last ? nB : cB + (size_t)(t + 2) * kstep;
;             const char* a3 = a2 + kstep; const char* b3 = b2 + kstep;
;             PG8_LDB(B0, 0, 0); PG8_LDB(B1, 0, 1); PG8_SCHED; PG8_LDA(At, 0, 0); PG8_STAGE(PG8_SA(1, 1), a1 + hstepA, voffA);
;             PG8_WAIT_V(8); PG8_WAIT_L(0); PG8_BAR; PG8_MMA(0, 0, At, B0); PG8_MMA(0, 1, At, B1); PG8_BAR; PG8_SCHED;
;             PG8_LDA(At, 0, 1); PG8_STAGE(PG8_SB(0, 0), b2, voffB); PG8_STAGE(PG8_SB(0, 1), b2 + hstepB, voffB); PG8_STAGE(PG8_SA(0, 0), a2, voffA);
;             PG8_WAIT_V(8); PG8_WAIT_L(0); PG8_BAR; PG8_MMA(1, 0, At, B0); PG8_MMA(1, 1, At, B1); PG8_BAR; PG8_SCHED;
.LBB0_1088:
	s_add_u32 s22, s46, 0xfffc0080
	s_addc_u32 s23, s47, -1
	s_add_i32 s68, 0, 0x10000
	s_cmp_eq_u32 s67, 12
	s_cselect_b32 s49, s35, s23
	s_cselect_b32 s48, s63, s22
	s_cselect_b32 s23, s15, s66
	s_cselect_b32 s22, s64, s65
	s_add_i32 s70, 0, 0x14000
	v_add_u32_e32 v154, s68, v158
	v_add_u32_e32 v161, s70, v158
	ds_read_b128 v[142:145], v154
	ds_read_b128 v[146:149], v154 offset:1024
	ds_read_b128 v[150:153], v154 offset:2048
	ds_read_b128 v[154:157], v154 offset:3072
	ds_read_b128 v[162:165], v161
	ds_read_b128 v[166:169], v161 offset:1024
	ds_read_b128 v[170:173], v161 offset:2048
	ds_read_b128 v[174:177], v161 offset:3072
	v_lshl_add_u64 v[198:199], s[46:47], 0, v[138:139]
	s_add_i32 m0, s55, 0xc000
	ds_read_b128 v[178:181], v160
	ds_read_b128 v[182:185], v160 offset:1024
	ds_read_b128 v[186:189], v160 offset:2048
	ds_read_b128 v[190:193], v160 offset:3072
	ds_read_b128 v[194:197], v160 offset:4096
	ds_read_b128 v[210:213], v160 offset:5120
	ds_read_b128 v[214:217], v160 offset:6144
	ds_read_b128 v[218:221], v160 offset:7168
	global_load_lds_dwordx4 v[198:199], off
	v_lshl_add_u64 v[198:199], s[46:47], 0, v[140:141]
	s_add_i32 m0, s55, 0xe000
	s_nop 0
	global_load_lds_dwordx4 v[198:199], off
	s_waitcnt vmcnt(8)
	s_waitcnt lgkmcnt(0)
	s_barrier
	s_setprio 1
	s_waitcnt lgkmcnt(0)
	v_mfma_f32_16x16x32_bf16 v[128:131], v[142:145], v[178:181], v[128:131]
	v_mfma_f32_16x16x32_bf16 v[120:123], v[150:153], v[178:181], v[120:123]
	v_mfma_f32_16x16x32_bf16 v[108:111], v[142:145], v[186:189], v[108:111]
	v_mfma_f32_16x16x32_bf16 v[100:103], v[150:153], v[186:189], v[100:103]
	v_mfma_f32_16x16x32_bf16 v[92:95], v[142:145], v[194:197], v[92:95]
	v_mfma_f32_16x16x32_bf16 v[84:87], v[150:153], v[194:197], v[84:87]
	v_mfma_f32_16x16x32_bf16 v[76:79], v[142:145], v[214:217], v[76:79]
	v_mfma_f32_16x16x32_bf16 v[68:71], v[150:153], v[214:217], v[68:71]
	v_mfma_f32_16x16x32_bf16 v[128:131], v[146:149], v[182:185], v[128:131]
	v_mfma_f32_16x16x32_bf16 v[120:123], v[154:157], v[182:185], v[120:123]
	v_mfma_f32_16x16x32_bf16 v[108:111], v[146:149], v[190:193], v[108:111]
	v_mfma_f32_16x16x32_bf16 v[100:103], v[154:157], v[190:193], v[100:103]
	v_mfma_f32_16x16x32_bf16 v[92:95], v[146:149], v[210:213], v[92:95]
	v_mfma_f32_16x16x32_bf16 v[84:87], v[154:157], v[210:213], v[84:87]
	v_mfma_f32_16x16x32_bf16 v[76:79], v[146:149], v[218:221], v[76:79]
	v_mfma_f32_16x16x32_bf16 v[68:71], v[154:157], v[218:221], v[68:71]
	s_setprio 0
	s_setprio 1
	v_mfma_f32_16x16x32_bf16 v[124:127], v[162:165], v[178:181], v[124:127]
	v_mfma_f32_16x16x32_bf16 v[116:119], v[170:173], v[178:181], v[116:119]
	v_mfma_f32_16x16x32_bf16 v[112:115], v[162:165], v[186:189], v[112:115]
	v_mfma_f32_16x16x32_bf16 v[104:107], v[170:173], v[186:189], v[104:107]
	v_mfma_f32_16x16x32_bf16 v[96:99], v[162:165], v[194:197], v[96:99]
	v_mfma_f32_16x16x32_bf16 v[88:91], v[170:173], v[194:197], v[88:91]
	v_mfma_f32_16x16x32_bf16 v[80:83], v[162:165], v[214:217], v[80:83]
	v_mfma_f32_16x16x32_bf16 v[72:75], v[170:173], v[214:217], v[72:75]
	v_mfma_f32_16x16x32_bf16 v[124:127], v[166:169], v[182:185], v[124:127]
	v_mfma_f32_16x16x32_bf16 v[116:119], v[174:177], v[182:185], v[116:119]
	v_mfma_f32_16x16x32_bf16 v[112:115], v[166:169], v[190:193], v[112:115]
	v_mfma_f32_16x16x32_bf16 v[104:107], v[174:177], v[190:193], v[104:107]
	v_mfma_f32_16x16x32_bf16 v[96:99], v[166:169], v[210:213], v[96:99]
	v_mfma_f32_16x16x32_bf16 v[88:91], v[174:177], v[210:213], v[88:91]
	v_mfma_f32_16x16x32_bf16 v[80:83], v[166:169], v[218:221], v[80:83]
	v_mfma_f32_16x16x32_bf16 v[72:75], v[174:177], v[218:221], v[72:75]
	s_setprio 0
	s_barrier
	s_add_i32 s68, s68, s54
	v_lshl_add_u64 v[198:199], s[22:23], 0, v[134:135]
	s_mov_b32 m0, s68
	ds_read_b128 v[178:181], v160 offset:16384
	ds_read_b128 v[182:185], v160 offset:17408
	ds_read_b128 v[186:189], v160 offset:18432
	ds_read_b128 v[190:193], v160 offset:19456
	ds_read_b128 v[194:197], v160 offset:20480
	ds_read_b128 v[210:213], v160 offset:21504
	ds_read_b128 v[214:217], v160 offset:22528
	ds_read_b128 v[218:221], v160 offset:23552
	global_load_lds_dwordx4 v[198:199], off
	s_add_i32 m0, s68, 0x2000
	s_add_u32 s68, s22, 0x10000
	v_lshl_add_u64 v[222:223], s[22:23], 0, v[0:1]
	s_addc_u32 s69, s23, 0
	s_add_i32 s70, s70, s54
	global_load_lds_dwordx4 v[222:223], off
	v_lshl_add_u64 v[224:225], s[68:69], 0, v[134:135]
	s_mov_b32 m0, s70
	v_lshl_add_u64 v[226:227], s[48:49], 0, v[132:133]
	global_load_lds_dwordx4 v[224:225], off
	v_lshl_add_u64 v[224:225], s[68:69], 0, v[0:1]
	s_add_i32 m0, s70, 0x2000
	s_nop 0
	global_load_lds_dwordx4 v[224:225], off
	v_lshl_add_u64 v[224:225], s[48:49], 0, v[136:137]
	s_mov_b32 m0, s55
	s_nop 0
	global_load_lds_dwordx4 v[224:225], off
	s_mov_b32 m0, s56
	s_nop 0
	global_load_lds_dwordx4 v[226:227], off
	s_waitcnt vmcnt(8)
	s_waitcnt lgkmcnt(0)
	s_barrier
; #define PG8_STAGE(bufoff, gbase, voff) do { _Pragma("unroll") for (int _i = 0; _i < 2; ++_i) \
;         __builtin_amdgcn_global_load_lds((const unsigned*)((const char*)(gbase) + (voff)[_i]), (LAS unsigned*)(lds + (bufoff) + ldsw + _i * 8192), 16, 0, 0); } while (0)
; #define PG8_LDA(dst, b, h) do { _Pragma("unroll") for (int m = 0; m < 4; ++m) _Pragma("unroll") for (int k = 0; k < 2; ++k) dst[m][k] = *(const LAS bf16x8*)(lds + PG8_SA(b, h) + aoff + m * 2048 + k * 1024); } while (0)
; #define PG8_LDB(dst, b, h) do { _Pragma("unroll") for (int n = 0; n < 2; ++n) _Pragma("unroll") for (int k = 0; k < 2; ++k) dst[n][k] = *(const LAS bf16x8*)(lds + PG8_SB(b, h) + boff + n * 2048 + k * 1024); } while (0)
; #define PG8_MMA(ai, bj, At, Bt) do { __builtin_amdgcn_s_setprio(1); _Pragma("unroll") for (int m = 0; m < 4; ++m) _Pragma("unroll") for (int n = 0; n < 2; ++n) _Pragma("unroll") for (int k = 0; k < 2; ++k) \
;         acc[ai][bj][m][n] = __builtin_amdgcn_mfma_f32_16x16x32_bf16(Bt[n][k], At[m][k], acc[ai][bj][m][n], 0, 0, 0); __builtin_amdgcn_s_setprio(0); } while (0)
; #define PG8_WAIT_V(n) asm volatile("s_waitcnt vmcnt(" #n ")" ::: "memory")
; #define PG8_WAIT_L(n) asm volatile("s_waitcnt lgkmcnt(" #n ")" ::: "memory")
; #define PG8_BAR __builtin_amdgcn_s_barrier()
; #define PG8_SCHED __builtin_amdgcn_sched_barrier(0)
; template <class Epi>
; __device__ __forceinline__ void gemm_phase(LAS unsigned char* lds, const Gemm g, const StaticOrder& S, const Epi& E) {
;     ...
;             PG8_WAIT_V(8); PG8_WAIT_L(0); PG8_BAR; PG8_MMA(1, 0, At, B0); PG8_MMA(1, 1, At, B1); PG8_BAR; PG8_SCHED;
;             PG8_LDB(B0, 1, 0); PG8_LDB(B1, 1, 1); PG8_SCHED; PG8_LDA(At, 1, 0); PG8_STAGE(PG8_SA(0, 1), a2 + hstepA, voffA);
;             PG8_WAIT_V(8); PG8_WAIT_L(0); PG8_BAR; PG8_MMA(0, 0, At, B0); PG8_MMA(0, 1, At, B1); PG8_BAR; PG8_SCHED;
	s_setprio 1
	s_waitcnt lgkmcnt(0)
	v_mfma_f32_16x16x32_bf16 v[60:63], v[142:145], v[178:181], v[60:63]
	v_mfma_f32_16x16x32_bf16 v[52:55], v[150:153], v[178:181], v[52:55]
	v_mfma_f32_16x16x32_bf16 v[44:47], v[142:145], v[186:189], v[44:47]
	v_mfma_f32_16x16x32_bf16 v[36:39], v[150:153], v[186:189], v[36:39]
	v_mfma_f32_16x16x32_bf16 v[28:31], v[142:145], v[194:197], v[28:31]
	v_mfma_f32_16x16x32_bf16 v[20:23], v[150:153], v[194:197], v[20:23]
	v_mfma_f32_16x16x32_bf16 v[4:7], v[142:145], v[214:217], v[4:7]
	v_mfma_f32_16x16x32_bf16 v[12:15], v[150:153], v[214:217], v[12:15]
	v_mfma_f32_16x16x32_bf16 v[60:63], v[146:149], v[182:185], v[60:63]
	v_mfma_f32_16x16x32_bf16 v[52:55], v[154:157], v[182:185], v[52:55]
	v_mfma_f32_16x16x32_bf16 v[44:47], v[146:149], v[190:193], v[44:47]
	v_mfma_f32_16x16x32_bf16 v[36:39], v[154:157], v[190:193], v[36:39]
	v_mfma_f32_16x16x32_bf16 v[28:31], v[146:149], v[210:213], v[28:31]
	v_mfma_f32_16x16x32_bf16 v[20:23], v[154:157], v[210:213], v[20:23]
	v_mfma_f32_16x16x32_bf16 v[4:7], v[146:149], v[218:221], v[4:7]
	v_mfma_f32_16x16x32_bf16 v[12:15], v[154:157], v[218:221], v[12:15]
	s_setprio 0
	s_setprio 1
	v_mfma_f32_16x16x32_bf16 v[64:67], v[162:165], v[178:181], v[64:67]
	v_mfma_f32_16x16x32_bf16 v[56:59], v[170:173], v[178:181], v[56:59]
	v_mfma_f32_16x16x32_bf16 v[48:51], v[162:165], v[186:189], v[48:51]
	v_mfma_f32_16x16x32_bf16 v[40:43], v[170:173], v[186:189], v[40:43]
	v_mfma_f32_16x16x32_bf16 v[32:35], v[162:165], v[194:197], v[32:35]
	v_mfma_f32_16x16x32_bf16 v[24:27], v[170:173], v[194:197], v[24:27]
	v_mfma_f32_16x16x32_bf16 v[8:11], v[162:165], v[214:217], v[8:11]
	v_mfma_f32_16x16x32_bf16 v[16:19], v[170:173], v[214:217], v[16:19]
	v_mfma_f32_16x16x32_bf16 v[64:67], v[166:169], v[182:185], v[64:67]
	v_mfma_f32_16x16x32_bf16 v[56:59], v[174:177], v[182:185], v[56:59]
	v_mfma_f32_16x16x32_bf16 v[48:51], v[166:169], v[190:193], v[48:51]
	v_mfma_f32_16x16x32_bf16 v[40:43], v[174:177], v[190:193], v[40:43]
	v_mfma_f32_16x16x32_bf16 v[32:35], v[166:169], v[210:213], v[32:35]
	v_mfma_f32_16x16x32_bf16 v[24:27], v[174:177], v[210:213], v[24:27]
	v_mfma_f32_16x16x32_bf16 v[8:11], v[166:169], v[218:221], v[8:11]
	v_mfma_f32_16x16x32_bf16 v[16:19], v[174:177], v[218:221], v[16:19]
	s_setprio 0
	s_barrier
	s_add_i32 s68, 0, 0x18000
	s_add_i32 s69, 0, 0x1c000
	v_add_u32_e32 v154, s68, v158
	v_add_u32_e32 v161, s69, v158
	ds_read_b128 v[142:145], v154
	ds_read_b128 v[146:149], v154 offset:1024
	ds_read_b128 v[150:153], v154 offset:2048
	ds_read_b128 v[154:157], v154 offset:3072
	ds_read_b128 v[162:165], v161
	ds_read_b128 v[166:169], v161 offset:1024
	ds_read_b128 v[170:173], v161 offset:2048
	ds_read_b128 v[174:177], v161 offset:3072
	s_add_u32 s48, s48, 0x40000
	s_addc_u32 s49, s49, 0
	s_mov_b32 m0, s57
	v_lshl_add_u64 v[228:229], s[48:49], 0, v[136:137]
	ds_read_b128 v[178:181], v160 offset:32768
	ds_read_b128 v[182:185], v160 offset:33792
	ds_read_b128 v[186:189], v160 offset:34816
	ds_read_b128 v[190:193], v160 offset:35840
	ds_read_b128 v[194:197], v160 offset:36864
	ds_read_b128 v[210:213], v160 offset:37888
	ds_read_b128 v[214:217], v160 offset:38912
	ds_read_b128 v[218:221], v160 offset:39936
	global_load_lds_dwordx4 v[228:229], off
	v_lshl_add_u64 v[228:229], s[48:49], 0, v[132:133]
	s_mov_b32 m0, s58
	s_nop 0
	global_load_lds_dwordx4 v[228:229], off
	s_waitcnt vmcnt(8)
	s_waitcnt lgkmcnt(0)
	s_barrier
	s_setprio 1
	s_waitcnt lgkmcnt(0)
	v_mfma_f32_16x16x32_bf16 v[128:131], v[142:145], v[178:181], v[128:131]
	v_mfma_f32_16x16x32_bf16 v[120:123], v[150:153], v[178:181], v[120:123]
	v_mfma_f32_16x16x32_bf16 v[108:111], v[142:145], v[186:189], v[108:111]
	v_mfma_f32_16x16x32_bf16 v[100:103], v[150:153], v[186:189], v[100:103]
	v_mfma_f32_16x16x32_bf16 v[92:95], v[142:145], v[194:197], v[92:95]
	v_mfma_f32_16x16x32_bf16 v[84:87], v[150:153], v[194:197], v[84:87]
	v_mfma_f32_16x16x32_bf16 v[76:79], v[142:145], v[214:217], v[76:79]
	v_mfma_f32_16x16x32_bf16 v[68:71], v[150:153], v[214:217], v[68:71]
	v_mfma_f32_16x16x32_bf16 v[128:131], v[146:149], v[182:185], v[128:131]
	v_mfma_f32_16x16x32_bf16 v[120:123], v[154:157], v[182:185], v[120:123]
	v_mfma_f32_16x16x32_bf16 v[108:111], v[146:149], v[190:193], v[108:111]
	v_mfma_f32_16x16x32_bf16 v[100:103], v[154:157], v[190:193], v[100:103]
	v_mfma_f32_16x16x32_bf16 v[92:95], v[146:149], v[210:213], v[92:95]
	v_mfma_f32_16x16x32_bf16 v[84:87], v[154:157], v[210:213], v[84:87]
	v_mfma_f32_16x16x32_bf16 v[76:79], v[146:149], v[218:221], v[76:79]
	v_mfma_f32_16x16x32_bf16 v[68:71], v[154:157], v[218:221], v[68:71]
	s_setprio 0
	s_setprio 1
	v_mfma_f32_16x16x32_bf16 v[124:127], v[162:165], v[178:181], v[124:127]
	v_mfma_f32_16x16x32_bf16 v[116:119], v[170:173], v[178:181], v[116:119]
	v_mfma_f32_16x16x32_bf16 v[112:115], v[162:165], v[186:189], v[112:115]
	v_mfma_f32_16x16x32_bf16 v[104:107], v[170:173], v[186:189], v[104:107]
	v_mfma_f32_16x16x32_bf16 v[96:99], v[162:165], v[194:197], v[96:99]
	v_mfma_f32_16x16x32_bf16 v[88:91], v[170:173], v[194:197], v[88:91]
	v_mfma_f32_16x16x32_bf16 v[80:83], v[162:165], v[214:217], v[80:83]
	v_mfma_f32_16x16x32_bf16 v[72:75], v[170:173], v[214:217], v[72:75]
	v_mfma_f32_16x16x32_bf16 v[124:127], v[166:169], v[182:185], v[124:127]
	v_mfma_f32_16x16x32_bf16 v[116:119], v[174:177], v[182:185], v[116:119]
	v_mfma_f32_16x16x32_bf16 v[112:115], v[166:169], v[190:193], v[112:115]
	v_mfma_f32_16x16x32_bf16 v[104:107], v[174:177], v[190:193], v[104:107]
	v_mfma_f32_16x16x32_bf16 v[96:99], v[166:169], v[210:213], v[96:99]
	v_mfma_f32_16x16x32_bf16 v[88:91], v[174:177], v[210:213], v[88:91]
	v_mfma_f32_16x16x32_bf16 v[80:83], v[166:169], v[218:221], v[80:83]
	v_mfma_f32_16x16x32_bf16 v[72:75], v[174:177], v[218:221], v[72:75]
	s_setprio 0
	s_barrier
; #define PG8_STAGE(bufoff, gbase, voff) do { _Pragma("unroll") for (int _i = 0; _i < 2; ++_i) \
;         __builtin_amdgcn_global_load_lds((const unsigned*)((const char*)(gbase) + (voff)[_i]), (LAS unsigned*)(lds + (bufoff) + ldsw + _i * 8192), 16, 0, 0); } while (0)
; #define PG8_LDA(dst, b, h) do { _Pragma("unroll") for (int m = 0; m < 4; ++m) _Pragma("unroll") for (int k = 0; k < 2; ++k) dst[m][k] = *(const LAS bf16x8*)(lds + PG8_SA(b, h) + aoff + m * 2048 + k * 1024); } while (0)
; #define PG8_MMA(ai, bj, At, Bt) do { __builtin_amdgcn_s_setprio(1); _Pragma("unroll") for (int m = 0; m < 4; ++m) _Pragma("unroll") for (int n = 0; n < 2; ++n) _Pragma("unroll") for (int k = 0; k < 2; ++k) \
;         acc[ai][bj][m][n] = __builtin_amdgcn_mfma_f32_16x16x32_bf16(Bt[n][k], At[m][k], acc[ai][bj][m][n], 0, 0, 0); __builtin_amdgcn_s_setprio(0); } while (0)
; #define PG8_WAIT_V(n) asm volatile("s_waitcnt vmcnt(" #n ")" ::: "memory")
; #define PG8_WAIT_L(n) asm volatile("s_waitcnt lgkmcnt(" #n ")" ::: "memory")
; #define PG8_BAR __builtin_amdgcn_s_barrier()
; #define PG8_SCHED __builtin_amdgcn_sched_barrier(0)
; template <class Epi>
; __device__ __forceinline__ void gemm_phase(LAS unsigned char* lds, const Gemm g, const StaticOrder& S, const Epi& E) {
;     ...
;             PG8_LDA(At, 1, 1); PG8_STAGE(PG8_SB(1, 0), b3, voffB); PG8_STAGE(PG8_SB(1, 1), b3 + hstepB, voffB); PG8_STAGE(PG8_SA(1, 0), a3, voffA);
;             PG8_WAIT_V(8); PG8_WAIT_L(0); PG8_BAR; PG8_MMA(1, 0, At, B0); PG8_MMA(1, 1, At, B1); PG8_BAR; PG8_SCHED;
;         }
;         if (wr == 0) PG8_BAR;
	s_add_i32 s48, s68, s54
	v_lshl_add_u64 v[198:199], v[198:199], 0, s[30:31]
	s_mov_b32 m0, s48
	ds_read_b128 v[178:181], v160 offset:49152
	ds_read_b128 v[182:185], v160 offset:50176
	ds_read_b128 v[186:189], v160 offset:51200
	ds_read_b128 v[190:193], v160 offset:52224
	ds_read_b128 v[194:197], v160 offset:53248
	ds_read_b128 v[210:213], v160 offset:54272
	ds_read_b128 v[214:217], v160 offset:55296
	ds_read_b128 v[218:221], v160 offset:56320
	global_load_lds_dwordx4 v[198:199], off
	s_add_i32 m0, s48, 0x2000
	s_add_u32 s22, s22, 0x10080
	v_lshl_add_u64 v[198:199], v[222:223], 0, s[30:31]
	s_addc_u32 s23, s23, 0
	s_add_i32 s48, s69, s54
	global_load_lds_dwordx4 v[198:199], off
	v_lshl_add_u64 v[198:199], s[22:23], 0, v[134:135]
	s_mov_b32 m0, s48
	s_nop 0
	global_load_lds_dwordx4 v[198:199], off
	v_lshl_add_u64 v[198:199], s[22:23], 0, v[0:1]
	s_add_i32 m0, s48, 0x2000
	s_nop 0
	global_load_lds_dwordx4 v[198:199], off
	v_lshl_add_u64 v[198:199], v[224:225], 0, s[30:31]
	s_mov_b32 m0, s28
	s_nop 0
	global_load_lds_dwordx4 v[198:199], off
	v_lshl_add_u64 v[198:199], v[226:227], 0, s[30:31]
	s_mov_b32 m0, s59
	s_nop 0
	global_load_lds_dwordx4 v[198:199], off
	s_waitcnt vmcnt(8)
	s_waitcnt lgkmcnt(0)
	s_barrier
	s_setprio 1
	s_waitcnt lgkmcnt(0)
	v_mfma_f32_16x16x32_bf16 v[60:63], v[142:145], v[178:181], v[60:63]
	v_mfma_f32_16x16x32_bf16 v[52:55], v[150:153], v[178:181], v[52:55]
	v_mfma_f32_16x16x32_bf16 v[44:47], v[142:145], v[186:189], v[44:47]
	v_mfma_f32_16x16x32_bf16 v[36:39], v[150:153], v[186:189], v[36:39]
	v_mfma_f32_16x16x32_bf16 v[28:31], v[142:145], v[194:197], v[28:31]
	v_mfma_f32_16x16x32_bf16 v[20:23], v[150:153], v[194:197], v[20:23]
	v_mfma_f32_16x16x32_bf16 v[4:7], v[142:145], v[214:217], v[4:7]
	v_mfma_f32_16x16x32_bf16 v[12:15], v[150:153], v[214:217], v[12:15]
	v_mfma_f32_16x16x32_bf16 v[60:63], v[146:149], v[182:185], v[60:63]
	v_mfma_f32_16x16x32_bf16 v[52:55], v[154:157], v[182:185], v[52:55]
	v_mfma_f32_16x16x32_bf16 v[44:47], v[146:149], v[190:193], v[44:47]
	v_mfma_f32_16x16x32_bf16 v[36:39], v[154:157], v[190:193], v[36:39]
	v_mfma_f32_16x16x32_bf16 v[28:31], v[146:149], v[210:213], v[28:31]
	v_mfma_f32_16x16x32_bf16 v[20:23], v[154:157], v[210:213], v[20:23]
	v_mfma_f32_16x16x32_bf16 v[4:7], v[146:149], v[218:221], v[4:7]
	v_mfma_f32_16x16x32_bf16 v[12:15], v[154:157], v[218:221], v[12:15]
	s_setprio 0
	s_setprio 1
	v_mfma_f32_16x16x32_bf16 v[64:67], v[162:165], v[178:181], v[64:67]
	v_mfma_f32_16x16x32_bf16 v[56:59], v[170:173], v[178:181], v[56:59]
	v_mfma_f32_16x16x32_bf16 v[48:51], v[162:165], v[186:189], v[48:51]
	v_mfma_f32_16x16x32_bf16 v[40:43], v[170:173], v[186:189], v[40:43]
	v_mfma_f32_16x16x32_bf16 v[32:35], v[162:165], v[194:197], v[32:35]
	v_mfma_f32_16x16x32_bf16 v[24:27], v[170:173], v[194:197], v[24:27]
	v_mfma_f32_16x16x32_bf16 v[8:11], v[162:165], v[214:217], v[8:11]
	v_mfma_f32_16x16x32_bf16 v[16:19], v[170:173], v[214:217], v[16:19]
	v_mfma_f32_16x16x32_bf16 v[64:67], v[166:169], v[182:185], v[64:67]
	v_mfma_f32_16x16x32_bf16 v[56:59], v[174:177], v[182:185], v[56:59]
	v_mfma_f32_16x16x32_bf16 v[48:51], v[166:169], v[190:193], v[48:51]
	v_mfma_f32_16x16x32_bf16 v[40:43], v[174:177], v[190:193], v[40:43]
	v_mfma_f32_16x16x32_bf16 v[32:35], v[166:169], v[210:213], v[32:35]
	v_mfma_f32_16x16x32_bf16 v[24:27], v[174:177], v[210:213], v[24:27]
	v_mfma_f32_16x16x32_bf16 v[8:11], v[166:169], v[218:221], v[8:11]
	v_mfma_f32_16x16x32_bf16 v[16:19], v[174:177], v[218:221], v[16:19]
	s_add_i32 s67, s67, 2
	s_add_u32 s46, s46, 0x100
	s_addc_u32 s47, s47, 0
	s_add_u32 s65, s65, 0x100
	s_addc_u32 s66, s66, 0
	s_cmp_gt_u32 s67, 13
	s_setprio 0
	s_barrier
	s_cbranch_scc0 .LBB0_1088
	s_and_b64 vcc, exec, s[12:13]
	s_cbranch_vccz .LBB0_1091
	s_barrier

; #define PG8_STAGE(bufoff, gbase, voff) do { _Pragma("unroll") for (int _i = 0; _i < 2; ++_i) \
;         __builtin_amdgcn_global_load_lds((const unsigned*)((const char*)(gbase) + (voff)[_i]), (LAS unsigned*)(lds + (bufoff) + ldsw + _i * 8192), 16, 0, 0); } while (0)
; #define PG8_LDA(dst, b, h) do { _Pragma("unroll") for (int m = 0; m < 4; ++m) _Pragma("unroll") for (int k = 0; k < 2; ++k) dst[m][k] = *(const LAS bf16x8*)(lds + PG8_SA(b, h) + aoff + m * 2048 + k * 1024); } while (0)
; #define PG8_LDB(dst, b, h) do { _Pragma("unroll") for (int n = 0; n < 2; ++n) _Pragma("unroll") for (int k = 0; k < 2; ++k) dst[n][k] = *(const LAS bf16x8*)(lds + PG8_SB(b, h) + boff + n * 2048 + k * 1024); } while (0)
; #define PG8_MMA(ai, bj, At, Bt) do { __builtin_amdgcn_s_setprio(1); _Pragma("unroll") for (int m = 0; m < 4; ++m) _Pragma("unroll") for (int n = 0; n < 2; ++n) _Pragma("unroll") for (int k = 0; k < 2; ++k) \
;         acc[ai][bj][m][n] = __builtin_amdgcn_mfma_f32_16x16x32_bf16(Bt[n][k], At[m][k], acc[ai][bj][m][n], 0, 0, 0); __builtin_amdgcn_s_setprio(0); } while (0)
; #define PG8_WAIT_V(n) asm volatile("s_waitcnt vmcnt(" #n ")" ::: "memory")
; #define PG8_WAIT_L(n) asm volatile("s_waitcnt lgkmcnt(" #n ")" ::: "memory")
; #define PG8_BAR __builtin_amdgcn_s_barrier()
; #define PG8_SCHED __builtin_amdgcn_sched_barrier(0)
; template <class Epi>
; __device__ __forceinline__ void gemm_phase(LAS unsigned char* lds, const Gemm g, const StaticOrder& S, const Epi& E) {
;     ...
;         for (int t = 0; t < nt; t += 2) {
;             const bool last = (t == nt - 2);
;             const char* a1 = cA + (size_t)(t + 1) * kstep;
;             const char* a2 = last ? nA : cA + (size_t)(t + 2) * kstep; const char* b2 = last ? nB : cB + (size_t)(t + 2) * kstep;
;             const char* a3 = a2 + kstep; const char* b3 = b2 + kstep;
;             PG8_LDB(B0, 0, 0); PG8_LDB(B1, 0, 1); PG8_SCHED; PG8_LDA(At, 0, 0); PG8_STAGE(PG8_SA(1, 1), a1 + hstepA, voffA);
;             PG8_WAIT_V(8); PG8_WAIT_L(0); PG8_BAR; PG8_MMA(0, 0, At, B0); PG8_MMA(0, 1, At, B1); PG8_BAR; PG8_SCHED;
;             PG8_LDA(At, 0, 1); PG8_STAGE(PG8_SB(0, 0), b2, voffB); PG8_STAGE(PG8_SB(0, 1), b2 + hstepB, voffB); PG8_STAGE(PG8_SA(0, 0), a2, voffA);
;             PG8_WAIT_V(8); PG8_WAIT_L(0); PG8_BAR; PG8_MMA(1, 0, At, B0); PG8_MMA(1, 1, At, B1); PG8_BAR; PG8_SCHED;
.LBB0_1270:
	s_add_u32 s22, s56, 0xfffc0080
	s_addc_u32 s23, s57, -1
	s_add_i32 s74, 0, 0x10000
	s_cmp_eq_u32 s73, 12
	s_cselect_b32 s59, s47, s23
	s_cselect_b32 s58, s69, s22
	s_cselect_b32 s23, s45, s72
	s_cselect_b32 s22, s70, s71
	s_add_i32 s76, 0, 0x14000
	v_add_u32_e32 v144, s74, v180
	v_add_u32_e32 v170, s76, v180
	ds_read_b128 v[132:135], v144
	ds_read_b128 v[136:139], v144 offset:1024
	ds_read_b128 v[140:143], v144 offset:2048
	ds_read_b128 v[144:147], v144 offset:3072
	ds_read_b128 v[148:151], v170
	ds_read_b128 v[152:155], v170 offset:1024
	ds_read_b128 v[166:169], v170 offset:2048
	ds_read_b128 v[170:173], v170 offset:3072
	v_lshl_add_u64 v[178:179], s[56:57], 0, v[162:163]
	s_add_i32 m0, s53, 0xc000
	ds_read_b128 v[174:177], v182
	ds_read_b128 v[184:187], v182 offset:1024
	ds_read_b128 v[188:191], v182 offset:2048
	ds_read_b128 v[192:195], v182 offset:3072
	ds_read_b128 v[196:199], v182 offset:4096
	ds_read_b128 v[210:213], v182 offset:5120
	ds_read_b128 v[214:217], v182 offset:6144
	ds_read_b128 v[218:221], v182 offset:7168
	global_load_lds_dwordx4 v[178:179], off
	v_lshl_add_u64 v[178:179], s[56:57], 0, v[164:165]
	s_add_i32 m0, s53, 0xe000
	s_nop 0
	global_load_lds_dwordx4 v[178:179], off
	s_waitcnt vmcnt(8)
	s_waitcnt lgkmcnt(0)
	s_barrier
	s_setprio 1
	s_waitcnt lgkmcnt(0)
	v_mfma_f32_16x16x32_bf16 v[128:131], v[132:135], v[174:177], v[128:131]
	v_mfma_f32_16x16x32_bf16 v[124:127], v[140:143], v[174:177], v[124:127]
	v_mfma_f32_16x16x32_bf16 v[112:115], v[132:135], v[188:191], v[112:115]
	v_mfma_f32_16x16x32_bf16 v[108:111], v[140:143], v[188:191], v[108:111]
	v_mfma_f32_16x16x32_bf16 v[96:99], v[132:135], v[196:199], v[96:99]
	v_mfma_f32_16x16x32_bf16 v[92:95], v[140:143], v[196:199], v[92:95]
	v_mfma_f32_16x16x32_bf16 v[80:83], v[132:135], v[214:217], v[80:83]
	v_mfma_f32_16x16x32_bf16 v[76:79], v[140:143], v[214:217], v[76:79]
	v_mfma_f32_16x16x32_bf16 v[128:131], v[136:139], v[184:187], v[128:131]
	v_mfma_f32_16x16x32_bf16 v[124:127], v[144:147], v[184:187], v[124:127]
	v_mfma_f32_16x16x32_bf16 v[112:115], v[136:139], v[192:195], v[112:115]
	v_mfma_f32_16x16x32_bf16 v[108:111], v[144:147], v[192:195], v[108:111]
	v_mfma_f32_16x16x32_bf16 v[96:99], v[136:139], v[210:213], v[96:99]
	v_mfma_f32_16x16x32_bf16 v[92:95], v[144:147], v[210:213], v[92:95]
	v_mfma_f32_16x16x32_bf16 v[80:83], v[136:139], v[218:221], v[80:83]
	v_mfma_f32_16x16x32_bf16 v[76:79], v[144:147], v[218:221], v[76:79]
	s_setprio 0
	s_setprio 1
	v_mfma_f32_16x16x32_bf16 v[120:123], v[148:151], v[174:177], v[120:123]
	v_mfma_f32_16x16x32_bf16 v[116:119], v[166:169], v[174:177], v[116:119]
	v_mfma_f32_16x16x32_bf16 v[104:107], v[148:151], v[188:191], v[104:107]
	v_mfma_f32_16x16x32_bf16 v[100:103], v[166:169], v[188:191], v[100:103]
	v_mfma_f32_16x16x32_bf16 v[88:91], v[148:151], v[196:199], v[88:91]
	v_mfma_f32_16x16x32_bf16 v[84:87], v[166:169], v[196:199], v[84:87]
	v_mfma_f32_16x16x32_bf16 v[72:75], v[148:151], v[214:217], v[72:75]
	v_mfma_f32_16x16x32_bf16 v[68:71], v[166:169], v[214:217], v[68:71]
	v_mfma_f32_16x16x32_bf16 v[120:123], v[152:155], v[184:187], v[120:123]
	v_mfma_f32_16x16x32_bf16 v[116:119], v[170:173], v[184:187], v[116:119]
	v_mfma_f32_16x16x32_bf16 v[104:107], v[152:155], v[192:195], v[104:107]
	v_mfma_f32_16x16x32_bf16 v[100:103], v[170:173], v[192:195], v[100:103]
	v_mfma_f32_16x16x32_bf16 v[88:91], v[152:155], v[210:213], v[88:91]
	v_mfma_f32_16x16x32_bf16 v[84:87], v[170:173], v[210:213], v[84:87]
	v_mfma_f32_16x16x32_bf16 v[72:75], v[152:155], v[218:221], v[72:75]
	v_mfma_f32_16x16x32_bf16 v[68:71], v[170:173], v[218:221], v[68:71]
	s_setprio 0
	s_barrier
	s_add_i32 s74, s74, s64
	v_lshl_add_u64 v[178:179], s[22:23], 0, v[158:159]
	s_mov_b32 m0, s74
	ds_read_b128 v[174:177], v182 offset:16384
	ds_read_b128 v[184:187], v182 offset:17408
	ds_read_b128 v[188:191], v182 offset:18432
	ds_read_b128 v[192:195], v182 offset:19456
	ds_read_b128 v[196:199], v182 offset:20480
	ds_read_b128 v[210:213], v182 offset:21504
	ds_read_b128 v[214:217], v182 offset:22528
	ds_read_b128 v[218:221], v182 offset:23552
	global_load_lds_dwordx4 v[178:179], off
	s_add_i32 m0, s74, 0x2000
	s_add_u32 s74, s22, 0x10000
	v_lshl_add_u64 v[222:223], s[22:23], 0, v[0:1]
	s_addc_u32 s75, s23, 0
	s_add_i32 s76, s76, s64
	global_load_lds_dwordx4 v[222:223], off
	v_lshl_add_u64 v[224:225], s[74:75], 0, v[158:159]
	s_mov_b32 m0, s76
	v_lshl_add_u64 v[226:227], s[58:59], 0, v[156:157]
	global_load_lds_dwordx4 v[224:225], off
	v_lshl_add_u64 v[224:225], s[74:75], 0, v[0:1]
	s_add_i32 m0, s76, 0x2000
	s_nop 0
	global_load_lds_dwordx4 v[224:225], off
	v_lshl_add_u64 v[224:225], s[58:59], 0, v[160:161]
	s_mov_b32 m0, s53
	s_nop 0
	global_load_lds_dwordx4 v[224:225], off
	s_mov_b32 m0, s55
	s_nop 0
	global_load_lds_dwordx4 v[226:227], off
	s_waitcnt vmcnt(8)
	s_waitcnt lgkmcnt(0)
	s_barrier
; #define PG8_STAGE(bufoff, gbase, voff) do { _Pragma("unroll") for (int _i = 0; _i < 2; ++_i) \
;         __builtin_amdgcn_global_load_lds((const unsigned*)((const char*)(gbase) + (voff)[_i]), (LAS unsigned*)(lds + (bufoff) + ldsw + _i * 8192), 16, 0, 0); } while (0)
; #define PG8_LDA(dst, b, h) do { _Pragma("unroll") for (int m = 0; m < 4; ++m) _Pragma("unroll") for (int k = 0; k < 2; ++k) dst[m][k] = *(const LAS bf16x8*)(lds + PG8_SA(b, h) + aoff + m * 2048 + k * 1024); } while (0)
; #define PG8_LDB(dst, b, h) do { _Pragma("unroll") for (int n = 0; n < 2; ++n) _Pragma("unroll") for (int k = 0; k < 2; ++k) dst[n][k] = *(const LAS bf16x8*)(lds + PG8_SB(b, h) + boff + n * 2048 + k * 1024); } while (0)
; #define PG8_MMA(ai, bj, At, Bt) do { __builtin_amdgcn_s_setprio(1); _Pragma("unroll") for (int m = 0; m < 4; ++m) _Pragma("unroll") for (int n = 0; n < 2; ++n) _Pragma("unroll") for (int k = 0; k < 2; ++k) \
;         acc[ai][bj][m][n] = __builtin_amdgcn_mfma_f32_16x16x32_bf16(Bt[n][k], At[m][k], acc[ai][bj][m][n], 0, 0, 0); __builtin_amdgcn_s_setprio(0); } while (0)
; #define PG8_WAIT_V(n) asm volatile("s_waitcnt vmcnt(" #n ")" ::: "memory")
; #define PG8_WAIT_L(n) asm volatile("s_waitcnt lgkmcnt(" #n ")" ::: "memory")
; #define PG8_BAR __builtin_amdgcn_s_barrier()
; #define PG8_SCHED __builtin_amdgcn_sched_barrier(0)
; template <class Epi>
; __device__ __forceinline__ void gemm_phase(LAS unsigned char* lds, const Gemm g, const StaticOrder& S, const Epi& E) {
;     ...
;             PG8_WAIT_V(8); PG8_WAIT_L(0); PG8_BAR; PG8_MMA(1, 0, At, B0); PG8_MMA(1, 1, At, B1); PG8_BAR; PG8_SCHED;
;             PG8_LDB(B0, 1, 0); PG8_LDB(B1, 1, 1); PG8_SCHED; PG8_LDA(At, 1, 0); PG8_STAGE(PG8_SA(0, 1), a2 + hstepA, voffA);
;             PG8_WAIT_V(8); PG8_WAIT_L(0); PG8_BAR; PG8_MMA(0, 0, At, B0); PG8_MMA(0, 1, At, B1); PG8_BAR; PG8_SCHED;
	s_setprio 1
	s_waitcnt lgkmcnt(0)
	v_mfma_f32_16x16x32_bf16 v[64:67], v[132:135], v[174:177], v[64:67]
	v_mfma_f32_16x16x32_bf16 v[60:63], v[140:143], v[174:177], v[60:63]
	v_mfma_f32_16x16x32_bf16 v[48:51], v[132:135], v[188:191], v[48:51]
	v_mfma_f32_16x16x32_bf16 v[44:47], v[140:143], v[188:191], v[44:47]
	v_mfma_f32_16x16x32_bf16 v[32:35], v[132:135], v[196:199], v[32:35]
	v_mfma_f32_16x16x32_bf16 v[28:31], v[140:143], v[196:199], v[28:31]
	v_mfma_f32_16x16x32_bf16 v[16:19], v[132:135], v[214:217], v[16:19]
	v_mfma_f32_16x16x32_bf16 v[12:15], v[140:143], v[214:217], v[12:15]
	v_mfma_f32_16x16x32_bf16 v[64:67], v[136:139], v[184:187], v[64:67]
	v_mfma_f32_16x16x32_bf16 v[60:63], v[144:147], v[184:187], v[60:63]
	v_mfma_f32_16x16x32_bf16 v[48:51], v[136:139], v[192:195], v[48:51]
	v_mfma_f32_16x16x32_bf16 v[44:47], v[144:147], v[192:195], v[44:47]
	v_mfma_f32_16x16x32_bf16 v[32:35], v[136:139], v[210:213], v[32:35]
	v_mfma_f32_16x16x32_bf16 v[28:31], v[144:147], v[210:213], v[28:31]
	v_mfma_f32_16x16x32_bf16 v[16:19], v[136:139], v[218:221], v[16:19]
	v_mfma_f32_16x16x32_bf16 v[12:15], v[144:147], v[218:221], v[12:15]
	s_setprio 0
	s_setprio 1
	v_mfma_f32_16x16x32_bf16 v[56:59], v[148:151], v[174:177], v[56:59]
	v_mfma_f32_16x16x32_bf16 v[52:55], v[166:169], v[174:177], v[52:55]
	v_mfma_f32_16x16x32_bf16 v[40:43], v[148:151], v[188:191], v[40:43]
	v_mfma_f32_16x16x32_bf16 v[36:39], v[166:169], v[188:191], v[36:39]
	v_mfma_f32_16x16x32_bf16 v[24:27], v[148:151], v[196:199], v[24:27]
	v_mfma_f32_16x16x32_bf16 v[20:23], v[166:169], v[196:199], v[20:23]
	v_mfma_f32_16x16x32_bf16 v[8:11], v[148:151], v[214:217], v[8:11]
	v_mfma_f32_16x16x32_bf16 v[4:7], v[166:169], v[214:217], v[4:7]
	v_mfma_f32_16x16x32_bf16 v[56:59], v[152:155], v[184:187], v[56:59]
	v_mfma_f32_16x16x32_bf16 v[52:55], v[170:173], v[184:187], v[52:55]
	v_mfma_f32_16x16x32_bf16 v[40:43], v[152:155], v[192:195], v[40:43]
	v_mfma_f32_16x16x32_bf16 v[36:39], v[170:173], v[192:195], v[36:39]
	v_mfma_f32_16x16x32_bf16 v[24:27], v[152:155], v[210:213], v[24:27]
	v_mfma_f32_16x16x32_bf16 v[20:23], v[170:173], v[210:213], v[20:23]
	v_mfma_f32_16x16x32_bf16 v[8:11], v[152:155], v[218:221], v[8:11]
	v_mfma_f32_16x16x32_bf16 v[4:7], v[170:173], v[218:221], v[4:7]
	s_setprio 0
	s_barrier
	s_add_i32 s74, 0, 0x18000
	s_add_i32 s75, 0, 0x1c000
	v_add_u32_e32 v144, s74, v180
	v_add_u32_e32 v170, s75, v180
	ds_read_b128 v[132:135], v144
	ds_read_b128 v[136:139], v144 offset:1024
	ds_read_b128 v[140:143], v144 offset:2048
	ds_read_b128 v[144:147], v144 offset:3072
	ds_read_b128 v[148:151], v170
	ds_read_b128 v[152:155], v170 offset:1024
	ds_read_b128 v[166:169], v170 offset:2048
	ds_read_b128 v[170:173], v170 offset:3072
	s_add_u32 s58, s58, 0x40000
	s_addc_u32 s59, s59, 0
	s_mov_b32 m0, s65
	v_lshl_add_u64 v[228:229], s[58:59], 0, v[160:161]
	ds_read_b128 v[174:177], v182 offset:32768
	ds_read_b128 v[184:187], v182 offset:33792
	ds_read_b128 v[188:191], v182 offset:34816
	ds_read_b128 v[192:195], v182 offset:35840
	ds_read_b128 v[196:199], v182 offset:36864
	ds_read_b128 v[210:213], v182 offset:37888
	ds_read_b128 v[214:217], v182 offset:38912
	ds_read_b128 v[218:221], v182 offset:39936
	global_load_lds_dwordx4 v[228:229], off
	v_lshl_add_u64 v[228:229], s[58:59], 0, v[156:157]
	s_mov_b32 m0, s66
	s_nop 0
	global_load_lds_dwordx4 v[228:229], off
	s_waitcnt vmcnt(8)
	s_waitcnt lgkmcnt(0)
	s_barrier
	s_setprio 1
	s_waitcnt lgkmcnt(0)
	v_mfma_f32_16x16x32_bf16 v[128:131], v[132:135], v[174:177], v[128:131]
	v_mfma_f32_16x16x32_bf16 v[124:127], v[140:143], v[174:177], v[124:127]
	v_mfma_f32_16x16x32_bf16 v[112:115], v[132:135], v[188:191], v[112:115]
	v_mfma_f32_16x16x32_bf16 v[108:111], v[140:143], v[188:191], v[108:111]
	v_mfma_f32_16x16x32_bf16 v[96:99], v[132:135], v[196:199], v[96:99]
	v_mfma_f32_16x16x32_bf16 v[92:95], v[140:143], v[196:199], v[92:95]
	v_mfma_f32_16x16x32_bf16 v[80:83], v[132:135], v[214:217], v[80:83]
	v_mfma_f32_16x16x32_bf16 v[76:79], v[140:143], v[214:217], v[76:79]
	v_mfma_f32_16x16x32_bf16 v[128:131], v[136:139], v[184:187], v[128:131]
	v_mfma_f32_16x16x32_bf16 v[124:127], v[144:147], v[184:187], v[124:127]
	v_mfma_f32_16x16x32_bf16 v[112:115], v[136:139], v[192:195], v[112:115]
	v_mfma_f32_16x16x32_bf16 v[108:111], v[144:147], v[192:195], v[108:111]
	v_mfma_f32_16x16x32_bf16 v[96:99], v[136:139], v[210:213], v[96:99]
	v_mfma_f32_16x16x32_bf16 v[92:95], v[144:147], v[210:213], v[92:95]
	v_mfma_f32_16x16x32_bf16 v[80:83], v[136:139], v[218:221], v[80:83]
	v_mfma_f32_16x16x32_bf16 v[76:79], v[144:147], v[218:221], v[76:79]
	s_setprio 0
	s_setprio 1
	v_mfma_f32_16x16x32_bf16 v[120:123], v[148:151], v[174:177], v[120:123]
	v_mfma_f32_16x16x32_bf16 v[116:119], v[166:169], v[174:177], v[116:119]
	v_mfma_f32_16x16x32_bf16 v[104:107], v[148:151], v[188:191], v[104:107]
	v_mfma_f32_16x16x32_bf16 v[100:103], v[166:169], v[188:191], v[100:103]
	v_mfma_f32_16x16x32_bf16 v[88:91], v[148:151], v[196:199], v[88:91]
	v_mfma_f32_16x16x32_bf16 v[84:87], v[166:169], v[196:199], v[84:87]
	v_mfma_f32_16x16x32_bf16 v[72:75], v[148:151], v[214:217], v[72:75]
	v_mfma_f32_16x16x32_bf16 v[68:71], v[166:169], v[214:217], v[68:71]
	v_mfma_f32_16x16x32_bf16 v[120:123], v[152:155], v[184:187], v[120:123]
	v_mfma_f32_16x16x32_bf16 v[116:119], v[170:173], v[184:187], v[116:119]
	v_mfma_f32_16x16x32_bf16 v[104:107], v[152:155], v[192:195], v[104:107]
	v_mfma_f32_16x16x32_bf16 v[100:103], v[170:173], v[192:195], v[100:103]
	v_mfma_f32_16x16x32_bf16 v[88:91], v[152:155], v[210:213], v[88:91]
	v_mfma_f32_16x16x32_bf16 v[84:87], v[170:173], v[210:213], v[84:87]
	v_mfma_f32_16x16x32_bf16 v[72:75], v[152:155], v[218:221], v[72:75]
	v_mfma_f32_16x16x32_bf16 v[68:71], v[170:173], v[218:221], v[68:71]
	s_setprio 0
	s_barrier
; #define PG8_STAGE(bufoff, gbase, voff) do { _Pragma("unroll") for (int _i = 0; _i < 2; ++_i) \
;         __builtin_amdgcn_global_load_lds((const unsigned*)((const char*)(gbase) + (voff)[_i]), (LAS unsigned*)(lds + (bufoff) + ldsw + _i * 8192), 16, 0, 0); } while (0)
; #define PG8_LDA(dst, b, h) do { _Pragma("unroll") for (int m = 0; m < 4; ++m) _Pragma("unroll") for (int k = 0; k < 2; ++k) dst[m][k] = *(const LAS bf16x8*)(lds + PG8_SA(b, h) + aoff + m * 2048 + k * 1024); } while (0)
; #define PG8_MMA(ai, bj, At, Bt) do { __builtin_amdgcn_s_setprio(1); _Pragma("unroll") for (int m = 0; m < 4; ++m) _Pragma("unroll") for (int n = 0; n < 2; ++n) _Pragma("unroll") for (int k = 0; k < 2; ++k) \
;         acc[ai][bj][m][n] = __builtin_amdgcn_mfma_f32_16x16x32_bf16(Bt[n][k], At[m][k], acc[ai][bj][m][n], 0, 0, 0); __builtin_amdgcn_s_setprio(0); } while (0)
; #define PG8_WAIT_V(n) asm volatile("s_waitcnt vmcnt(" #n ")" ::: "memory")
; #define PG8_WAIT_L(n) asm volatile("s_waitcnt lgkmcnt(" #n ")" ::: "memory")
; #define PG8_BAR __builtin_amdgcn_s_barrier()
; #define PG8_SCHED __builtin_amdgcn_sched_barrier(0)
; template <class Epi>
; __device__ __forceinline__ void gemm_phase(LAS unsigned char* lds, const Gemm g, const StaticOrder& S, const Epi& E) {
;     ...
;             PG8_LDA(At, 1, 1); PG8_STAGE(PG8_SB(1, 0), b3, voffB); PG8_STAGE(PG8_SB(1, 1), b3 + hstepB, voffB); PG8_STAGE(PG8_SA(1, 0), a3, voffA);
;             PG8_WAIT_V(8); PG8_WAIT_L(0); PG8_BAR; PG8_MMA(1, 0, At, B0); PG8_MMA(1, 1, At, B1); PG8_BAR; PG8_SCHED;
;         }
;         if (wr == 0) PG8_BAR;
	s_add_i32 s58, s74, s64
	v_lshl_add_u64 v[178:179], v[178:179], 0, s[30:31]
	s_mov_b32 m0, s58
	ds_read_b128 v[174:177], v182 offset:49152
	ds_read_b128 v[184:187], v182 offset:50176
	ds_read_b128 v[188:191], v182 offset:51200
	ds_read_b128 v[192:195], v182 offset:52224
	ds_read_b128 v[196:199], v182 offset:53248
	ds_read_b128 v[210:213], v182 offset:54272
	ds_read_b128 v[214:217], v182 offset:55296
	ds_read_b128 v[218:221], v182 offset:56320
	global_load_lds_dwordx4 v[178:179], off
	s_add_i32 m0, s58, 0x2000
	s_add_u32 s22, s22, 0x10080
	v_lshl_add_u64 v[178:179], v[222:223], 0, s[30:31]
	s_addc_u32 s23, s23, 0
	s_add_i32 s58, s75, s64
	global_load_lds_dwordx4 v[178:179], off
	v_lshl_add_u64 v[178:179], s[22:23], 0, v[158:159]
	s_mov_b32 m0, s58
	s_nop 0
	global_load_lds_dwordx4 v[178:179], off
	v_lshl_add_u64 v[178:179], s[22:23], 0, v[0:1]
	s_add_i32 m0, s58, 0x2000
	s_nop 0
	global_load_lds_dwordx4 v[178:179], off
	v_lshl_add_u64 v[178:179], v[224:225], 0, s[30:31]
	s_mov_b32 m0, s28
	s_nop 0
	global_load_lds_dwordx4 v[178:179], off
	v_lshl_add_u64 v[178:179], v[226:227], 0, s[30:31]
	s_mov_b32 m0, s67
	s_nop 0
	global_load_lds_dwordx4 v[178:179], off
	s_waitcnt vmcnt(8)
	s_waitcnt lgkmcnt(0)
	s_barrier
	s_setprio 1
	s_waitcnt lgkmcnt(0)
	v_mfma_f32_16x16x32_bf16 v[64:67], v[132:135], v[174:177], v[64:67]
	v_mfma_f32_16x16x32_bf16 v[60:63], v[140:143], v[174:177], v[60:63]
	v_mfma_f32_16x16x32_bf16 v[48:51], v[132:135], v[188:191], v[48:51]
	v_mfma_f32_16x16x32_bf16 v[44:47], v[140:143], v[188:191], v[44:47]
	v_mfma_f32_16x16x32_bf16 v[32:35], v[132:135], v[196:199], v[32:35]
	v_mfma_f32_16x16x32_bf16 v[28:31], v[140:143], v[196:199], v[28:31]
	v_mfma_f32_16x16x32_bf16 v[16:19], v[132:135], v[214:217], v[16:19]
	v_mfma_f32_16x16x32_bf16 v[12:15], v[140:143], v[214:217], v[12:15]
	v_mfma_f32_16x16x32_bf16 v[64:67], v[136:139], v[184:187], v[64:67]
	v_mfma_f32_16x16x32_bf16 v[60:63], v[144:147], v[184:187], v[60:63]
	v_mfma_f32_16x16x32_bf16 v[48:51], v[136:139], v[192:195], v[48:51]
	v_mfma_f32_16x16x32_bf16 v[44:47], v[144:147], v[192:195], v[44:47]
	v_mfma_f32_16x16x32_bf16 v[32:35], v[136:139], v[210:213], v[32:35]
	v_mfma_f32_16x16x32_bf16 v[28:31], v[144:147], v[210:213], v[28:31]
	v_mfma_f32_16x16x32_bf16 v[16:19], v[136:139], v[218:221], v[16:19]
	v_mfma_f32_16x16x32_bf16 v[12:15], v[144:147], v[218:221], v[12:15]
	s_setprio 0
	s_setprio 1
	v_mfma_f32_16x16x32_bf16 v[56:59], v[148:151], v[174:177], v[56:59]
	v_mfma_f32_16x16x32_bf16 v[52:55], v[166:169], v[174:177], v[52:55]
	v_mfma_f32_16x16x32_bf16 v[40:43], v[148:151], v[188:191], v[40:43]
	v_mfma_f32_16x16x32_bf16 v[36:39], v[166:169], v[188:191], v[36:39]
	v_mfma_f32_16x16x32_bf16 v[24:27], v[148:151], v[196:199], v[24:27]
	v_mfma_f32_16x16x32_bf16 v[20:23], v[166:169], v[196:199], v[20:23]
	v_mfma_f32_16x16x32_bf16 v[8:11], v[148:151], v[214:217], v[8:11]
	v_mfma_f32_16x16x32_bf16 v[4:7], v[166:169], v[214:217], v[4:7]
	v_mfma_f32_16x16x32_bf16 v[56:59], v[152:155], v[184:187], v[56:59]
	v_mfma_f32_16x16x32_bf16 v[52:55], v[170:173], v[184:187], v[52:55]
	v_mfma_f32_16x16x32_bf16 v[40:43], v[152:155], v[192:195], v[40:43]
	v_mfma_f32_16x16x32_bf16 v[36:39], v[170:173], v[192:195], v[36:39]
	v_mfma_f32_16x16x32_bf16 v[24:27], v[152:155], v[210:213], v[24:27]
	v_mfma_f32_16x16x32_bf16 v[20:23], v[170:173], v[210:213], v[20:23]
	v_mfma_f32_16x16x32_bf16 v[8:11], v[152:155], v[218:221], v[8:11]
	v_mfma_f32_16x16x32_bf16 v[4:7], v[170:173], v[218:221], v[4:7]
	s_add_i32 s73, s73, 2
	s_add_u32 s56, s56, 0x100
	s_addc_u32 s57, s57, 0
	s_add_u32 s71, s71, 0x100
	s_addc_u32 s72, s72, 0
	s_cmp_gt_u32 s73, 13
	s_setprio 0
	s_barrier
	s_cbranch_scc0 .LBB0_1270
	s_and_b64 vcc, exec, s[38:39]
	s_cbranch_vccz .LBB0_1273
	s_barrier
